# EpiRes (w_o and w_ff2 residual epilogues): x_old loads prefetched into a register pool with counted vmcnt
# speedup vs baseline: 1.0700x; 1.0049x over previous
; __device__ __forceinline__ unsigned pk2(float lo, float hi) { unsigned r; asm volatile("v_cvt_pk_bf16_f32 %0, %1, %2" : "=v"(r) : "v"(lo), "v"(hi)); return r; }
;     __device__ __forceinline__ void operator()(const f32x4 (&acc)[2][2][4][2], const Unit& u, int wr, int wc, int fr, int fq) const {
;         const int row0 = u.pm * 256 + wr * 64 + fr, col0 = u.pn * 256 + wc * 32 + 4 * fq;
;         const float* xo = (u.pm < 64) ? xoldA : (xoldB - (size_t)T_P * DM);
; #pragma unroll
;         for (int ai = 0; ai < 2; ++ai)
; #pragma unroll
;             for (int m = 0; m < 4; ++m) {
;                 const int row = row0 + ai * 128 + m * 16; const size_t ro = (size_t)row * DM + col0;
;                 float s = 0.f;
; #pragma unroll
;                 for (int bj = 0; bj < 2; ++bj)
; #pragma unroll
;                     for (int n = 0; n < 2; ++n) {
;                         const size_t o = ro + bj * 128 + n * 16;
;                         const f32x4 xn = *(const f32x4*)(xo + o) + acc[ai][bj][m][n];
;                         *(f32x4*)(xf + o) = xn;
;                         u32x2 w; w.x = pk2(xn[0], xn[1]); w.y = pk2(xn[2], xn[3]); *(u32x2*)(xb + o) = w;
;                         s += (xn[0] * xn[0] + xn[1] * xn[1]) + (xn[2] * xn[2] + xn[3] * xn[3]);
;                     }
;                 s += __shfl_xor(s, 16); s += __shfl_xor(s, 32);
;                 if (fq == 0) ssq[(size_t)row * 16 + u.pn * 4 + wc] = s;
.LBB0_781:
	v_lshl_add_u32 v146, s83, 8, v148
	v_lshl_or_b32 v142, s56, 8, v150
	v_ashrrev_i32_e32 v147, 31, v146
	v_ashrrev_i32_e32 v143, 31, v142
	v_lshlrev_b64 v[154:155], 10, v[146:147]
	s_cmp_lt_i32 s83, 64
	v_lshl_add_u64 v[158:159], v[154:155], 0, v[142:143]
	s_cselect_b32 s17, s23, -1
	s_cselect_b32 s16, s22, 0xfc000000
	v_lshlrev_b64 v[160:161], 2, v[158:159]
	v_lshl_add_u64 v[162:163], s[16:17], 0, v[160:161]
	v_subrev_u32_e32 v172, s16, v162
	v_add_u32_e32 v173, 0x0, v172
	global_load_dwordx4 v[174:177], v173, s[16:17]
	v_add_u32_e32 v173, 0x40, v172
	global_load_dwordx4 v[178:181], v173, s[16:17]
	v_add_u32_e32 v173, 0x200, v172
	global_load_dwordx4 v[182:185], v173, s[16:17]
	v_add_u32_e32 v173, 0x240, v172
	global_load_dwordx4 v[186:189], v173, s[16:17]
	v_add_u32_e32 v173, 0x10000, v172
	global_load_dwordx4 v[190:193], v173, s[16:17]
	v_add_u32_e32 v173, 0x10040, v172
	global_load_dwordx4 v[194:197], v173, s[16:17]
	v_add_u32_e32 v173, 0x10200, v172
	global_load_dwordx4 v[198:201], v173, s[16:17]
	v_add_u32_e32 v173, 0x10240, v172
	global_load_dwordx4 v[202:205], v173, s[16:17]
	v_add_u32_e32 v173, 0x20000, v172
	global_load_dwordx4 v[206:209], v173, s[16:17]
	v_add_u32_e32 v173, 0x20040, v172
	global_load_dwordx4 v[210:213], v173, s[16:17]
	v_add_u32_e32 v173, 0x20200, v172
	global_load_dwordx4 v[214:217], v173, s[16:17]
	v_add_u32_e32 v173, 0x20240, v172
	global_load_dwordx4 v[218:221], v173, s[16:17]
	v_add_u32_e32 v173, 0x30000, v172
	global_load_dwordx4 v[232:235], v173, s[16:17]
	v_add_u32_e32 v173, 0x30040, v172
	global_load_dwordx4 v[236:239], v173, s[16:17]
	v_add_u32_e32 v173, 0x30200, v172
	global_load_dwordx4 v[240:243], v173, s[16:17]
	v_add_u32_e32 v173, 0x30240, v172
	global_load_dwordx4 v[244:247], v173, s[16:17]
	v_add_u32_e32 v173, 0x80000, v172
	global_load_dwordx4 v[248:251], v173, s[16:17]
	v_add_u32_e32 v173, 0x80040, v172
	global_load_dwordx4 v[252:255], v173, s[16:17]
	v_lshl_add_u64 v[164:165], v[158:159], 1, s[24:25]
	v_lshl_add_u64 v[170:171], s[28:29], 0, v[160:161]
	v_xor_b32_e32 v153, 32, v152
	s_lshl_b32 s56, s56, 2
	s_ashr_i32 s57, s56, 31
	s_waitcnt vmcnt(17)
	v_mov_b32_e32 v154, v174
	v_mov_b32_e32 v155, v175
	v_mov_b32_e32 v156, v176
	v_mov_b32_e32 v157, v177
	v_add_u32_e32 v173, 0x80200, v172
	global_load_dwordx4 v[174:177], v173, s[16:17]
	v_pk_add_f32 v[126:127], v[126:127], v[156:157]
	v_pk_add_f32 v[124:125], v[124:125], v[154:155]
	global_store_dwordx4 v[170:171], v[124:127], off
	v_cvt_pk_bf16_f32 v154, v124, v125
	v_cvt_pk_bf16_f32 v155, v126, v127
	global_store_dwordx2 v[164:165], v[154:155], off
	s_waitcnt vmcnt(19)
	v_mov_b32_e32 v154, v178
	v_mov_b32_e32 v155, v179
	v_mov_b32_e32 v156, v180
	v_mov_b32_e32 v157, v181
	v_add_u32_e32 v173, 0x80240, v172
	global_load_dwordx4 v[178:181], v173, s[16:17]
	v_pk_add_f32 v[122:123], v[122:123], v[156:157]
	v_pk_add_f32 v[120:121], v[120:121], v[154:155]
	global_store_dwordx4 v[170:171], v[120:123], off offset:64
	v_cvt_pk_bf16_f32 v154, v120, v121
	v_cvt_pk_bf16_f32 v155, v122, v123
	global_store_dwordx2 v[164:165], v[154:155], off offset:32
	s_waitcnt vmcnt(21)
	v_mov_b32_e32 v154, v182
	v_mov_b32_e32 v155, v183
	v_mov_b32_e32 v156, v184
	v_mov_b32_e32 v157, v185
	v_add_u32_e32 v173, 0x90000, v172
	global_load_dwordx4 v[182:185], v173, s[16:17]
	v_pk_add_f32 v[156:157], v[118:119], v[156:157]
	v_pk_add_f32 v[154:155], v[116:117], v[154:155]
	global_store_dwordx4 v[170:171], v[154:157], off offset:512
	v_cvt_pk_bf16_f32 v116, v154, v155
	v_cvt_pk_bf16_f32 v117, v156, v157
	global_store_dwordx2 v[164:165], v[116:117], off offset:256
	v_mul_f32_e32 v118, v125, v125
	v_mul_f32_e32 v119, v127, v127
	v_fmac_f32_e32 v118, v124, v124
	v_fmac_f32_e32 v119, v126, v126
	v_add_f32_e32 v118, v118, v119
	v_mul_f32_e32 v119, v121, v121
	v_mul_f32_e32 v121, v123, v123
	v_fmac_f32_e32 v119, v120, v120
	v_fmac_f32_e32 v121, v122, v122
	v_add_f32_e32 v119, v119, v121
	v_add_f32_e32 v118, v118, v119
	v_mul_f32_e32 v119, v155, v155
	v_mul_f32_e32 v120, v157, v157
	v_fmac_f32_e32 v119, v154, v154
	v_fmac_f32_e32 v120, v156, v156
	v_add_f32_e32 v119, v119, v120
	v_and_b32_e32 v117, 64, v152
	v_add_f32_e32 v122, v118, v119
	v_xor_b32_e32 v116, 16, v152
	v_add_u32_e32 v117, 64, v117
	v_cmp_lt_i32_e32 vcc, v116, v117
	s_waitcnt vmcnt(23)
	v_mov_b32_e32 v158, v186
	v_mov_b32_e32 v159, v187
	v_mov_b32_e32 v160, v188
	v_mov_b32_e32 v161, v189
	v_add_u32_e32 v173, 0x90040, v172
	global_load_dwordx4 v[186:189], v173, s[16:17]
	v_pk_add_f32 v[120:121], v[114:115], v[160:161]
	v_pk_add_f32 v[118:119], v[112:113], v[158:159]
	v_mul_f32_e32 v113, v121, v121
	v_mul_f32_e32 v112, v119, v119
	v_fmac_f32_e32 v112, v118, v118
	v_fmac_f32_e32 v113, v120, v120
	v_cndmask_b32_e32 v116, v152, v116, vcc
	v_add_f32_e32 v112, v112, v113
	v_lshlrev_b32_e32 v116, 2, v116
	v_add_f32_e32 v112, v122, v112
	ds_bpermute_b32 v113, v116, v112
	v_cmp_lt_i32_e32 vcc, v153, v117
	global_store_dwordx4 v[170:171], v[118:121], off offset:576
	s_waitcnt lgkmcnt(0)
	v_add_f32_e32 v112, v112, v113
	v_cndmask_b32_e32 v114, v152, v153, vcc
	v_lshlrev_b32_e32 v114, 2, v114
	ds_bpermute_b32 v113, v114, v112
	v_cvt_pk_bf16_f32 v118, v118, v119
	v_cvt_pk_bf16_f32 v119, v120, v121
	global_store_dwordx2 v[164:165], v[118:119], off offset:288
	s_and_saveexec_b64 s[58:59], s[12:13]
	s_cbranch_execz .LBB0_783
	s_waitcnt lgkmcnt(0)
	v_add_f32_e32 v115, v112, v113
	v_lshlrev_b64 v[112:113], 6, v[146:147]
	v_lshl_add_u64 v[112:113], s[26:27], 0, v[112:113]
	v_lshl_add_u64 v[112:113], s[56:57], 2, v[112:113]
	s_lshl_b32 s36, s74, 2
	v_lshl_add_u64 v[112:113], v[112:113], 0, s[36:37]
	global_store_dword v[112:113], v115, off
; __device__ __forceinline__ unsigned pk2(float lo, float hi) { unsigned r; asm volatile("v_cvt_pk_bf16_f32 %0, %1, %2" : "=v"(r) : "v"(lo), "v"(hi)); return r; }
;     __device__ __forceinline__ void operator()(const f32x4 (&acc)[2][2][4][2], const Unit& u, int wr, int wc, int fr, int fq) const {
;     ...
;             for (int m = 0; m < 4; ++m) {
;                 const int row = row0 + ai * 128 + m * 16; const size_t ro = (size_t)row * DM + col0;
;                 float s = 0.f;
; #pragma unroll
;                 for (int bj = 0; bj < 2; ++bj)
; #pragma unroll
;                     for (int n = 0; n < 2; ++n) {
;                         const size_t o = ro + bj * 128 + n * 16;
;                         const f32x4 xn = *(const f32x4*)(xo + o) + acc[ai][bj][m][n];
;                         *(f32x4*)(xf + o) = xn;
;                         u32x2 w; w.x = pk2(xn[0], xn[1]); w.y = pk2(xn[2], xn[3]); *(u32x2*)(xb + o) = w;
;                         s += (xn[0] * xn[0] + xn[1] * xn[1]) + (xn[2] * xn[2] + xn[3] * xn[3]);
;                     }
;                 s += __shfl_xor(s, 16); s += __shfl_xor(s, 32);
;                 if (fq == 0) ssq[(size_t)row * 16 + u.pn * 4 + wc] = s;
.LBB0_783:
	s_or_b64 exec, exec, s[58:59]
	v_or_b32_e32 v112, 16, v146
	s_waitcnt lgkmcnt(0)
	v_ashrrev_i32_e32 v113, 31, v112
	v_lshlrev_b64 v[118:119], 10, v[112:113]
	v_lshl_add_u64 v[122:123], v[118:119], 0, v[142:143]
	v_lshlrev_b64 v[124:125], 2, v[122:123]
	v_lshl_add_u64 v[126:127], s[16:17], 0, v[124:125]
	v_lshl_add_u64 v[122:123], v[122:123], 1, s[24:25]
	v_lshl_add_u64 v[124:125], s[28:29], 0, v[124:125]
	s_waitcnt vmcnt(25)
	v_mov_b32_e32 v118, v190
	v_mov_b32_e32 v119, v191
	v_mov_b32_e32 v120, v192
	v_mov_b32_e32 v121, v193
	v_add_u32_e32 v173, 0x90200, v172
	global_load_dwordx4 v[190:193], v173, s[16:17]
	v_pk_add_f32 v[110:111], v[110:111], v[120:121]
	v_pk_add_f32 v[108:109], v[108:109], v[118:119]
	global_store_dwordx4 v[124:125], v[108:111], off
	v_cvt_pk_bf16_f32 v118, v108, v109
	v_cvt_pk_bf16_f32 v119, v110, v111
	global_store_dwordx2 v[122:123], v[118:119], off
	v_mul_f32_e32 v109, v109, v109
	v_mul_f32_e32 v111, v111, v111
	v_fmac_f32_e32 v109, v108, v108
	v_fmac_f32_e32 v111, v110, v110
	v_add_f32_e32 v108, v109, v111
	s_waitcnt vmcnt(27)
	v_mov_b32_e32 v118, v194
	v_mov_b32_e32 v119, v195
	v_mov_b32_e32 v120, v196
	v_mov_b32_e32 v121, v197
	v_add_u32_e32 v173, 0x90240, v172
	global_load_dwordx4 v[194:197], v173, s[16:17]
	v_pk_add_f32 v[106:107], v[106:107], v[120:121]
	v_pk_add_f32 v[104:105], v[104:105], v[118:119]
	global_store_dwordx4 v[124:125], v[104:107], off offset:64
	v_cvt_pk_bf16_f32 v118, v104, v105
	v_cvt_pk_bf16_f32 v119, v106, v107
	global_store_dwordx2 v[122:123], v[118:119], off offset:32
	v_mul_f32_e32 v105, v105, v105
	v_mul_f32_e32 v107, v107, v107
	v_fmac_f32_e32 v105, v104, v104
	v_fmac_f32_e32 v107, v106, v106
	v_add_f32_e32 v104, v105, v107
	v_add_f32_e32 v104, v108, v104
	s_waitcnt vmcnt(29)
	v_mov_b32_e32 v118, v198
	v_mov_b32_e32 v119, v199
	v_mov_b32_e32 v120, v200
	v_mov_b32_e32 v121, v201
	v_add_u32_e32 v173, 0xa0000, v172
	global_load_dwordx4 v[198:201], v173, s[16:17]
	v_pk_add_f32 v[102:103], v[102:103], v[120:121]
	v_pk_add_f32 v[100:101], v[100:101], v[118:119]
	global_store_dwordx4 v[124:125], v[100:103], off offset:512
	v_cvt_pk_bf16_f32 v118, v100, v101
	v_cvt_pk_bf16_f32 v119, v102, v103
	global_store_dwordx2 v[122:123], v[118:119], off offset:256
	v_mul_f32_e32 v101, v101, v101
	v_mul_f32_e32 v103, v103, v103
	v_fmac_f32_e32 v101, v100, v100
	v_fmac_f32_e32 v103, v102, v102
	v_add_f32_e32 v100, v101, v103
	v_add_f32_e32 v102, v104, v100
	s_waitcnt vmcnt(31)
	v_mov_b32_e32 v118, v202
	v_mov_b32_e32 v119, v203
	v_mov_b32_e32 v120, v204
	v_mov_b32_e32 v121, v205
	v_add_u32_e32 v173, 0xa0040, v172
	global_load_dwordx4 v[202:205], v173, s[16:17]
	v_pk_add_f32 v[100:101], v[98:99], v[120:121]
	v_pk_add_f32 v[98:99], v[96:97], v[118:119]
	v_mul_f32_e32 v97, v101, v101
	v_mul_f32_e32 v96, v99, v99
	v_fmac_f32_e32 v96, v98, v98
	v_fmac_f32_e32 v97, v100, v100
	v_add_f32_e32 v96, v96, v97
	v_add_f32_e32 v96, v102, v96
	ds_bpermute_b32 v97, v116, v96
	global_store_dwordx4 v[124:125], v[98:101], off offset:576
	s_waitcnt lgkmcnt(0)
	v_add_f32_e32 v96, v96, v97
	ds_bpermute_b32 v97, v114, v96
	v_cvt_pk_bf16_f32 v98, v98, v99
	v_cvt_pk_bf16_f32 v99, v100, v101
	global_store_dwordx2 v[122:123], v[98:99], off offset:288
	s_and_saveexec_b64 s[58:59], s[12:13]
	s_cbranch_execz .LBB0_785
	s_waitcnt lgkmcnt(0)
	v_add_f32_e32 v98, v96, v97
	v_lshlrev_b64 v[96:97], 6, v[112:113]
	v_lshl_add_u64 v[96:97], s[26:27], 0, v[96:97]
	v_lshl_add_u64 v[96:97], s[56:57], 2, v[96:97]
	s_lshl_b32 s36, s74, 2
	v_lshl_add_u64 v[96:97], v[96:97], 0, s[36:37]
	global_store_dword v[96:97], v98, off
.LBB0_785:
	s_or_b64 exec, exec, s[58:59]
	v_or_b32_e32 v96, 32, v146
	s_waitcnt lgkmcnt(0)
	v_ashrrev_i32_e32 v97, 31, v96
	v_lshlrev_b64 v[98:99], 10, v[96:97]
	v_lshl_add_u64 v[102:103], v[98:99], 0, v[142:143]
	v_lshlrev_b64 v[104:105], 2, v[102:103]
	v_lshl_add_u64 v[106:107], s[16:17], 0, v[104:105]
	v_lshl_add_u64 v[102:103], v[102:103], 1, s[24:25]
	v_lshl_add_u64 v[104:105], s[28:29], 0, v[104:105]
	s_waitcnt vmcnt(33)
	v_mov_b32_e32 v98, v206
	v_mov_b32_e32 v99, v207
	v_mov_b32_e32 v100, v208
	v_mov_b32_e32 v101, v209
	v_add_u32_e32 v173, 0xa0200, v172
	global_load_dwordx4 v[206:209], v173, s[16:17]
	v_pk_add_f32 v[94:95], v[94:95], v[100:101]
	v_pk_add_f32 v[92:93], v[92:93], v[98:99]
	global_store_dwordx4 v[104:105], v[92:95], off
	v_cvt_pk_bf16_f32 v98, v92, v93
	v_cvt_pk_bf16_f32 v99, v94, v95
	global_store_dwordx2 v[102:103], v[98:99], off
	v_mul_f32_e32 v93, v93, v93
	v_mul_f32_e32 v95, v95, v95
	v_fmac_f32_e32 v93, v92, v92
	v_fmac_f32_e32 v95, v94, v94
	v_add_f32_e32 v92, v93, v95
	s_waitcnt vmcnt(35)
	v_mov_b32_e32 v98, v210
	v_mov_b32_e32 v99, v211
	v_mov_b32_e32 v100, v212
	v_mov_b32_e32 v101, v213
	v_add_u32_e32 v173, 0xa0240, v172
	global_load_dwordx4 v[210:213], v173, s[16:17]
	v_pk_add_f32 v[90:91], v[90:91], v[100:101]
	v_pk_add_f32 v[88:89], v[88:89], v[98:99]
	global_store_dwordx4 v[104:105], v[88:91], off offset:64
	v_cvt_pk_bf16_f32 v98, v88, v89
	v_cvt_pk_bf16_f32 v99, v90, v91
	global_store_dwordx2 v[102:103], v[98:99], off offset:32
	v_mul_f32_e32 v89, v89, v89
	v_mul_f32_e32 v91, v91, v91
	v_fmac_f32_e32 v89, v88, v88
	v_fmac_f32_e32 v91, v90, v90
	v_add_f32_e32 v88, v89, v91
	v_add_f32_e32 v88, v92, v88
	s_waitcnt vmcnt(37)
	v_mov_b32_e32 v98, v214
	v_mov_b32_e32 v99, v215
	v_mov_b32_e32 v100, v216
	v_mov_b32_e32 v101, v217
	v_add_u32_e32 v173, 0xb0000, v172
	global_load_dwordx4 v[214:217], v173, s[16:17]
	v_pk_add_f32 v[86:87], v[86:87], v[100:101]
	v_pk_add_f32 v[84:85], v[84:85], v[98:99]
	global_store_dwordx4 v[104:105], v[84:87], off offset:512
	v_cvt_pk_bf16_f32 v98, v84, v85
	v_cvt_pk_bf16_f32 v99, v86, v87
	global_store_dwordx2 v[102:103], v[98:99], off offset:256
	v_mul_f32_e32 v85, v85, v85
	v_mul_f32_e32 v87, v87, v87
	v_fmac_f32_e32 v85, v84, v84
	v_fmac_f32_e32 v87, v86, v86
	v_add_f32_e32 v84, v85, v87
	v_add_f32_e32 v86, v88, v84
	s_waitcnt vmcnt(39)
	v_mov_b32_e32 v98, v218
	v_mov_b32_e32 v99, v219
	v_mov_b32_e32 v100, v220
	v_mov_b32_e32 v101, v221
	v_add_u32_e32 v173, 0xb0040, v172
	global_load_dwordx4 v[218:221], v173, s[16:17]
	v_pk_add_f32 v[84:85], v[82:83], v[100:101]
	v_pk_add_f32 v[82:83], v[80:81], v[98:99]
	v_mul_f32_e32 v81, v85, v85
	v_mul_f32_e32 v80, v83, v83
	v_fmac_f32_e32 v80, v82, v82
	v_fmac_f32_e32 v81, v84, v84
	v_add_f32_e32 v80, v80, v81
	v_add_f32_e32 v80, v86, v80
	ds_bpermute_b32 v81, v116, v80
	global_store_dwordx4 v[104:105], v[82:85], off offset:576
	s_waitcnt lgkmcnt(0)
	v_add_f32_e32 v80, v80, v81
	ds_bpermute_b32 v81, v114, v80
	v_cvt_pk_bf16_f32 v82, v82, v83
	v_cvt_pk_bf16_f32 v83, v84, v85
	global_store_dwordx2 v[102:103], v[82:83], off offset:288
	s_and_saveexec_b64 s[58:59], s[12:13]
	s_cbranch_execz .LBB0_787
	s_waitcnt lgkmcnt(0)
	v_add_f32_e32 v82, v80, v81
	v_lshlrev_b64 v[80:81], 6, v[96:97]
	v_lshl_add_u64 v[80:81], s[26:27], 0, v[80:81]
	v_lshl_add_u64 v[80:81], s[56:57], 2, v[80:81]
	s_lshl_b32 s36, s74, 2
	v_lshl_add_u64 v[80:81], v[80:81], 0, s[36:37]
	global_store_dword v[80:81], v82, off
; __device__ __forceinline__ unsigned pk2(float lo, float hi) { unsigned r; asm volatile("v_cvt_pk_bf16_f32 %0, %1, %2" : "=v"(r) : "v"(lo), "v"(hi)); return r; }
;     __device__ __forceinline__ void operator()(const f32x4 (&acc)[2][2][4][2], const Unit& u, int wr, int wc, int fr, int fq) const {
;     ...
;             for (int m = 0; m < 4; ++m) {
;                 const int row = row0 + ai * 128 + m * 16; const size_t ro = (size_t)row * DM + col0;
;                 float s = 0.f;
; #pragma unroll
;                 for (int bj = 0; bj < 2; ++bj)
; #pragma unroll
;                     for (int n = 0; n < 2; ++n) {
;                         const size_t o = ro + bj * 128 + n * 16;
;                         const f32x4 xn = *(const f32x4*)(xo + o) + acc[ai][bj][m][n];
;                         *(f32x4*)(xf + o) = xn;
;                         u32x2 w; w.x = pk2(xn[0], xn[1]); w.y = pk2(xn[2], xn[3]); *(u32x2*)(xb + o) = w;
;                         s += (xn[0] * xn[0] + xn[1] * xn[1]) + (xn[2] * xn[2] + xn[3] * xn[3]);
;                     }
;                 s += __shfl_xor(s, 16); s += __shfl_xor(s, 32);
;                 if (fq == 0) ssq[(size_t)row * 16 + u.pn * 4 + wc] = s;
.LBB0_787:
	s_or_b64 exec, exec, s[58:59]
	v_or_b32_e32 v80, 48, v146
	s_waitcnt lgkmcnt(0)
	v_ashrrev_i32_e32 v81, 31, v80
	v_lshlrev_b64 v[82:83], 10, v[80:81]
	v_lshl_add_u64 v[86:87], v[82:83], 0, v[142:143]
	v_lshlrev_b64 v[88:89], 2, v[86:87]
	v_lshl_add_u64 v[90:91], s[16:17], 0, v[88:89]
	v_lshl_add_u64 v[86:87], v[86:87], 1, s[24:25]
	v_lshl_add_u64 v[88:89], s[28:29], 0, v[88:89]
	s_waitcnt vmcnt(41)
	v_mov_b32_e32 v82, v232
	v_mov_b32_e32 v83, v233
	v_mov_b32_e32 v84, v234
	v_mov_b32_e32 v85, v235
	v_add_u32_e32 v173, 0xb0200, v172
	global_load_dwordx4 v[232:235], v173, s[16:17]
	v_pk_add_f32 v[78:79], v[78:79], v[84:85]
	v_pk_add_f32 v[76:77], v[76:77], v[82:83]
	global_store_dwordx4 v[88:89], v[76:79], off
	v_cvt_pk_bf16_f32 v82, v76, v77
	v_cvt_pk_bf16_f32 v83, v78, v79
	global_store_dwordx2 v[86:87], v[82:83], off
	v_mul_f32_e32 v77, v77, v77
	v_mul_f32_e32 v79, v79, v79
	v_fmac_f32_e32 v77, v76, v76
	v_fmac_f32_e32 v79, v78, v78
	v_add_f32_e32 v76, v77, v79
	s_waitcnt vmcnt(43)
	v_mov_b32_e32 v82, v236
	v_mov_b32_e32 v83, v237
	v_mov_b32_e32 v84, v238
	v_mov_b32_e32 v85, v239
	v_add_u32_e32 v173, 0xb0240, v172
	global_load_dwordx4 v[236:239], v173, s[16:17]
	v_pk_add_f32 v[74:75], v[74:75], v[84:85]
	v_pk_add_f32 v[72:73], v[72:73], v[82:83]
	global_store_dwordx4 v[88:89], v[72:75], off offset:64
	v_cvt_pk_bf16_f32 v82, v72, v73
	v_cvt_pk_bf16_f32 v83, v74, v75
	global_store_dwordx2 v[86:87], v[82:83], off offset:32
	v_mul_f32_e32 v73, v73, v73
	v_mul_f32_e32 v75, v75, v75
	v_fmac_f32_e32 v73, v72, v72
	v_fmac_f32_e32 v75, v74, v74
	v_add_f32_e32 v72, v73, v75
	v_add_f32_e32 v72, v76, v72
	s_waitcnt vmcnt(45)
	v_mov_b32_e32 v82, v240
	v_mov_b32_e32 v83, v241
	v_mov_b32_e32 v84, v242
	v_mov_b32_e32 v85, v243
	v_pk_add_f32 v[70:71], v[70:71], v[84:85]
	v_pk_add_f32 v[68:69], v[68:69], v[82:83]
	global_store_dwordx4 v[88:89], v[68:71], off offset:512
	v_cvt_pk_bf16_f32 v82, v68, v69
	v_cvt_pk_bf16_f32 v83, v70, v71
	global_store_dwordx2 v[86:87], v[82:83], off offset:256
	v_mul_f32_e32 v69, v69, v69
	v_mul_f32_e32 v71, v71, v71
	v_fmac_f32_e32 v69, v68, v68
	v_fmac_f32_e32 v71, v70, v70
	v_add_f32_e32 v68, v69, v71
	v_add_f32_e32 v70, v72, v68
	s_waitcnt vmcnt(46)
	v_mov_b32_e32 v82, v244
	v_mov_b32_e32 v83, v245
	v_mov_b32_e32 v84, v246
	v_mov_b32_e32 v85, v247
	v_pk_add_f32 v[68:69], v[66:67], v[84:85]
	v_pk_add_f32 v[66:67], v[64:65], v[82:83]
	v_mul_f32_e32 v65, v69, v69
	v_mul_f32_e32 v64, v67, v67
	v_fmac_f32_e32 v64, v66, v66
	v_fmac_f32_e32 v65, v68, v68
	v_add_f32_e32 v64, v64, v65
	v_add_f32_e32 v64, v70, v64
	ds_bpermute_b32 v65, v116, v64
	global_store_dwordx4 v[88:89], v[66:69], off offset:576
	s_waitcnt lgkmcnt(0)
	v_add_f32_e32 v64, v64, v65
	ds_bpermute_b32 v65, v114, v64
	v_cvt_pk_bf16_f32 v66, v66, v67
	v_cvt_pk_bf16_f32 v67, v68, v69
	global_store_dwordx2 v[86:87], v[66:67], off offset:288
	s_and_saveexec_b64 s[58:59], s[12:13]
	s_cbranch_execz .LBB0_789
	s_waitcnt lgkmcnt(0)
	v_add_f32_e32 v66, v64, v65
	v_lshlrev_b64 v[64:65], 6, v[80:81]
	v_lshl_add_u64 v[64:65], s[26:27], 0, v[64:65]
	v_lshl_add_u64 v[64:65], s[56:57], 2, v[64:65]
	s_lshl_b32 s36, s74, 2
	v_lshl_add_u64 v[64:65], v[64:65], 0, s[36:37]
	global_store_dword v[64:65], v66, off
.LBB0_789:
	s_or_b64 exec, exec, s[58:59]
	v_add_u32_e32 v64, 0x80, v146
	s_waitcnt lgkmcnt(0)
	v_ashrrev_i32_e32 v65, 31, v64
	v_lshlrev_b64 v[66:67], 10, v[64:65]
	v_lshl_add_u64 v[70:71], v[66:67], 0, v[142:143]
	v_lshlrev_b64 v[72:73], 2, v[70:71]
	v_lshl_add_u64 v[74:75], s[16:17], 0, v[72:73]
	v_lshl_add_u64 v[70:71], v[70:71], 1, s[24:25]
	v_lshl_add_u64 v[72:73], s[28:29], 0, v[72:73]
	s_waitcnt vmcnt(47)
	v_mov_b32_e32 v66, v248
	v_mov_b32_e32 v67, v249
	v_mov_b32_e32 v68, v250
	v_mov_b32_e32 v69, v251
	v_pk_add_f32 v[62:63], v[62:63], v[68:69]
	v_pk_add_f32 v[60:61], v[60:61], v[66:67]
	global_store_dwordx4 v[72:73], v[60:63], off
	v_cvt_pk_bf16_f32 v66, v60, v61
	v_cvt_pk_bf16_f32 v67, v62, v63
	global_store_dwordx2 v[70:71], v[66:67], off
	v_mul_f32_e32 v61, v61, v61
	v_mul_f32_e32 v63, v63, v63
	v_fmac_f32_e32 v61, v60, v60
	v_fmac_f32_e32 v63, v62, v62
	v_add_f32_e32 v60, v61, v63
	s_waitcnt vmcnt(48)
	v_mov_b32_e32 v66, v252
	v_mov_b32_e32 v67, v253
	v_mov_b32_e32 v68, v254
	v_mov_b32_e32 v69, v255
	v_pk_add_f32 v[58:59], v[58:59], v[68:69]
	v_pk_add_f32 v[56:57], v[56:57], v[66:67]
	global_store_dwordx4 v[72:73], v[56:59], off offset:64
	v_cvt_pk_bf16_f32 v66, v56, v57
	v_cvt_pk_bf16_f32 v67, v58, v59
	global_store_dwordx2 v[70:71], v[66:67], off offset:32
	v_mul_f32_e32 v57, v57, v57
	v_mul_f32_e32 v59, v59, v59
	v_fmac_f32_e32 v57, v56, v56
	v_fmac_f32_e32 v59, v58, v58
	v_add_f32_e32 v56, v57, v59
	v_add_f32_e32 v56, v60, v56
	s_waitcnt vmcnt(49)
	v_mov_b32_e32 v66, v174
	v_mov_b32_e32 v67, v175
	v_mov_b32_e32 v68, v176
	v_mov_b32_e32 v69, v177
	v_pk_add_f32 v[54:55], v[54:55], v[68:69]
	v_pk_add_f32 v[52:53], v[52:53], v[66:67]
	global_store_dwordx4 v[72:73], v[52:55], off offset:512
	v_cvt_pk_bf16_f32 v66, v52, v53
	v_cvt_pk_bf16_f32 v67, v54, v55
	global_store_dwordx2 v[70:71], v[66:67], off offset:256
	v_mul_f32_e32 v53, v53, v53
	v_mul_f32_e32 v55, v55, v55
	v_fmac_f32_e32 v53, v52, v52
	v_fmac_f32_e32 v55, v54, v54
	v_add_f32_e32 v52, v53, v55
	v_add_f32_e32 v54, v56, v52
	s_waitcnt vmcnt(48)
	v_mov_b32_e32 v66, v178
	v_mov_b32_e32 v67, v179
	v_mov_b32_e32 v68, v180
	v_mov_b32_e32 v69, v181
	v_pk_add_f32 v[52:53], v[50:51], v[68:69]
	v_pk_add_f32 v[50:51], v[48:49], v[66:67]
	v_mul_f32_e32 v49, v53, v53
	v_mul_f32_e32 v48, v51, v51
	v_fmac_f32_e32 v48, v50, v50
	v_fmac_f32_e32 v49, v52, v52
	v_add_f32_e32 v48, v48, v49
	v_add_f32_e32 v48, v54, v48
	ds_bpermute_b32 v49, v116, v48
	global_store_dwordx4 v[72:73], v[50:53], off offset:576
	s_waitcnt lgkmcnt(0)
	v_add_f32_e32 v48, v48, v49
	ds_bpermute_b32 v49, v114, v48
	v_cvt_pk_bf16_f32 v50, v50, v51
	v_cvt_pk_bf16_f32 v51, v52, v53
	global_store_dwordx2 v[70:71], v[50:51], off offset:288
	s_and_saveexec_b64 s[58:59], s[12:13]
	s_cbranch_execz .LBB0_791
	s_waitcnt lgkmcnt(0)
	v_add_f32_e32 v50, v48, v49
	v_lshlrev_b64 v[48:49], 6, v[64:65]
	v_lshl_add_u64 v[48:49], s[26:27], 0, v[48:49]
	v_lshl_add_u64 v[48:49], s[56:57], 2, v[48:49]
	s_lshl_b32 s36, s74, 2
	v_lshl_add_u64 v[48:49], v[48:49], 0, s[36:37]
	global_store_dword v[48:49], v50, off
; __device__ __forceinline__ unsigned pk2(float lo, float hi) { unsigned r; asm volatile("v_cvt_pk_bf16_f32 %0, %1, %2" : "=v"(r) : "v"(lo), "v"(hi)); return r; }
;     __device__ __forceinline__ void operator()(const f32x4 (&acc)[2][2][4][2], const Unit& u, int wr, int wc, int fr, int fq) const {
;     ...
;             for (int m = 0; m < 4; ++m) {
;                 const int row = row0 + ai * 128 + m * 16; const size_t ro = (size_t)row * DM + col0;
;                 float s = 0.f;
; #pragma unroll
;                 for (int bj = 0; bj < 2; ++bj)
; #pragma unroll
;                     for (int n = 0; n < 2; ++n) {
;                         const size_t o = ro + bj * 128 + n * 16;
;                         const f32x4 xn = *(const f32x4*)(xo + o) + acc[ai][bj][m][n];
;                         *(f32x4*)(xf + o) = xn;
;                         u32x2 w; w.x = pk2(xn[0], xn[1]); w.y = pk2(xn[2], xn[3]); *(u32x2*)(xb + o) = w;
;                         s += (xn[0] * xn[0] + xn[1] * xn[1]) + (xn[2] * xn[2] + xn[3] * xn[3]);
;                     }
;                 s += __shfl_xor(s, 16); s += __shfl_xor(s, 32);
;                 if (fq == 0) ssq[(size_t)row * 16 + u.pn * 4 + wc] = s;
.LBB0_791:
	s_or_b64 exec, exec, s[58:59]
	v_add_u32_e32 v48, 0x90, v146
	s_waitcnt lgkmcnt(0)
	v_ashrrev_i32_e32 v49, 31, v48
	v_lshlrev_b64 v[50:51], 10, v[48:49]
	v_lshl_add_u64 v[54:55], v[50:51], 0, v[142:143]
	v_lshlrev_b64 v[56:57], 2, v[54:55]
	v_lshl_add_u64 v[58:59], s[16:17], 0, v[56:57]
	v_lshl_add_u64 v[54:55], v[54:55], 1, s[24:25]
	v_lshl_add_u64 v[56:57], s[28:29], 0, v[56:57]
	s_waitcnt vmcnt(47)
	v_mov_b32_e32 v50, v182
	v_mov_b32_e32 v51, v183
	v_mov_b32_e32 v52, v184
	v_mov_b32_e32 v53, v185
	v_pk_add_f32 v[46:47], v[46:47], v[52:53]
	v_pk_add_f32 v[44:45], v[44:45], v[50:51]
	global_store_dwordx4 v[56:57], v[44:47], off
	v_cvt_pk_bf16_f32 v50, v44, v45
	v_cvt_pk_bf16_f32 v51, v46, v47
	global_store_dwordx2 v[54:55], v[50:51], off
	v_mul_f32_e32 v45, v45, v45
	v_mul_f32_e32 v47, v47, v47
	v_fmac_f32_e32 v45, v44, v44
	v_fmac_f32_e32 v47, v46, v46
	v_add_f32_e32 v44, v45, v47
	s_waitcnt vmcnt(46)
	v_mov_b32_e32 v50, v186
	v_mov_b32_e32 v51, v187
	v_mov_b32_e32 v52, v188
	v_mov_b32_e32 v53, v189
	v_pk_add_f32 v[42:43], v[42:43], v[52:53]
	v_pk_add_f32 v[40:41], v[40:41], v[50:51]
	global_store_dwordx4 v[56:57], v[40:43], off offset:64
	v_cvt_pk_bf16_f32 v50, v40, v41
	v_cvt_pk_bf16_f32 v51, v42, v43
	global_store_dwordx2 v[54:55], v[50:51], off offset:32
	v_mul_f32_e32 v41, v41, v41
	v_mul_f32_e32 v43, v43, v43
	v_fmac_f32_e32 v41, v40, v40
	v_fmac_f32_e32 v43, v42, v42
	v_add_f32_e32 v40, v41, v43
	v_add_f32_e32 v40, v44, v40
	s_waitcnt vmcnt(45)
	v_mov_b32_e32 v50, v190
	v_mov_b32_e32 v51, v191
	v_mov_b32_e32 v52, v192
	v_mov_b32_e32 v53, v193
	v_pk_add_f32 v[38:39], v[38:39], v[52:53]
	v_pk_add_f32 v[36:37], v[36:37], v[50:51]
	global_store_dwordx4 v[56:57], v[36:39], off offset:512
	v_cvt_pk_bf16_f32 v50, v36, v37
	v_cvt_pk_bf16_f32 v51, v38, v39
	global_store_dwordx2 v[54:55], v[50:51], off offset:256
	v_mul_f32_e32 v37, v37, v37
	v_mul_f32_e32 v39, v39, v39
	v_fmac_f32_e32 v37, v36, v36
	v_fmac_f32_e32 v39, v38, v38
	v_add_f32_e32 v36, v37, v39
	v_add_f32_e32 v38, v40, v36
	s_waitcnt vmcnt(44)
	v_mov_b32_e32 v50, v194
	v_mov_b32_e32 v51, v195
	v_mov_b32_e32 v52, v196
	v_mov_b32_e32 v53, v197
	v_pk_add_f32 v[36:37], v[34:35], v[52:53]
	v_pk_add_f32 v[34:35], v[32:33], v[50:51]
	v_mul_f32_e32 v33, v37, v37
	v_mul_f32_e32 v32, v35, v35
	v_fmac_f32_e32 v32, v34, v34
	v_fmac_f32_e32 v33, v36, v36
	v_add_f32_e32 v32, v32, v33
	v_add_f32_e32 v32, v38, v32
	ds_bpermute_b32 v33, v116, v32
	global_store_dwordx4 v[56:57], v[34:37], off offset:576
	s_waitcnt lgkmcnt(0)
	v_add_f32_e32 v32, v32, v33
	ds_bpermute_b32 v33, v114, v32
	v_cvt_pk_bf16_f32 v34, v34, v35
	v_cvt_pk_bf16_f32 v35, v36, v37
	global_store_dwordx2 v[54:55], v[34:35], off offset:288
	s_and_saveexec_b64 s[58:59], s[12:13]
	s_cbranch_execz .LBB0_793
	s_waitcnt lgkmcnt(0)
	v_add_f32_e32 v34, v32, v33
	v_lshlrev_b64 v[32:33], 6, v[48:49]
	v_lshl_add_u64 v[32:33], s[26:27], 0, v[32:33]
	v_lshl_add_u64 v[32:33], s[56:57], 2, v[32:33]
	s_lshl_b32 s36, s74, 2
	v_lshl_add_u64 v[32:33], v[32:33], 0, s[36:37]
	global_store_dword v[32:33], v34, off
; __device__ __forceinline__ unsigned pk2(float lo, float hi) { unsigned r; asm volatile("v_cvt_pk_bf16_f32 %0, %1, %2" : "=v"(r) : "v"(lo), "v"(hi)); return r; }
;     __device__ __forceinline__ void operator()(const f32x4 (&acc)[2][2][4][2], const Unit& u, int wr, int wc, int fr, int fq) const {
;     ...
;             for (int m = 0; m < 4; ++m) {
;                 const int row = row0 + ai * 128 + m * 16; const size_t ro = (size_t)row * DM + col0;
;                 float s = 0.f;
; #pragma unroll
;                 for (int bj = 0; bj < 2; ++bj)
; #pragma unroll
;                     for (int n = 0; n < 2; ++n) {
;                         const size_t o = ro + bj * 128 + n * 16;
;                         const f32x4 xn = *(const f32x4*)(xo + o) + acc[ai][bj][m][n];
;                         *(f32x4*)(xf + o) = xn;
;                         u32x2 w; w.x = pk2(xn[0], xn[1]); w.y = pk2(xn[2], xn[3]); *(u32x2*)(xb + o) = w;
;                         s += (xn[0] * xn[0] + xn[1] * xn[1]) + (xn[2] * xn[2] + xn[3] * xn[3]);
;                     }
;                 s += __shfl_xor(s, 16); s += __shfl_xor(s, 32);
;                 if (fq == 0) ssq[(size_t)row * 16 + u.pn * 4 + wc] = s;
.LBB0_793:
	s_or_b64 exec, exec, s[58:59]
	v_add_u32_e32 v32, 0xa0, v146
	s_waitcnt lgkmcnt(0)
	v_ashrrev_i32_e32 v33, 31, v32
	v_lshlrev_b64 v[34:35], 10, v[32:33]
	v_lshl_add_u64 v[38:39], v[34:35], 0, v[142:143]
	v_lshlrev_b64 v[40:41], 2, v[38:39]
	v_lshl_add_u64 v[42:43], s[16:17], 0, v[40:41]
	v_lshl_add_u64 v[38:39], v[38:39], 1, s[24:25]
	v_lshl_add_u64 v[40:41], s[28:29], 0, v[40:41]
	s_waitcnt vmcnt(43)
	v_mov_b32_e32 v34, v198
	v_mov_b32_e32 v35, v199
	v_mov_b32_e32 v36, v200
	v_mov_b32_e32 v37, v201
	v_pk_add_f32 v[30:31], v[30:31], v[36:37]
	v_pk_add_f32 v[28:29], v[28:29], v[34:35]
	global_store_dwordx4 v[40:41], v[28:31], off
	v_cvt_pk_bf16_f32 v34, v28, v29
	v_cvt_pk_bf16_f32 v35, v30, v31
	global_store_dwordx2 v[38:39], v[34:35], off
	v_mul_f32_e32 v29, v29, v29
	v_mul_f32_e32 v31, v31, v31
	v_fmac_f32_e32 v29, v28, v28
	v_fmac_f32_e32 v31, v30, v30
	v_add_f32_e32 v28, v29, v31
	s_waitcnt vmcnt(42)
	v_mov_b32_e32 v34, v202
	v_mov_b32_e32 v35, v203
	v_mov_b32_e32 v36, v204
	v_mov_b32_e32 v37, v205
	v_pk_add_f32 v[26:27], v[26:27], v[36:37]
	v_pk_add_f32 v[24:25], v[24:25], v[34:35]
	global_store_dwordx4 v[40:41], v[24:27], off offset:64
	v_cvt_pk_bf16_f32 v34, v24, v25
	v_cvt_pk_bf16_f32 v35, v26, v27
	global_store_dwordx2 v[38:39], v[34:35], off offset:32
	v_mul_f32_e32 v25, v25, v25
	v_mul_f32_e32 v27, v27, v27
	v_fmac_f32_e32 v25, v24, v24
	v_fmac_f32_e32 v27, v26, v26
	v_add_f32_e32 v24, v25, v27
	v_add_f32_e32 v24, v28, v24
	s_waitcnt vmcnt(41)
	v_mov_b32_e32 v34, v206
	v_mov_b32_e32 v35, v207
	v_mov_b32_e32 v36, v208
	v_mov_b32_e32 v37, v209
	v_pk_add_f32 v[22:23], v[22:23], v[36:37]
	v_pk_add_f32 v[20:21], v[20:21], v[34:35]
	global_store_dwordx4 v[40:41], v[20:23], off offset:512
	v_cvt_pk_bf16_f32 v34, v20, v21
	v_cvt_pk_bf16_f32 v35, v22, v23
	global_store_dwordx2 v[38:39], v[34:35], off offset:256
	v_mul_f32_e32 v21, v21, v21
	v_mul_f32_e32 v23, v23, v23
	v_fmac_f32_e32 v21, v20, v20
	v_fmac_f32_e32 v23, v22, v22
	v_add_f32_e32 v20, v21, v23
	v_add_f32_e32 v22, v24, v20
	s_waitcnt vmcnt(40)
	v_mov_b32_e32 v34, v210
	v_mov_b32_e32 v35, v211
	v_mov_b32_e32 v36, v212
	v_mov_b32_e32 v37, v213
	v_pk_add_f32 v[20:21], v[18:19], v[36:37]
	v_pk_add_f32 v[18:19], v[16:17], v[34:35]
	v_mul_f32_e32 v17, v21, v21
	v_mul_f32_e32 v16, v19, v19
	v_fmac_f32_e32 v16, v18, v18
	v_fmac_f32_e32 v17, v20, v20
	v_add_f32_e32 v16, v16, v17
	v_add_f32_e32 v16, v22, v16
	ds_bpermute_b32 v17, v116, v16
	global_store_dwordx4 v[40:41], v[18:21], off offset:576
	s_waitcnt lgkmcnt(0)
	v_add_f32_e32 v16, v16, v17
	ds_bpermute_b32 v17, v114, v16
	v_cvt_pk_bf16_f32 v18, v18, v19
	v_cvt_pk_bf16_f32 v19, v20, v21
	global_store_dwordx2 v[38:39], v[18:19], off offset:288
	s_and_saveexec_b64 s[58:59], s[12:13]
	s_cbranch_execz .LBB0_795
	s_waitcnt lgkmcnt(0)
	v_add_f32_e32 v18, v16, v17
	v_lshlrev_b64 v[16:17], 6, v[32:33]
	v_lshl_add_u64 v[16:17], s[26:27], 0, v[16:17]
	v_lshl_add_u64 v[16:17], s[56:57], 2, v[16:17]
	s_lshl_b32 s36, s74, 2
	v_lshl_add_u64 v[16:17], v[16:17], 0, s[36:37]
	global_store_dword v[16:17], v18, off
.LBB0_795:
	s_or_b64 exec, exec, s[58:59]
	v_add_u32_e32 v16, 0xb0, v146
	s_waitcnt lgkmcnt(0)
	v_ashrrev_i32_e32 v17, 31, v16
	v_lshlrev_b64 v[18:19], 10, v[16:17]
	v_lshl_add_u64 v[22:23], v[18:19], 0, v[142:143]
	v_lshlrev_b64 v[24:25], 2, v[22:23]
	v_lshl_add_u64 v[26:27], s[16:17], 0, v[24:25]
	v_lshl_add_u64 v[22:23], v[22:23], 1, s[24:25]
	v_lshl_add_u64 v[24:25], s[28:29], 0, v[24:25]
	s_waitcnt vmcnt(39)
	v_mov_b32_e32 v18, v214
	v_mov_b32_e32 v19, v215
	v_mov_b32_e32 v20, v216
	v_mov_b32_e32 v21, v217
	v_pk_add_f32 v[14:15], v[14:15], v[20:21]
	v_pk_add_f32 v[12:13], v[12:13], v[18:19]
	global_store_dwordx4 v[24:25], v[12:15], off
	v_cvt_pk_bf16_f32 v18, v12, v13
	v_cvt_pk_bf16_f32 v19, v14, v15
	global_store_dwordx2 v[22:23], v[18:19], off
	v_mul_f32_e32 v13, v13, v13
	v_mul_f32_e32 v15, v15, v15
	v_fmac_f32_e32 v13, v12, v12
	v_fmac_f32_e32 v15, v14, v14
	v_add_f32_e32 v12, v13, v15
	s_waitcnt vmcnt(38)
	v_mov_b32_e32 v18, v218
	v_mov_b32_e32 v19, v219
	v_mov_b32_e32 v20, v220
	v_mov_b32_e32 v21, v221
	v_pk_add_f32 v[10:11], v[10:11], v[20:21]
	v_pk_add_f32 v[8:9], v[8:9], v[18:19]
	global_store_dwordx4 v[24:25], v[8:11], off offset:64
	v_cvt_pk_bf16_f32 v18, v8, v9
	v_cvt_pk_bf16_f32 v19, v10, v11
	global_store_dwordx2 v[22:23], v[18:19], off offset:32
	v_mul_f32_e32 v9, v9, v9
	v_mul_f32_e32 v11, v11, v11
	v_fmac_f32_e32 v9, v8, v8
	v_fmac_f32_e32 v11, v10, v10
	v_add_f32_e32 v8, v9, v11
	v_add_f32_e32 v8, v12, v8
	s_waitcnt vmcnt(37)
	v_mov_b32_e32 v18, v232
	v_mov_b32_e32 v19, v233
	v_mov_b32_e32 v20, v234
	v_mov_b32_e32 v21, v235
	v_pk_add_f32 v[6:7], v[6:7], v[20:21]
	v_pk_add_f32 v[4:5], v[4:5], v[18:19]
	global_store_dwordx4 v[24:25], v[4:7], off offset:512
	v_cvt_pk_bf16_f32 v18, v4, v5
	v_cvt_pk_bf16_f32 v19, v6, v7
	global_store_dwordx2 v[22:23], v[18:19], off offset:256
	v_mul_f32_e32 v5, v5, v5
	v_mul_f32_e32 v7, v7, v7
	v_fmac_f32_e32 v5, v4, v4
	v_fmac_f32_e32 v7, v6, v6
	v_add_f32_e32 v4, v5, v7
	v_add_f32_e32 v6, v8, v4
	s_waitcnt vmcnt(36)
	v_mov_b32_e32 v18, v236
	v_mov_b32_e32 v19, v237
	v_mov_b32_e32 v20, v238
	v_mov_b32_e32 v21, v239
	v_pk_add_f32 v[4:5], v[2:3], v[20:21]
	v_pk_add_f32 v[2:3], v[0:1], v[18:19]
	v_mul_f32_e32 v1, v5, v5
	v_mul_f32_e32 v0, v3, v3
	v_fmac_f32_e32 v0, v2, v2
	v_fmac_f32_e32 v1, v4, v4
	v_add_f32_e32 v0, v0, v1
	v_add_f32_e32 v0, v6, v0
	ds_bpermute_b32 v1, v116, v0
	global_store_dwordx4 v[24:25], v[2:5], off offset:576
	s_waitcnt lgkmcnt(0)
	v_add_f32_e32 v0, v0, v1
	ds_bpermute_b32 v1, v114, v0
	v_cvt_pk_bf16_f32 v2, v2, v3
	v_cvt_pk_bf16_f32 v3, v4, v5
	global_store_dwordx2 v[22:23], v[2:3], off offset:288
	s_and_saveexec_b64 s[16:17], s[12:13]
	s_cbranch_execz .LBB0_754
	s_waitcnt lgkmcnt(0)
	v_add_f32_e32 v2, v0, v1
	v_lshlrev_b64 v[0:1], 6, v[16:17]
	v_lshl_add_u64 v[0:1], s[26:27], 0, v[0:1]
	v_lshl_add_u64 v[0:1], s[56:57], 2, v[0:1]
	s_lshl_b32 s36, s74, 2
	v_lshl_add_u64 v[0:1], v[0:1], 0, s[36:37]
	global_store_dword v[0:1], v2, off
	s_branch .LBB0_754

; __device__ __forceinline__ unsigned pk2(float lo, float hi) { unsigned r; asm volatile("v_cvt_pk_bf16_f32 %0, %1, %2" : "=v"(r) : "v"(lo), "v"(hi)); return r; }
;     __device__ __forceinline__ void operator()(const f32x4 (&acc)[2][2][4][2], const Unit& u, int wr, int wc, int fr, int fq) const {
;         const int row0 = u.pm * 256 + wr * 64 + fr, col0 = u.pn * 256 + wc * 32 + 4 * fq;
;         const float* xo = (u.pm < 64) ? xoldA : (xoldB - (size_t)T_P * DM);
; #pragma unroll
;         for (int ai = 0; ai < 2; ++ai)
; #pragma unroll
;             for (int m = 0; m < 4; ++m) {
;                 const int row = row0 + ai * 128 + m * 16; const size_t ro = (size_t)row * DM + col0;
;                 float s = 0.f;
; #pragma unroll
;                 for (int bj = 0; bj < 2; ++bj)
; #pragma unroll
;                     for (int n = 0; n < 2; ++n) {
;                         const size_t o = ro + bj * 128 + n * 16;
;                         const f32x4 xn = *(const f32x4*)(xo + o) + acc[ai][bj][m][n];
;                         *(f32x4*)(xf + o) = xn;
;                         u32x2 w; w.x = pk2(xn[0], xn[1]); w.y = pk2(xn[2], xn[3]); *(u32x2*)(xb + o) = w;
;                         s += (xn[0] * xn[0] + xn[1] * xn[1]) + (xn[2] * xn[2] + xn[3] * xn[3]);
;                     }
;                 s += __shfl_xor(s, 16); s += __shfl_xor(s, 32);
;                 if (fq == 0) ssq[(size_t)row * 16 + u.pn * 4 + wc] = s;
.LBB0_1037:
	v_lshl_add_u32 v138, s58, 8, v140
	v_lshl_or_b32 v136, s56, 8, v142
	v_ashrrev_i32_e32 v139, 31, v138
	v_ashrrev_i32_e32 v137, 31, v136
	v_lshlrev_b64 v[148:149], 10, v[138:139]
	s_cmp_lt_i32 s58, 64
	v_lshl_add_u64 v[152:153], v[148:149], 0, v[136:137]
	s_cselect_b32 s17, s21, -1
	s_cselect_b32 s16, s20, 0xfc000000
	v_lshlrev_b64 v[154:155], 2, v[152:153]
	v_lshl_add_u64 v[156:157], s[16:17], 0, v[154:155]
	v_subrev_u32_e32 v162, s16, v156
	v_add_u32_e32 v163, 0x0, v162
	global_load_dwordx4 v[170:173], v163, s[16:17]
	v_add_u32_e32 v163, 0x40, v162
	global_load_dwordx4 v[174:177], v163, s[16:17]
	v_add_u32_e32 v163, 0x200, v162
	global_load_dwordx4 v[178:181], v163, s[16:17]
	v_add_u32_e32 v163, 0x240, v162
	global_load_dwordx4 v[182:185], v163, s[16:17]
	v_add_u32_e32 v163, 0x10000, v162
	global_load_dwordx4 v[186:189], v163, s[16:17]
	v_add_u32_e32 v163, 0x10040, v162
	global_load_dwordx4 v[190:193], v163, s[16:17]
	v_add_u32_e32 v163, 0x10200, v162
	global_load_dwordx4 v[194:197], v163, s[16:17]
	v_add_u32_e32 v163, 0x10240, v162
	global_load_dwordx4 v[198:201], v163, s[16:17]
	v_add_u32_e32 v163, 0x20000, v162
	global_load_dwordx4 v[202:205], v163, s[16:17]
	v_add_u32_e32 v163, 0x20040, v162
	global_load_dwordx4 v[206:209], v163, s[16:17]
	v_add_u32_e32 v163, 0x20200, v162
	global_load_dwordx4 v[210:213], v163, s[16:17]
	v_add_u32_e32 v163, 0x20240, v162
	global_load_dwordx4 v[232:235], v163, s[16:17]
	v_add_u32_e32 v163, 0x30000, v162
	global_load_dwordx4 v[236:239], v163, s[16:17]
	v_add_u32_e32 v163, 0x30040, v162
	global_load_dwordx4 v[240:243], v163, s[16:17]
	v_add_u32_e32 v163, 0x30200, v162
	global_load_dwordx4 v[244:247], v163, s[16:17]
	v_add_u32_e32 v163, 0x30240, v162
	global_load_dwordx4 v[248:251], v163, s[16:17]
	v_add_u32_e32 v163, 0x80000, v162
	global_load_dwordx4 v[252:255], v163, s[16:17]
	v_lshl_add_u64 v[158:159], v[152:153], 1, s[26:27]
	v_lshl_add_u64 v[160:161], s[20:21], 0, v[154:155]
	v_xor_b32_e32 v147, 32, v146
	s_lshl_b32 s56, s56, 2
	s_ashr_i32 s57, s56, 31
	s_waitcnt vmcnt(16)
	v_mov_b32_e32 v148, v170
	v_mov_b32_e32 v149, v171
	v_mov_b32_e32 v150, v172
	v_mov_b32_e32 v151, v173
	v_add_u32_e32 v163, 0x80040, v162
	global_load_dwordx4 v[170:173], v163, s[16:17]
	v_pk_add_f32 v[126:127], v[126:127], v[150:151]
	v_pk_add_f32 v[124:125], v[124:125], v[148:149]
	global_store_dwordx4 v[160:161], v[124:127], off
	v_cvt_pk_bf16_f32 v148, v124, v125
	v_cvt_pk_bf16_f32 v149, v126, v127
	global_store_dwordx2 v[158:159], v[148:149], off
	s_waitcnt vmcnt(18)
	v_mov_b32_e32 v148, v174
	v_mov_b32_e32 v149, v175
	v_mov_b32_e32 v150, v176
	v_mov_b32_e32 v151, v177
	v_add_u32_e32 v163, 0x80200, v162
	global_load_dwordx4 v[174:177], v163, s[16:17]
	v_pk_add_f32 v[122:123], v[122:123], v[150:151]
	v_pk_add_f32 v[120:121], v[120:121], v[148:149]
	global_store_dwordx4 v[160:161], v[120:123], off offset:64
	v_cvt_pk_bf16_f32 v148, v120, v121
	v_cvt_pk_bf16_f32 v149, v122, v123
	global_store_dwordx2 v[158:159], v[148:149], off offset:32
	s_waitcnt vmcnt(20)
	v_mov_b32_e32 v148, v178
	v_mov_b32_e32 v149, v179
	v_mov_b32_e32 v150, v180
	v_mov_b32_e32 v151, v181
	v_add_u32_e32 v163, 0x80240, v162
	global_load_dwordx4 v[178:181], v163, s[16:17]
	v_pk_add_f32 v[150:151], v[118:119], v[150:151]
	v_pk_add_f32 v[148:149], v[116:117], v[148:149]
	global_store_dwordx4 v[160:161], v[148:151], off offset:512
	v_cvt_pk_bf16_f32 v116, v148, v149
	v_cvt_pk_bf16_f32 v117, v150, v151
	global_store_dwordx2 v[158:159], v[116:117], off offset:256
	v_mul_f32_e32 v118, v125, v125
	v_mul_f32_e32 v119, v127, v127
	v_fmac_f32_e32 v118, v124, v124
	v_fmac_f32_e32 v119, v126, v126
	v_add_f32_e32 v118, v118, v119
	v_mul_f32_e32 v119, v121, v121
	v_mul_f32_e32 v121, v123, v123
	v_fmac_f32_e32 v119, v120, v120
	v_fmac_f32_e32 v121, v122, v122
	v_add_f32_e32 v119, v119, v121
	v_add_f32_e32 v118, v118, v119
	v_mul_f32_e32 v119, v149, v149
	v_mul_f32_e32 v120, v151, v151
	v_fmac_f32_e32 v119, v148, v148
	v_fmac_f32_e32 v120, v150, v150
	v_add_f32_e32 v119, v119, v120
	v_and_b32_e32 v117, 64, v146
	v_add_f32_e32 v122, v118, v119
	v_xor_b32_e32 v116, 16, v146
	v_add_u32_e32 v117, 64, v117
	v_cmp_lt_i32_e32 vcc, v116, v117
	s_waitcnt vmcnt(22)
	v_mov_b32_e32 v152, v182
	v_mov_b32_e32 v153, v183
	v_mov_b32_e32 v154, v184
	v_mov_b32_e32 v155, v185
	v_add_u32_e32 v163, 0x90000, v162
	global_load_dwordx4 v[182:185], v163, s[16:17]
	v_pk_add_f32 v[120:121], v[114:115], v[154:155]
	v_pk_add_f32 v[118:119], v[112:113], v[152:153]
	v_mul_f32_e32 v113, v121, v121
	v_mul_f32_e32 v112, v119, v119
	v_fmac_f32_e32 v112, v118, v118
	v_fmac_f32_e32 v113, v120, v120
	v_cndmask_b32_e32 v116, v146, v116, vcc
	v_add_f32_e32 v112, v112, v113
	v_lshlrev_b32_e32 v116, 2, v116
	v_add_f32_e32 v112, v122, v112
	ds_bpermute_b32 v113, v116, v112
	v_cmp_lt_i32_e32 vcc, v147, v117
	global_store_dwordx4 v[160:161], v[118:121], off offset:576
	s_waitcnt lgkmcnt(0)
	v_add_f32_e32 v112, v112, v113
	v_cndmask_b32_e32 v114, v146, v147, vcc
	v_lshlrev_b32_e32 v114, 2, v114
	ds_bpermute_b32 v113, v114, v112
	v_cvt_pk_bf16_f32 v118, v118, v119
	v_cvt_pk_bf16_f32 v119, v120, v121
	global_store_dwordx2 v[158:159], v[118:119], off offset:288
	s_and_saveexec_b64 s[58:59], s[12:13]
	s_cbranch_execz .LBB0_1039
	s_waitcnt lgkmcnt(0)
	v_add_f32_e32 v115, v112, v113
	v_lshlrev_b64 v[112:113], 6, v[138:139]
	v_lshl_add_u64 v[112:113], s[28:29], 0, v[112:113]
	v_lshl_add_u64 v[112:113], s[56:57], 2, v[112:113]
	s_lshl_b32 s30, s84, 2
	v_lshl_add_u64 v[112:113], v[112:113], 0, s[30:31]
	global_store_dword v[112:113], v115, off
; __device__ __forceinline__ unsigned pk2(float lo, float hi) { unsigned r; asm volatile("v_cvt_pk_bf16_f32 %0, %1, %2" : "=v"(r) : "v"(lo), "v"(hi)); return r; }
;     __device__ __forceinline__ void operator()(const f32x4 (&acc)[2][2][4][2], const Unit& u, int wr, int wc, int fr, int fq) const {
;     ...
;             for (int m = 0; m < 4; ++m) {
;                 const int row = row0 + ai * 128 + m * 16; const size_t ro = (size_t)row * DM + col0;
;                 float s = 0.f;
; #pragma unroll
;                 for (int bj = 0; bj < 2; ++bj)
; #pragma unroll
;                     for (int n = 0; n < 2; ++n) {
;                         const size_t o = ro + bj * 128 + n * 16;
;                         const f32x4 xn = *(const f32x4*)(xo + o) + acc[ai][bj][m][n];
;                         *(f32x4*)(xf + o) = xn;
;                         u32x2 w; w.x = pk2(xn[0], xn[1]); w.y = pk2(xn[2], xn[3]); *(u32x2*)(xb + o) = w;
;                         s += (xn[0] * xn[0] + xn[1] * xn[1]) + (xn[2] * xn[2] + xn[3] * xn[3]);
;                     }
;                 s += __shfl_xor(s, 16); s += __shfl_xor(s, 32);
;                 if (fq == 0) ssq[(size_t)row * 16 + u.pn * 4 + wc] = s;
.LBB0_1039:
	s_or_b64 exec, exec, s[58:59]
	v_or_b32_e32 v112, 16, v138
	s_waitcnt lgkmcnt(0)
	v_ashrrev_i32_e32 v113, 31, v112
	v_lshlrev_b64 v[118:119], 10, v[112:113]
	v_lshl_add_u64 v[122:123], v[118:119], 0, v[136:137]
	v_lshlrev_b64 v[124:125], 2, v[122:123]
	v_lshl_add_u64 v[126:127], s[16:17], 0, v[124:125]
	v_lshl_add_u64 v[122:123], v[122:123], 1, s[26:27]
	v_lshl_add_u64 v[124:125], s[20:21], 0, v[124:125]
	s_waitcnt vmcnt(24)
	v_mov_b32_e32 v118, v186
	v_mov_b32_e32 v119, v187
	v_mov_b32_e32 v120, v188
	v_mov_b32_e32 v121, v189
	v_add_u32_e32 v163, 0x90040, v162
	global_load_dwordx4 v[186:189], v163, s[16:17]
	v_pk_add_f32 v[110:111], v[110:111], v[120:121]
	v_pk_add_f32 v[108:109], v[108:109], v[118:119]
	global_store_dwordx4 v[124:125], v[108:111], off
	v_cvt_pk_bf16_f32 v118, v108, v109
	v_cvt_pk_bf16_f32 v119, v110, v111
	global_store_dwordx2 v[122:123], v[118:119], off
	v_mul_f32_e32 v109, v109, v109
	v_mul_f32_e32 v111, v111, v111
	v_fmac_f32_e32 v109, v108, v108
	v_fmac_f32_e32 v111, v110, v110
	v_add_f32_e32 v108, v109, v111
	s_waitcnt vmcnt(26)
	v_mov_b32_e32 v118, v190
	v_mov_b32_e32 v119, v191
	v_mov_b32_e32 v120, v192
	v_mov_b32_e32 v121, v193
	v_add_u32_e32 v163, 0x90200, v162
	global_load_dwordx4 v[190:193], v163, s[16:17]
	v_pk_add_f32 v[106:107], v[106:107], v[120:121]
	v_pk_add_f32 v[104:105], v[104:105], v[118:119]
	global_store_dwordx4 v[124:125], v[104:107], off offset:64
	v_cvt_pk_bf16_f32 v118, v104, v105
	v_cvt_pk_bf16_f32 v119, v106, v107
	global_store_dwordx2 v[122:123], v[118:119], off offset:32
	v_mul_f32_e32 v105, v105, v105
	v_mul_f32_e32 v107, v107, v107
	v_fmac_f32_e32 v105, v104, v104
	v_fmac_f32_e32 v107, v106, v106
	v_add_f32_e32 v104, v105, v107
	v_add_f32_e32 v104, v108, v104
	s_waitcnt vmcnt(28)
	v_mov_b32_e32 v118, v194
	v_mov_b32_e32 v119, v195
	v_mov_b32_e32 v120, v196
	v_mov_b32_e32 v121, v197
	v_add_u32_e32 v163, 0x90240, v162
	global_load_dwordx4 v[194:197], v163, s[16:17]
	v_pk_add_f32 v[102:103], v[102:103], v[120:121]
	v_pk_add_f32 v[100:101], v[100:101], v[118:119]
	global_store_dwordx4 v[124:125], v[100:103], off offset:512
	v_cvt_pk_bf16_f32 v118, v100, v101
	v_cvt_pk_bf16_f32 v119, v102, v103
	global_store_dwordx2 v[122:123], v[118:119], off offset:256
	v_mul_f32_e32 v101, v101, v101
	v_mul_f32_e32 v103, v103, v103
	v_fmac_f32_e32 v101, v100, v100
	v_fmac_f32_e32 v103, v102, v102
	v_add_f32_e32 v100, v101, v103
	v_add_f32_e32 v102, v104, v100
	s_waitcnt vmcnt(30)
	v_mov_b32_e32 v118, v198
	v_mov_b32_e32 v119, v199
	v_mov_b32_e32 v120, v200
	v_mov_b32_e32 v121, v201
	v_add_u32_e32 v163, 0xa0000, v162
	global_load_dwordx4 v[198:201], v163, s[16:17]
	v_pk_add_f32 v[100:101], v[98:99], v[120:121]
	v_pk_add_f32 v[98:99], v[96:97], v[118:119]
	v_mul_f32_e32 v97, v101, v101
	v_mul_f32_e32 v96, v99, v99
	v_fmac_f32_e32 v96, v98, v98
	v_fmac_f32_e32 v97, v100, v100
	v_add_f32_e32 v96, v96, v97
	v_add_f32_e32 v96, v102, v96
	ds_bpermute_b32 v97, v116, v96
	global_store_dwordx4 v[124:125], v[98:101], off offset:576
	s_waitcnt lgkmcnt(0)
	v_add_f32_e32 v96, v96, v97
	ds_bpermute_b32 v97, v114, v96
	v_cvt_pk_bf16_f32 v98, v98, v99
	v_cvt_pk_bf16_f32 v99, v100, v101
	global_store_dwordx2 v[122:123], v[98:99], off offset:288
	s_and_saveexec_b64 s[58:59], s[12:13]
	s_cbranch_execz .LBB0_1041
	s_waitcnt lgkmcnt(0)
	v_add_f32_e32 v98, v96, v97
	v_lshlrev_b64 v[96:97], 6, v[112:113]
	v_lshl_add_u64 v[96:97], s[28:29], 0, v[96:97]
	v_lshl_add_u64 v[96:97], s[56:57], 2, v[96:97]
	s_lshl_b32 s30, s84, 2
	v_lshl_add_u64 v[96:97], v[96:97], 0, s[30:31]
	global_store_dword v[96:97], v98, off
.LBB0_1041:
	s_or_b64 exec, exec, s[58:59]
	v_or_b32_e32 v96, 32, v138
	s_waitcnt lgkmcnt(0)
	v_ashrrev_i32_e32 v97, 31, v96
	v_lshlrev_b64 v[98:99], 10, v[96:97]
	v_lshl_add_u64 v[102:103], v[98:99], 0, v[136:137]
	v_lshlrev_b64 v[104:105], 2, v[102:103]
	v_lshl_add_u64 v[106:107], s[16:17], 0, v[104:105]
	v_lshl_add_u64 v[102:103], v[102:103], 1, s[26:27]
	v_lshl_add_u64 v[104:105], s[20:21], 0, v[104:105]
	s_waitcnt vmcnt(32)
	v_mov_b32_e32 v98, v202
	v_mov_b32_e32 v99, v203
	v_mov_b32_e32 v100, v204
	v_mov_b32_e32 v101, v205
	v_add_u32_e32 v163, 0xa0040, v162
	global_load_dwordx4 v[202:205], v163, s[16:17]
	v_pk_add_f32 v[94:95], v[94:95], v[100:101]
	v_pk_add_f32 v[92:93], v[92:93], v[98:99]
	global_store_dwordx4 v[104:105], v[92:95], off
	v_cvt_pk_bf16_f32 v98, v92, v93
	v_cvt_pk_bf16_f32 v99, v94, v95
	global_store_dwordx2 v[102:103], v[98:99], off
	v_mul_f32_e32 v93, v93, v93
	v_mul_f32_e32 v95, v95, v95
	v_fmac_f32_e32 v93, v92, v92
	v_fmac_f32_e32 v95, v94, v94
	v_add_f32_e32 v92, v93, v95
	s_waitcnt vmcnt(34)
	v_mov_b32_e32 v98, v206
	v_mov_b32_e32 v99, v207
	v_mov_b32_e32 v100, v208
	v_mov_b32_e32 v101, v209
	v_add_u32_e32 v163, 0xa0200, v162
	global_load_dwordx4 v[206:209], v163, s[16:17]
	v_pk_add_f32 v[90:91], v[90:91], v[100:101]
	v_pk_add_f32 v[88:89], v[88:89], v[98:99]
	global_store_dwordx4 v[104:105], v[88:91], off offset:64
	v_cvt_pk_bf16_f32 v98, v88, v89
	v_cvt_pk_bf16_f32 v99, v90, v91
	global_store_dwordx2 v[102:103], v[98:99], off offset:32
	v_mul_f32_e32 v89, v89, v89
	v_mul_f32_e32 v91, v91, v91
	v_fmac_f32_e32 v89, v88, v88
	v_fmac_f32_e32 v91, v90, v90
	v_add_f32_e32 v88, v89, v91
	v_add_f32_e32 v88, v92, v88
	s_waitcnt vmcnt(36)
	v_mov_b32_e32 v98, v210
	v_mov_b32_e32 v99, v211
	v_mov_b32_e32 v100, v212
	v_mov_b32_e32 v101, v213
	v_add_u32_e32 v163, 0xa0240, v162
	global_load_dwordx4 v[210:213], v163, s[16:17]
	v_pk_add_f32 v[86:87], v[86:87], v[100:101]
	v_pk_add_f32 v[84:85], v[84:85], v[98:99]
	global_store_dwordx4 v[104:105], v[84:87], off offset:512
	v_cvt_pk_bf16_f32 v98, v84, v85
	v_cvt_pk_bf16_f32 v99, v86, v87
	global_store_dwordx2 v[102:103], v[98:99], off offset:256
	v_mul_f32_e32 v85, v85, v85
	v_mul_f32_e32 v87, v87, v87
	v_fmac_f32_e32 v85, v84, v84
	v_fmac_f32_e32 v87, v86, v86
	v_add_f32_e32 v84, v85, v87
	v_add_f32_e32 v86, v88, v84
	s_waitcnt vmcnt(38)
	v_mov_b32_e32 v98, v232
	v_mov_b32_e32 v99, v233
	v_mov_b32_e32 v100, v234
	v_mov_b32_e32 v101, v235
	v_add_u32_e32 v163, 0xb0000, v162
	global_load_dwordx4 v[232:235], v163, s[16:17]
	v_pk_add_f32 v[84:85], v[82:83], v[100:101]
	v_pk_add_f32 v[82:83], v[80:81], v[98:99]
	v_mul_f32_e32 v81, v85, v85
	v_mul_f32_e32 v80, v83, v83
	v_fmac_f32_e32 v80, v82, v82
	v_fmac_f32_e32 v81, v84, v84
	v_add_f32_e32 v80, v80, v81
	v_add_f32_e32 v80, v86, v80
	ds_bpermute_b32 v81, v116, v80
	global_store_dwordx4 v[104:105], v[82:85], off offset:576
	s_waitcnt lgkmcnt(0)
	v_add_f32_e32 v80, v80, v81
	ds_bpermute_b32 v81, v114, v80
	v_cvt_pk_bf16_f32 v82, v82, v83
	v_cvt_pk_bf16_f32 v83, v84, v85
	global_store_dwordx2 v[102:103], v[82:83], off offset:288
	s_and_saveexec_b64 s[58:59], s[12:13]
	s_cbranch_execz .LBB0_1043
	s_waitcnt lgkmcnt(0)
	v_add_f32_e32 v82, v80, v81
	v_lshlrev_b64 v[80:81], 6, v[96:97]
	v_lshl_add_u64 v[80:81], s[28:29], 0, v[80:81]
	v_lshl_add_u64 v[80:81], s[56:57], 2, v[80:81]
	s_lshl_b32 s30, s84, 2
	v_lshl_add_u64 v[80:81], v[80:81], 0, s[30:31]
	global_store_dword v[80:81], v82, off
; __device__ __forceinline__ unsigned pk2(float lo, float hi) { unsigned r; asm volatile("v_cvt_pk_bf16_f32 %0, %1, %2" : "=v"(r) : "v"(lo), "v"(hi)); return r; }
;     __device__ __forceinline__ void operator()(const f32x4 (&acc)[2][2][4][2], const Unit& u, int wr, int wc, int fr, int fq) const {
;     ...
;             for (int m = 0; m < 4; ++m) {
;                 const int row = row0 + ai * 128 + m * 16; const size_t ro = (size_t)row * DM + col0;
;                 float s = 0.f;
; #pragma unroll
;                 for (int bj = 0; bj < 2; ++bj)
; #pragma unroll
;                     for (int n = 0; n < 2; ++n) {
;                         const size_t o = ro + bj * 128 + n * 16;
;                         const f32x4 xn = *(const f32x4*)(xo + o) + acc[ai][bj][m][n];
;                         *(f32x4*)(xf + o) = xn;
;                         u32x2 w; w.x = pk2(xn[0], xn[1]); w.y = pk2(xn[2], xn[3]); *(u32x2*)(xb + o) = w;
;                         s += (xn[0] * xn[0] + xn[1] * xn[1]) + (xn[2] * xn[2] + xn[3] * xn[3]);
;                     }
;                 s += __shfl_xor(s, 16); s += __shfl_xor(s, 32);
;                 if (fq == 0) ssq[(size_t)row * 16 + u.pn * 4 + wc] = s;
.LBB0_1043:
	s_or_b64 exec, exec, s[58:59]
	v_or_b32_e32 v80, 48, v138
	s_waitcnt lgkmcnt(0)
	v_ashrrev_i32_e32 v81, 31, v80
	v_lshlrev_b64 v[82:83], 10, v[80:81]
	v_lshl_add_u64 v[86:87], v[82:83], 0, v[136:137]
	v_lshlrev_b64 v[88:89], 2, v[86:87]
	v_lshl_add_u64 v[90:91], s[16:17], 0, v[88:89]
	v_lshl_add_u64 v[86:87], v[86:87], 1, s[26:27]
	v_lshl_add_u64 v[88:89], s[20:21], 0, v[88:89]
	s_waitcnt vmcnt(40)
	v_mov_b32_e32 v82, v236
	v_mov_b32_e32 v83, v237
	v_mov_b32_e32 v84, v238
	v_mov_b32_e32 v85, v239
	v_add_u32_e32 v163, 0xb0040, v162
	global_load_dwordx4 v[236:239], v163, s[16:17]
	v_pk_add_f32 v[78:79], v[78:79], v[84:85]
	v_pk_add_f32 v[76:77], v[76:77], v[82:83]
	global_store_dwordx4 v[88:89], v[76:79], off
	v_cvt_pk_bf16_f32 v82, v76, v77
	v_cvt_pk_bf16_f32 v83, v78, v79
	global_store_dwordx2 v[86:87], v[82:83], off
	v_mul_f32_e32 v77, v77, v77
	v_mul_f32_e32 v79, v79, v79
	v_fmac_f32_e32 v77, v76, v76
	v_fmac_f32_e32 v79, v78, v78
	v_add_f32_e32 v76, v77, v79
	s_waitcnt vmcnt(42)
	v_mov_b32_e32 v82, v240
	v_mov_b32_e32 v83, v241
	v_mov_b32_e32 v84, v242
	v_mov_b32_e32 v85, v243
	v_add_u32_e32 v163, 0xb0200, v162
	global_load_dwordx4 v[240:243], v163, s[16:17]
	v_pk_add_f32 v[74:75], v[74:75], v[84:85]
	v_pk_add_f32 v[72:73], v[72:73], v[82:83]
	global_store_dwordx4 v[88:89], v[72:75], off offset:64
	v_cvt_pk_bf16_f32 v82, v72, v73
	v_cvt_pk_bf16_f32 v83, v74, v75
	global_store_dwordx2 v[86:87], v[82:83], off offset:32
	v_mul_f32_e32 v73, v73, v73
	v_mul_f32_e32 v75, v75, v75
	v_fmac_f32_e32 v73, v72, v72
	v_fmac_f32_e32 v75, v74, v74
	v_add_f32_e32 v72, v73, v75
	v_add_f32_e32 v72, v76, v72
	s_waitcnt vmcnt(44)
	v_mov_b32_e32 v82, v244
	v_mov_b32_e32 v83, v245
	v_mov_b32_e32 v84, v246
	v_mov_b32_e32 v85, v247
	v_add_u32_e32 v163, 0xb0240, v162
	global_load_dwordx4 v[244:247], v163, s[16:17]
	v_pk_add_f32 v[70:71], v[70:71], v[84:85]
	v_pk_add_f32 v[68:69], v[68:69], v[82:83]
	global_store_dwordx4 v[88:89], v[68:71], off offset:512
	v_cvt_pk_bf16_f32 v82, v68, v69
	v_cvt_pk_bf16_f32 v83, v70, v71
	global_store_dwordx2 v[86:87], v[82:83], off offset:256
	v_mul_f32_e32 v69, v69, v69
	v_mul_f32_e32 v71, v71, v71
	v_fmac_f32_e32 v69, v68, v68
	v_fmac_f32_e32 v71, v70, v70
	v_add_f32_e32 v68, v69, v71
	v_add_f32_e32 v70, v72, v68
	s_waitcnt vmcnt(46)
	v_mov_b32_e32 v82, v248
	v_mov_b32_e32 v83, v249
	v_mov_b32_e32 v84, v250
	v_mov_b32_e32 v85, v251
	v_pk_add_f32 v[68:69], v[66:67], v[84:85]
	v_pk_add_f32 v[66:67], v[64:65], v[82:83]
	v_mul_f32_e32 v65, v69, v69
	v_mul_f32_e32 v64, v67, v67
	v_fmac_f32_e32 v64, v66, v66
	v_fmac_f32_e32 v65, v68, v68
	v_add_f32_e32 v64, v64, v65
	v_add_f32_e32 v64, v70, v64
	ds_bpermute_b32 v65, v116, v64
	global_store_dwordx4 v[88:89], v[66:69], off offset:576
	s_waitcnt lgkmcnt(0)
	v_add_f32_e32 v64, v64, v65
	ds_bpermute_b32 v65, v114, v64
	v_cvt_pk_bf16_f32 v66, v66, v67
	v_cvt_pk_bf16_f32 v67, v68, v69
	global_store_dwordx2 v[86:87], v[66:67], off offset:288
	s_and_saveexec_b64 s[58:59], s[12:13]
	s_cbranch_execz .LBB0_1045
	s_waitcnt lgkmcnt(0)
	v_add_f32_e32 v66, v64, v65
	v_lshlrev_b64 v[64:65], 6, v[80:81]
	v_lshl_add_u64 v[64:65], s[28:29], 0, v[64:65]
	v_lshl_add_u64 v[64:65], s[56:57], 2, v[64:65]
	s_lshl_b32 s30, s84, 2
	v_lshl_add_u64 v[64:65], v[64:65], 0, s[30:31]
	global_store_dword v[64:65], v66, off
.LBB0_1045:
	s_or_b64 exec, exec, s[58:59]
	v_add_u32_e32 v64, 0x80, v138
	s_waitcnt lgkmcnt(0)
	v_ashrrev_i32_e32 v65, 31, v64
	v_lshlrev_b64 v[66:67], 10, v[64:65]
	v_lshl_add_u64 v[70:71], v[66:67], 0, v[136:137]
	v_lshlrev_b64 v[72:73], 2, v[70:71]
	v_lshl_add_u64 v[74:75], s[16:17], 0, v[72:73]
	v_lshl_add_u64 v[70:71], v[70:71], 1, s[26:27]
	v_lshl_add_u64 v[72:73], s[20:21], 0, v[72:73]
	s_waitcnt vmcnt(47)
	v_mov_b32_e32 v66, v252
	v_mov_b32_e32 v67, v253
	v_mov_b32_e32 v68, v254
	v_mov_b32_e32 v69, v255
	v_pk_add_f32 v[62:63], v[62:63], v[68:69]
	v_pk_add_f32 v[60:61], v[60:61], v[66:67]
	global_store_dwordx4 v[72:73], v[60:63], off
	v_cvt_pk_bf16_f32 v66, v60, v61
	v_cvt_pk_bf16_f32 v67, v62, v63
	global_store_dwordx2 v[70:71], v[66:67], off
	v_mul_f32_e32 v61, v61, v61
	v_mul_f32_e32 v63, v63, v63
	v_fmac_f32_e32 v61, v60, v60
	v_fmac_f32_e32 v63, v62, v62
	v_add_f32_e32 v60, v61, v63
	s_waitcnt vmcnt(48)
	v_mov_b32_e32 v66, v170
	v_mov_b32_e32 v67, v171
	v_mov_b32_e32 v68, v172
	v_mov_b32_e32 v69, v173
	v_pk_add_f32 v[58:59], v[58:59], v[68:69]
	v_pk_add_f32 v[56:57], v[56:57], v[66:67]
	global_store_dwordx4 v[72:73], v[56:59], off offset:64
	v_cvt_pk_bf16_f32 v66, v56, v57
	v_cvt_pk_bf16_f32 v67, v58, v59
	global_store_dwordx2 v[70:71], v[66:67], off offset:32
	v_mul_f32_e32 v57, v57, v57
	v_mul_f32_e32 v59, v59, v59
	v_fmac_f32_e32 v57, v56, v56
	v_fmac_f32_e32 v59, v58, v58
	v_add_f32_e32 v56, v57, v59
	v_add_f32_e32 v56, v60, v56
	s_waitcnt vmcnt(47)
	v_mov_b32_e32 v66, v174
	v_mov_b32_e32 v67, v175
	v_mov_b32_e32 v68, v176
	v_mov_b32_e32 v69, v177
	v_pk_add_f32 v[54:55], v[54:55], v[68:69]
	v_pk_add_f32 v[52:53], v[52:53], v[66:67]
	global_store_dwordx4 v[72:73], v[52:55], off offset:512
	v_cvt_pk_bf16_f32 v66, v52, v53
	v_cvt_pk_bf16_f32 v67, v54, v55
	global_store_dwordx2 v[70:71], v[66:67], off offset:256
	v_mul_f32_e32 v53, v53, v53
	v_mul_f32_e32 v55, v55, v55
	v_fmac_f32_e32 v53, v52, v52
	v_fmac_f32_e32 v55, v54, v54
	v_add_f32_e32 v52, v53, v55
	v_add_f32_e32 v54, v56, v52
	s_waitcnt vmcnt(46)
	v_mov_b32_e32 v66, v178
	v_mov_b32_e32 v67, v179
	v_mov_b32_e32 v68, v180
	v_mov_b32_e32 v69, v181
	v_pk_add_f32 v[52:53], v[50:51], v[68:69]
	v_pk_add_f32 v[50:51], v[48:49], v[66:67]
	v_mul_f32_e32 v49, v53, v53
	v_mul_f32_e32 v48, v51, v51
	v_fmac_f32_e32 v48, v50, v50
	v_fmac_f32_e32 v49, v52, v52
	v_add_f32_e32 v48, v48, v49
	v_add_f32_e32 v48, v54, v48
	ds_bpermute_b32 v49, v116, v48
	global_store_dwordx4 v[72:73], v[50:53], off offset:576
	s_waitcnt lgkmcnt(0)
	v_add_f32_e32 v48, v48, v49
	ds_bpermute_b32 v49, v114, v48
	v_cvt_pk_bf16_f32 v50, v50, v51
	v_cvt_pk_bf16_f32 v51, v52, v53
	global_store_dwordx2 v[70:71], v[50:51], off offset:288
	s_and_saveexec_b64 s[58:59], s[12:13]
	s_cbranch_execz .LBB0_1047
	s_waitcnt lgkmcnt(0)
	v_add_f32_e32 v50, v48, v49
	v_lshlrev_b64 v[48:49], 6, v[64:65]
	v_lshl_add_u64 v[48:49], s[28:29], 0, v[48:49]
	v_lshl_add_u64 v[48:49], s[56:57], 2, v[48:49]
	s_lshl_b32 s30, s84, 2
	v_lshl_add_u64 v[48:49], v[48:49], 0, s[30:31]
	global_store_dword v[48:49], v50, off
; __device__ __forceinline__ unsigned pk2(float lo, float hi) { unsigned r; asm volatile("v_cvt_pk_bf16_f32 %0, %1, %2" : "=v"(r) : "v"(lo), "v"(hi)); return r; }
;     __device__ __forceinline__ void operator()(const f32x4 (&acc)[2][2][4][2], const Unit& u, int wr, int wc, int fr, int fq) const {
;     ...
;             for (int m = 0; m < 4; ++m) {
;                 const int row = row0 + ai * 128 + m * 16; const size_t ro = (size_t)row * DM + col0;
;                 float s = 0.f;
; #pragma unroll
;                 for (int bj = 0; bj < 2; ++bj)
; #pragma unroll
;                     for (int n = 0; n < 2; ++n) {
;                         const size_t o = ro + bj * 128 + n * 16;
;                         const f32x4 xn = *(const f32x4*)(xo + o) + acc[ai][bj][m][n];
;                         *(f32x4*)(xf + o) = xn;
;                         u32x2 w; w.x = pk2(xn[0], xn[1]); w.y = pk2(xn[2], xn[3]); *(u32x2*)(xb + o) = w;
;                         s += (xn[0] * xn[0] + xn[1] * xn[1]) + (xn[2] * xn[2] + xn[3] * xn[3]);
;                     }
;                 s += __shfl_xor(s, 16); s += __shfl_xor(s, 32);
;                 if (fq == 0) ssq[(size_t)row * 16 + u.pn * 4 + wc] = s;
.LBB0_1047:
	s_or_b64 exec, exec, s[58:59]
	v_add_u32_e32 v48, 0x90, v138
	s_waitcnt lgkmcnt(0)
	v_ashrrev_i32_e32 v49, 31, v48
	v_lshlrev_b64 v[50:51], 10, v[48:49]
	v_lshl_add_u64 v[54:55], v[50:51], 0, v[136:137]
	v_lshlrev_b64 v[56:57], 2, v[54:55]
	v_lshl_add_u64 v[58:59], s[16:17], 0, v[56:57]
	v_lshl_add_u64 v[54:55], v[54:55], 1, s[26:27]
	v_lshl_add_u64 v[56:57], s[20:21], 0, v[56:57]
	s_waitcnt vmcnt(45)
	v_mov_b32_e32 v50, v182
	v_mov_b32_e32 v51, v183
	v_mov_b32_e32 v52, v184
	v_mov_b32_e32 v53, v185
	v_pk_add_f32 v[46:47], v[46:47], v[52:53]
	v_pk_add_f32 v[44:45], v[44:45], v[50:51]
	global_store_dwordx4 v[56:57], v[44:47], off
	v_cvt_pk_bf16_f32 v50, v44, v45
	v_cvt_pk_bf16_f32 v51, v46, v47
	global_store_dwordx2 v[54:55], v[50:51], off
	v_mul_f32_e32 v45, v45, v45
	v_mul_f32_e32 v47, v47, v47
	v_fmac_f32_e32 v45, v44, v44
	v_fmac_f32_e32 v47, v46, v46
	v_add_f32_e32 v44, v45, v47
	s_waitcnt vmcnt(44)
	v_mov_b32_e32 v50, v186
	v_mov_b32_e32 v51, v187
	v_mov_b32_e32 v52, v188
	v_mov_b32_e32 v53, v189
	v_pk_add_f32 v[42:43], v[42:43], v[52:53]
	v_pk_add_f32 v[40:41], v[40:41], v[50:51]
	global_store_dwordx4 v[56:57], v[40:43], off offset:64
	v_cvt_pk_bf16_f32 v50, v40, v41
	v_cvt_pk_bf16_f32 v51, v42, v43
	global_store_dwordx2 v[54:55], v[50:51], off offset:32
	v_mul_f32_e32 v41, v41, v41
	v_mul_f32_e32 v43, v43, v43
	v_fmac_f32_e32 v41, v40, v40
	v_fmac_f32_e32 v43, v42, v42
	v_add_f32_e32 v40, v41, v43
	v_add_f32_e32 v40, v44, v40
	s_waitcnt vmcnt(43)
	v_mov_b32_e32 v50, v190
	v_mov_b32_e32 v51, v191
	v_mov_b32_e32 v52, v192
	v_mov_b32_e32 v53, v193
	v_pk_add_f32 v[38:39], v[38:39], v[52:53]
	v_pk_add_f32 v[36:37], v[36:37], v[50:51]
	global_store_dwordx4 v[56:57], v[36:39], off offset:512
	v_cvt_pk_bf16_f32 v50, v36, v37
	v_cvt_pk_bf16_f32 v51, v38, v39
	global_store_dwordx2 v[54:55], v[50:51], off offset:256
	v_mul_f32_e32 v37, v37, v37
	v_mul_f32_e32 v39, v39, v39
	v_fmac_f32_e32 v37, v36, v36
	v_fmac_f32_e32 v39, v38, v38
	v_add_f32_e32 v36, v37, v39
	v_add_f32_e32 v38, v40, v36
	s_waitcnt vmcnt(42)
	v_mov_b32_e32 v50, v194
	v_mov_b32_e32 v51, v195
	v_mov_b32_e32 v52, v196
	v_mov_b32_e32 v53, v197
	v_pk_add_f32 v[36:37], v[34:35], v[52:53]
	v_pk_add_f32 v[34:35], v[32:33], v[50:51]
	v_mul_f32_e32 v33, v37, v37
	v_mul_f32_e32 v32, v35, v35
	v_fmac_f32_e32 v32, v34, v34
	v_fmac_f32_e32 v33, v36, v36
	v_add_f32_e32 v32, v32, v33
	v_add_f32_e32 v32, v38, v32
	ds_bpermute_b32 v33, v116, v32
	global_store_dwordx4 v[56:57], v[34:37], off offset:576
	s_waitcnt lgkmcnt(0)
	v_add_f32_e32 v32, v32, v33
	ds_bpermute_b32 v33, v114, v32
	v_cvt_pk_bf16_f32 v34, v34, v35
	v_cvt_pk_bf16_f32 v35, v36, v37
	global_store_dwordx2 v[54:55], v[34:35], off offset:288
	s_and_saveexec_b64 s[58:59], s[12:13]
	s_cbranch_execz .LBB0_1049
	s_waitcnt lgkmcnt(0)
	v_add_f32_e32 v34, v32, v33
	v_lshlrev_b64 v[32:33], 6, v[48:49]
	v_lshl_add_u64 v[32:33], s[28:29], 0, v[32:33]
	v_lshl_add_u64 v[32:33], s[56:57], 2, v[32:33]
	s_lshl_b32 s30, s84, 2
	v_lshl_add_u64 v[32:33], v[32:33], 0, s[30:31]
	global_store_dword v[32:33], v34, off
; __device__ __forceinline__ unsigned pk2(float lo, float hi) { unsigned r; asm volatile("v_cvt_pk_bf16_f32 %0, %1, %2" : "=v"(r) : "v"(lo), "v"(hi)); return r; }
;     __device__ __forceinline__ void operator()(const f32x4 (&acc)[2][2][4][2], const Unit& u, int wr, int wc, int fr, int fq) const {
;     ...
;             for (int m = 0; m < 4; ++m) {
;                 const int row = row0 + ai * 128 + m * 16; const size_t ro = (size_t)row * DM + col0;
;                 float s = 0.f;
; #pragma unroll
;                 for (int bj = 0; bj < 2; ++bj)
; #pragma unroll
;                     for (int n = 0; n < 2; ++n) {
;                         const size_t o = ro + bj * 128 + n * 16;
;                         const f32x4 xn = *(const f32x4*)(xo + o) + acc[ai][bj][m][n];
;                         *(f32x4*)(xf + o) = xn;
;                         u32x2 w; w.x = pk2(xn[0], xn[1]); w.y = pk2(xn[2], xn[3]); *(u32x2*)(xb + o) = w;
;                         s += (xn[0] * xn[0] + xn[1] * xn[1]) + (xn[2] * xn[2] + xn[3] * xn[3]);
;                     }
;                 s += __shfl_xor(s, 16); s += __shfl_xor(s, 32);
;                 if (fq == 0) ssq[(size_t)row * 16 + u.pn * 4 + wc] = s;
.LBB0_1049:
	s_or_b64 exec, exec, s[58:59]
	v_add_u32_e32 v32, 0xa0, v138
	s_waitcnt lgkmcnt(0)
	v_ashrrev_i32_e32 v33, 31, v32
	v_lshlrev_b64 v[34:35], 10, v[32:33]
	v_lshl_add_u64 v[38:39], v[34:35], 0, v[136:137]
	v_lshlrev_b64 v[40:41], 2, v[38:39]
	v_lshl_add_u64 v[42:43], s[16:17], 0, v[40:41]
	v_lshl_add_u64 v[38:39], v[38:39], 1, s[26:27]
	v_lshl_add_u64 v[40:41], s[20:21], 0, v[40:41]
	s_waitcnt vmcnt(41)
	v_mov_b32_e32 v34, v198
	v_mov_b32_e32 v35, v199
	v_mov_b32_e32 v36, v200
	v_mov_b32_e32 v37, v201
	v_pk_add_f32 v[30:31], v[30:31], v[36:37]
	v_pk_add_f32 v[28:29], v[28:29], v[34:35]
	global_store_dwordx4 v[40:41], v[28:31], off
	v_cvt_pk_bf16_f32 v34, v28, v29
	v_cvt_pk_bf16_f32 v35, v30, v31
	global_store_dwordx2 v[38:39], v[34:35], off
	v_mul_f32_e32 v29, v29, v29
	v_mul_f32_e32 v31, v31, v31
	v_fmac_f32_e32 v29, v28, v28
	v_fmac_f32_e32 v31, v30, v30
	v_add_f32_e32 v28, v29, v31
	s_waitcnt vmcnt(40)
	v_mov_b32_e32 v34, v202
	v_mov_b32_e32 v35, v203
	v_mov_b32_e32 v36, v204
	v_mov_b32_e32 v37, v205
	v_pk_add_f32 v[26:27], v[26:27], v[36:37]
	v_pk_add_f32 v[24:25], v[24:25], v[34:35]
	global_store_dwordx4 v[40:41], v[24:27], off offset:64
	v_cvt_pk_bf16_f32 v34, v24, v25
	v_cvt_pk_bf16_f32 v35, v26, v27
	global_store_dwordx2 v[38:39], v[34:35], off offset:32
	v_mul_f32_e32 v25, v25, v25
	v_mul_f32_e32 v27, v27, v27
	v_fmac_f32_e32 v25, v24, v24
	v_fmac_f32_e32 v27, v26, v26
	v_add_f32_e32 v24, v25, v27
	v_add_f32_e32 v24, v28, v24
	s_waitcnt vmcnt(39)
	v_mov_b32_e32 v34, v206
	v_mov_b32_e32 v35, v207
	v_mov_b32_e32 v36, v208
	v_mov_b32_e32 v37, v209
	v_pk_add_f32 v[22:23], v[22:23], v[36:37]
	v_pk_add_f32 v[20:21], v[20:21], v[34:35]
	global_store_dwordx4 v[40:41], v[20:23], off offset:512
	v_cvt_pk_bf16_f32 v34, v20, v21
	v_cvt_pk_bf16_f32 v35, v22, v23
	global_store_dwordx2 v[38:39], v[34:35], off offset:256
	v_mul_f32_e32 v21, v21, v21
	v_mul_f32_e32 v23, v23, v23
	v_fmac_f32_e32 v21, v20, v20
	v_fmac_f32_e32 v23, v22, v22
	v_add_f32_e32 v20, v21, v23
	v_add_f32_e32 v22, v24, v20
	s_waitcnt vmcnt(38)
	v_mov_b32_e32 v34, v210
	v_mov_b32_e32 v35, v211
	v_mov_b32_e32 v36, v212
	v_mov_b32_e32 v37, v213
	v_pk_add_f32 v[20:21], v[18:19], v[36:37]
	v_pk_add_f32 v[18:19], v[16:17], v[34:35]
	v_mul_f32_e32 v17, v21, v21
	v_mul_f32_e32 v16, v19, v19
	v_fmac_f32_e32 v16, v18, v18
	v_fmac_f32_e32 v17, v20, v20
	v_add_f32_e32 v16, v16, v17
	v_add_f32_e32 v16, v22, v16
	ds_bpermute_b32 v17, v116, v16
	global_store_dwordx4 v[40:41], v[18:21], off offset:576
	s_waitcnt lgkmcnt(0)
	v_add_f32_e32 v16, v16, v17
	ds_bpermute_b32 v17, v114, v16
	v_cvt_pk_bf16_f32 v18, v18, v19
	v_cvt_pk_bf16_f32 v19, v20, v21
	global_store_dwordx2 v[38:39], v[18:19], off offset:288
	s_and_saveexec_b64 s[58:59], s[12:13]
	s_cbranch_execz .LBB0_1051
	s_waitcnt lgkmcnt(0)
	v_add_f32_e32 v18, v16, v17
	v_lshlrev_b64 v[16:17], 6, v[32:33]
	v_lshl_add_u64 v[16:17], s[28:29], 0, v[16:17]
	v_lshl_add_u64 v[16:17], s[56:57], 2, v[16:17]
	s_lshl_b32 s30, s84, 2
	v_lshl_add_u64 v[16:17], v[16:17], 0, s[30:31]
	global_store_dword v[16:17], v18, off
.LBB0_1051:
	s_or_b64 exec, exec, s[58:59]
	v_add_u32_e32 v16, 0xb0, v138
	s_waitcnt lgkmcnt(0)
	v_ashrrev_i32_e32 v17, 31, v16
	v_lshlrev_b64 v[18:19], 10, v[16:17]
	v_lshl_add_u64 v[22:23], v[18:19], 0, v[136:137]
	v_lshlrev_b64 v[24:25], 2, v[22:23]
	v_lshl_add_u64 v[26:27], s[16:17], 0, v[24:25]
	v_lshl_add_u64 v[22:23], v[22:23], 1, s[26:27]
	v_lshl_add_u64 v[24:25], s[20:21], 0, v[24:25]
	s_waitcnt vmcnt(37)
	v_mov_b32_e32 v18, v232
	v_mov_b32_e32 v19, v233
	v_mov_b32_e32 v20, v234
	v_mov_b32_e32 v21, v235
	v_pk_add_f32 v[14:15], v[14:15], v[20:21]
	v_pk_add_f32 v[12:13], v[12:13], v[18:19]
	global_store_dwordx4 v[24:25], v[12:15], off
	v_cvt_pk_bf16_f32 v18, v12, v13
	v_cvt_pk_bf16_f32 v19, v14, v15
	global_store_dwordx2 v[22:23], v[18:19], off
	v_mul_f32_e32 v13, v13, v13
	v_mul_f32_e32 v15, v15, v15
	v_fmac_f32_e32 v13, v12, v12
	v_fmac_f32_e32 v15, v14, v14
	v_add_f32_e32 v12, v13, v15
	s_waitcnt vmcnt(36)
	v_mov_b32_e32 v18, v236
	v_mov_b32_e32 v19, v237
	v_mov_b32_e32 v20, v238
	v_mov_b32_e32 v21, v239
	v_pk_add_f32 v[10:11], v[10:11], v[20:21]
	v_pk_add_f32 v[8:9], v[8:9], v[18:19]
	global_store_dwordx4 v[24:25], v[8:11], off offset:64
	v_cvt_pk_bf16_f32 v18, v8, v9
	v_cvt_pk_bf16_f32 v19, v10, v11
	global_store_dwordx2 v[22:23], v[18:19], off offset:32
	v_mul_f32_e32 v9, v9, v9
	v_mul_f32_e32 v11, v11, v11
	v_fmac_f32_e32 v9, v8, v8
	v_fmac_f32_e32 v11, v10, v10
	v_add_f32_e32 v8, v9, v11
	v_add_f32_e32 v8, v12, v8
	s_waitcnt vmcnt(35)
	v_mov_b32_e32 v18, v240
	v_mov_b32_e32 v19, v241
	v_mov_b32_e32 v20, v242
	v_mov_b32_e32 v21, v243
	v_pk_add_f32 v[6:7], v[6:7], v[20:21]
	v_pk_add_f32 v[4:5], v[4:5], v[18:19]
	global_store_dwordx4 v[24:25], v[4:7], off offset:512
	v_cvt_pk_bf16_f32 v18, v4, v5
	v_cvt_pk_bf16_f32 v19, v6, v7
	global_store_dwordx2 v[22:23], v[18:19], off offset:256
	v_mul_f32_e32 v5, v5, v5
	v_mul_f32_e32 v7, v7, v7
	v_fmac_f32_e32 v5, v4, v4
	v_fmac_f32_e32 v7, v6, v6
	v_add_f32_e32 v4, v5, v7
	v_add_f32_e32 v6, v8, v4
	s_waitcnt vmcnt(34)
	v_mov_b32_e32 v18, v244
	v_mov_b32_e32 v19, v245
	v_mov_b32_e32 v20, v246
	v_mov_b32_e32 v21, v247
	v_pk_add_f32 v[4:5], v[2:3], v[20:21]
	v_pk_add_f32 v[2:3], v[0:1], v[18:19]
	v_mul_f32_e32 v1, v5, v5
	v_mul_f32_e32 v0, v3, v3
	v_fmac_f32_e32 v0, v2, v2
	v_fmac_f32_e32 v1, v4, v4
	v_add_f32_e32 v0, v0, v1
	v_add_f32_e32 v0, v6, v0
	ds_bpermute_b32 v1, v116, v0
	global_store_dwordx4 v[24:25], v[2:5], off offset:576
	s_waitcnt lgkmcnt(0)
	v_add_f32_e32 v0, v0, v1
	ds_bpermute_b32 v1, v114, v0
	v_cvt_pk_bf16_f32 v2, v2, v3
	v_cvt_pk_bf16_f32 v3, v4, v5
	global_store_dwordx2 v[22:23], v[2:3], off offset:288
	s_and_saveexec_b64 s[16:17], s[12:13]
	s_cbranch_execz .LBB0_1012
	s_waitcnt lgkmcnt(0)
	v_add_f32_e32 v2, v0, v1
	v_lshlrev_b64 v[0:1], 6, v[16:17]
	v_lshl_add_u64 v[0:1], s[28:29], 0, v[0:1]
	v_lshl_add_u64 v[0:1], s[56:57], 2, v[0:1]
	s_lshl_b32 s30, s84, 2
	v_lshl_add_u64 v[0:1], v[0:1], 0, s[30:31]
	global_store_dword v[0:1], v2, off
	s_branch .LBB0_1012

; __device__ __forceinline__ unsigned pk2(float lo, float hi) { unsigned r; asm volatile("v_cvt_pk_bf16_f32 %0, %1, %2" : "=v"(r) : "v"(lo), "v"(hi)); return r; }
;     __device__ __forceinline__ void operator()(const f32x4 (&acc)[2][2][4][2], const Unit& u, int wr, int wc, int fr, int fq) const {
;         const int row0 = u.pm * 256 + wr * 64 + fr, col0 = u.pn * 256 + wc * 32 + 4 * fq;
;         const float* xo = (u.pm < 64) ? xoldA : (xoldB - (size_t)T_P * DM);
; #pragma unroll
;         for (int ai = 0; ai < 2; ++ai)
; #pragma unroll
;             for (int m = 0; m < 4; ++m) {
;                 const int row = row0 + ai * 128 + m * 16; const size_t ro = (size_t)row * DM + col0;
;                 float s = 0.f;
; #pragma unroll
;                 for (int bj = 0; bj < 2; ++bj)
; #pragma unroll
;                     for (int n = 0; n < 2; ++n) {
;                         const size_t o = ro + bj * 128 + n * 16;
;                         const f32x4 xn = *(const f32x4*)(xo + o) + acc[ai][bj][m][n];
;                         *(f32x4*)(xf + o) = xn;
;                         u32x2 w; w.x = pk2(xn[0], xn[1]); w.y = pk2(xn[2], xn[3]); *(u32x2*)(xb + o) = w;
;                         s += (xn[0] * xn[0] + xn[1] * xn[1]) + (xn[2] * xn[2] + xn[3] * xn[3]);
;                     }
;                 s += __shfl_xor(s, 16); s += __shfl_xor(s, 32);
;                 if (fq == 0) ssq[(size_t)row * 16 + u.pn * 4 + wc] = s;
.LBB0_1922:
	v_lshl_add_u32 v146, s77, 8, v148
	v_lshl_or_b32 v142, s40, 8, v150
	v_ashrrev_i32_e32 v147, 31, v146
	v_ashrrev_i32_e32 v143, 31, v142
	v_lshlrev_b64 v[154:155], 10, v[146:147]
	s_cmp_lt_i32 s77, 64
	v_lshl_add_u64 v[158:159], v[154:155], 0, v[142:143]
	s_cselect_b32 s15, s25, -1
	s_cselect_b32 s14, s24, 0xfc000000
	v_lshlrev_b64 v[160:161], 2, v[158:159]
	v_lshl_add_u64 v[162:163], s[14:15], 0, v[160:161]
	v_subrev_u32_e32 v172, s14, v162
	v_add_u32_e32 v173, 0x0, v172
	global_load_dwordx4 v[174:177], v173, s[14:15]
	v_add_u32_e32 v173, 0x40, v172
	global_load_dwordx4 v[178:181], v173, s[14:15]
	v_add_u32_e32 v173, 0x200, v172
	global_load_dwordx4 v[182:185], v173, s[14:15]
	v_add_u32_e32 v173, 0x240, v172
	global_load_dwordx4 v[186:189], v173, s[14:15]
	v_add_u32_e32 v173, 0x10000, v172
	global_load_dwordx4 v[190:193], v173, s[14:15]
	v_add_u32_e32 v173, 0x10040, v172
	global_load_dwordx4 v[194:197], v173, s[14:15]
	v_add_u32_e32 v173, 0x10200, v172
	global_load_dwordx4 v[198:201], v173, s[14:15]
	v_add_u32_e32 v173, 0x10240, v172
	global_load_dwordx4 v[202:205], v173, s[14:15]
	v_add_u32_e32 v173, 0x20000, v172
	global_load_dwordx4 v[206:209], v173, s[14:15]
	v_add_u32_e32 v173, 0x20040, v172
	global_load_dwordx4 v[210:213], v173, s[14:15]
	v_add_u32_e32 v173, 0x20200, v172
	global_load_dwordx4 v[214:217], v173, s[14:15]
	v_add_u32_e32 v173, 0x20240, v172
	global_load_dwordx4 v[218:221], v173, s[14:15]
	v_add_u32_e32 v173, 0x30000, v172
	global_load_dwordx4 v[232:235], v173, s[14:15]
	v_add_u32_e32 v173, 0x30040, v172
	global_load_dwordx4 v[236:239], v173, s[14:15]
	v_add_u32_e32 v173, 0x30200, v172
	global_load_dwordx4 v[240:243], v173, s[14:15]
	v_add_u32_e32 v173, 0x30240, v172
	global_load_dwordx4 v[244:247], v173, s[14:15]
	v_add_u32_e32 v173, 0x80000, v172
	global_load_dwordx4 v[248:251], v173, s[14:15]
	v_add_u32_e32 v173, 0x80040, v172
	global_load_dwordx4 v[252:255], v173, s[14:15]
	v_lshl_add_u64 v[164:165], v[158:159], 1, s[20:21]
	v_lshl_add_u64 v[170:171], s[24:25], 0, v[160:161]
	v_xor_b32_e32 v153, 32, v152
	s_lshl_b32 s40, s40, 2
	s_ashr_i32 s41, s40, 31
	s_waitcnt vmcnt(17)
	v_mov_b32_e32 v154, v174
	v_mov_b32_e32 v155, v175
	v_mov_b32_e32 v156, v176
	v_mov_b32_e32 v157, v177
	v_add_u32_e32 v173, 0x80200, v172
	global_load_dwordx4 v[174:177], v173, s[14:15]
	v_pk_add_f32 v[126:127], v[126:127], v[156:157]
	v_pk_add_f32 v[124:125], v[124:125], v[154:155]
	global_store_dwordx4 v[170:171], v[124:127], off
	v_cvt_pk_bf16_f32 v154, v124, v125
	v_cvt_pk_bf16_f32 v155, v126, v127
	global_store_dwordx2 v[164:165], v[154:155], off
	s_waitcnt vmcnt(19)
	v_mov_b32_e32 v154, v178
	v_mov_b32_e32 v155, v179
	v_mov_b32_e32 v156, v180
	v_mov_b32_e32 v157, v181
	v_add_u32_e32 v173, 0x80240, v172
	global_load_dwordx4 v[178:181], v173, s[14:15]
	v_pk_add_f32 v[122:123], v[122:123], v[156:157]
	v_pk_add_f32 v[120:121], v[120:121], v[154:155]
	global_store_dwordx4 v[170:171], v[120:123], off offset:64
	v_cvt_pk_bf16_f32 v154, v120, v121
	v_cvt_pk_bf16_f32 v155, v122, v123
	global_store_dwordx2 v[164:165], v[154:155], off offset:32
	s_waitcnt vmcnt(21)
	v_mov_b32_e32 v154, v182
	v_mov_b32_e32 v155, v183
	v_mov_b32_e32 v156, v184
	v_mov_b32_e32 v157, v185
	v_add_u32_e32 v173, 0x90000, v172
	global_load_dwordx4 v[182:185], v173, s[14:15]
	v_pk_add_f32 v[156:157], v[118:119], v[156:157]
	v_pk_add_f32 v[154:155], v[116:117], v[154:155]
	global_store_dwordx4 v[170:171], v[154:157], off offset:512
	v_cvt_pk_bf16_f32 v116, v154, v155
	v_cvt_pk_bf16_f32 v117, v156, v157
	global_store_dwordx2 v[164:165], v[116:117], off offset:256
	v_mul_f32_e32 v118, v125, v125
	v_mul_f32_e32 v119, v127, v127
	v_fmac_f32_e32 v118, v124, v124
	v_fmac_f32_e32 v119, v126, v126
	v_add_f32_e32 v118, v118, v119
	v_mul_f32_e32 v119, v121, v121
	v_mul_f32_e32 v121, v123, v123
	v_fmac_f32_e32 v119, v120, v120
	v_fmac_f32_e32 v121, v122, v122
	v_add_f32_e32 v119, v119, v121
	v_add_f32_e32 v118, v118, v119
	v_mul_f32_e32 v119, v155, v155
	v_mul_f32_e32 v120, v157, v157
	v_fmac_f32_e32 v119, v154, v154
	v_fmac_f32_e32 v120, v156, v156
	v_add_f32_e32 v119, v119, v120
	v_and_b32_e32 v117, 64, v152
	v_add_f32_e32 v122, v118, v119
	v_xor_b32_e32 v116, 16, v152
	v_add_u32_e32 v117, 64, v117
	v_cmp_lt_i32_e32 vcc, v116, v117
	s_waitcnt vmcnt(23)
	v_mov_b32_e32 v158, v186
	v_mov_b32_e32 v159, v187
	v_mov_b32_e32 v160, v188
	v_mov_b32_e32 v161, v189
	v_add_u32_e32 v173, 0x90040, v172
	global_load_dwordx4 v[186:189], v173, s[14:15]
	v_pk_add_f32 v[120:121], v[114:115], v[160:161]
	v_pk_add_f32 v[118:119], v[112:113], v[158:159]
	v_mul_f32_e32 v113, v121, v121
	v_mul_f32_e32 v112, v119, v119
	v_fmac_f32_e32 v112, v118, v118
	v_fmac_f32_e32 v113, v120, v120
	v_cndmask_b32_e32 v116, v152, v116, vcc
	v_add_f32_e32 v112, v112, v113
	v_lshlrev_b32_e32 v116, 2, v116
	v_add_f32_e32 v112, v122, v112
	ds_bpermute_b32 v113, v116, v112
	v_cmp_lt_i32_e32 vcc, v153, v117
	global_store_dwordx4 v[170:171], v[118:121], off offset:576
	s_waitcnt lgkmcnt(0)
	v_add_f32_e32 v112, v112, v113
	v_cndmask_b32_e32 v114, v152, v153, vcc
	v_lshlrev_b32_e32 v114, 2, v114
	ds_bpermute_b32 v113, v114, v112
	v_cvt_pk_bf16_f32 v118, v118, v119
	v_cvt_pk_bf16_f32 v119, v120, v121
	global_store_dwordx2 v[164:165], v[118:119], off offset:288
	s_and_saveexec_b64 s[42:43], s[10:11]
	s_cbranch_execz .LBB0_1924
	s_waitcnt lgkmcnt(0)
	v_add_f32_e32 v115, v112, v113
	v_lshlrev_b64 v[112:113], 6, v[146:147]
	v_lshl_add_u64 v[112:113], s[22:23], 0, v[112:113]
	v_lshl_add_u64 v[112:113], s[40:41], 2, v[112:113]
	s_lshl_b32 s30, s67, 2
	v_lshl_add_u64 v[112:113], v[112:113], 0, s[30:31]
	global_store_dword v[112:113], v115, off
; __device__ __forceinline__ unsigned pk2(float lo, float hi) { unsigned r; asm volatile("v_cvt_pk_bf16_f32 %0, %1, %2" : "=v"(r) : "v"(lo), "v"(hi)); return r; }
;     __device__ __forceinline__ void operator()(const f32x4 (&acc)[2][2][4][2], const Unit& u, int wr, int wc, int fr, int fq) const {
;     ...
;             for (int m = 0; m < 4; ++m) {
;                 const int row = row0 + ai * 128 + m * 16; const size_t ro = (size_t)row * DM + col0;
;                 float s = 0.f;
; #pragma unroll
;                 for (int bj = 0; bj < 2; ++bj)
; #pragma unroll
;                     for (int n = 0; n < 2; ++n) {
;                         const size_t o = ro + bj * 128 + n * 16;
;                         const f32x4 xn = *(const f32x4*)(xo + o) + acc[ai][bj][m][n];
;                         *(f32x4*)(xf + o) = xn;
;                         u32x2 w; w.x = pk2(xn[0], xn[1]); w.y = pk2(xn[2], xn[3]); *(u32x2*)(xb + o) = w;
;                         s += (xn[0] * xn[0] + xn[1] * xn[1]) + (xn[2] * xn[2] + xn[3] * xn[3]);
;                     }
;                 s += __shfl_xor(s, 16); s += __shfl_xor(s, 32);
;                 if (fq == 0) ssq[(size_t)row * 16 + u.pn * 4 + wc] = s;
.LBB0_1924:
	s_or_b64 exec, exec, s[42:43]
	v_or_b32_e32 v112, 16, v146
	s_waitcnt lgkmcnt(0)
	v_ashrrev_i32_e32 v113, 31, v112
	v_lshlrev_b64 v[118:119], 10, v[112:113]
	v_lshl_add_u64 v[122:123], v[118:119], 0, v[142:143]
	v_lshlrev_b64 v[124:125], 2, v[122:123]
	v_lshl_add_u64 v[126:127], s[14:15], 0, v[124:125]
	v_lshl_add_u64 v[122:123], v[122:123], 1, s[20:21]
	v_lshl_add_u64 v[124:125], s[24:25], 0, v[124:125]
	s_waitcnt vmcnt(25)
	v_mov_b32_e32 v118, v190
	v_mov_b32_e32 v119, v191
	v_mov_b32_e32 v120, v192
	v_mov_b32_e32 v121, v193
	v_add_u32_e32 v173, 0x90200, v172
	global_load_dwordx4 v[190:193], v173, s[14:15]
	v_pk_add_f32 v[110:111], v[110:111], v[120:121]
	v_pk_add_f32 v[108:109], v[108:109], v[118:119]
	global_store_dwordx4 v[124:125], v[108:111], off
	v_cvt_pk_bf16_f32 v118, v108, v109
	v_cvt_pk_bf16_f32 v119, v110, v111
	global_store_dwordx2 v[122:123], v[118:119], off
	v_mul_f32_e32 v109, v109, v109
	v_mul_f32_e32 v111, v111, v111
	v_fmac_f32_e32 v109, v108, v108
	v_fmac_f32_e32 v111, v110, v110
	v_add_f32_e32 v108, v109, v111
	s_waitcnt vmcnt(27)
	v_mov_b32_e32 v118, v194
	v_mov_b32_e32 v119, v195
	v_mov_b32_e32 v120, v196
	v_mov_b32_e32 v121, v197
	v_add_u32_e32 v173, 0x90240, v172
	global_load_dwordx4 v[194:197], v173, s[14:15]
	v_pk_add_f32 v[106:107], v[106:107], v[120:121]
	v_pk_add_f32 v[104:105], v[104:105], v[118:119]
	global_store_dwordx4 v[124:125], v[104:107], off offset:64
	v_cvt_pk_bf16_f32 v118, v104, v105
	v_cvt_pk_bf16_f32 v119, v106, v107
	global_store_dwordx2 v[122:123], v[118:119], off offset:32
	v_mul_f32_e32 v105, v105, v105
	v_mul_f32_e32 v107, v107, v107
	v_fmac_f32_e32 v105, v104, v104
	v_fmac_f32_e32 v107, v106, v106
	v_add_f32_e32 v104, v105, v107
	v_add_f32_e32 v104, v108, v104
	s_waitcnt vmcnt(29)
	v_mov_b32_e32 v118, v198
	v_mov_b32_e32 v119, v199
	v_mov_b32_e32 v120, v200
	v_mov_b32_e32 v121, v201
	v_add_u32_e32 v173, 0xa0000, v172
	global_load_dwordx4 v[198:201], v173, s[14:15]
	v_pk_add_f32 v[102:103], v[102:103], v[120:121]
	v_pk_add_f32 v[100:101], v[100:101], v[118:119]
	global_store_dwordx4 v[124:125], v[100:103], off offset:512
	v_cvt_pk_bf16_f32 v118, v100, v101
	v_cvt_pk_bf16_f32 v119, v102, v103
	global_store_dwordx2 v[122:123], v[118:119], off offset:256
	v_mul_f32_e32 v101, v101, v101
	v_mul_f32_e32 v103, v103, v103
	v_fmac_f32_e32 v101, v100, v100
	v_fmac_f32_e32 v103, v102, v102
	v_add_f32_e32 v100, v101, v103
	v_add_f32_e32 v102, v104, v100
	s_waitcnt vmcnt(31)
	v_mov_b32_e32 v118, v202
	v_mov_b32_e32 v119, v203
	v_mov_b32_e32 v120, v204
	v_mov_b32_e32 v121, v205
	v_add_u32_e32 v173, 0xa0040, v172
	global_load_dwordx4 v[202:205], v173, s[14:15]
	v_pk_add_f32 v[100:101], v[98:99], v[120:121]
	v_pk_add_f32 v[98:99], v[96:97], v[118:119]
	v_mul_f32_e32 v97, v101, v101
	v_mul_f32_e32 v96, v99, v99
	v_fmac_f32_e32 v96, v98, v98
	v_fmac_f32_e32 v97, v100, v100
	v_add_f32_e32 v96, v96, v97
	v_add_f32_e32 v96, v102, v96
	ds_bpermute_b32 v97, v116, v96
	global_store_dwordx4 v[124:125], v[98:101], off offset:576
	s_waitcnt lgkmcnt(0)
	v_add_f32_e32 v96, v96, v97
	ds_bpermute_b32 v97, v114, v96
	v_cvt_pk_bf16_f32 v98, v98, v99
	v_cvt_pk_bf16_f32 v99, v100, v101
	global_store_dwordx2 v[122:123], v[98:99], off offset:288
	s_and_saveexec_b64 s[42:43], s[10:11]
	s_cbranch_execz .LBB0_1926
	s_waitcnt lgkmcnt(0)
	v_add_f32_e32 v98, v96, v97
	v_lshlrev_b64 v[96:97], 6, v[112:113]
	v_lshl_add_u64 v[96:97], s[22:23], 0, v[96:97]
	v_lshl_add_u64 v[96:97], s[40:41], 2, v[96:97]
	s_lshl_b32 s30, s67, 2
	v_lshl_add_u64 v[96:97], v[96:97], 0, s[30:31]
	global_store_dword v[96:97], v98, off
.LBB0_1926:
	s_or_b64 exec, exec, s[42:43]
	v_or_b32_e32 v96, 32, v146
	s_waitcnt lgkmcnt(0)
	v_ashrrev_i32_e32 v97, 31, v96
	v_lshlrev_b64 v[98:99], 10, v[96:97]
	v_lshl_add_u64 v[102:103], v[98:99], 0, v[142:143]
	v_lshlrev_b64 v[104:105], 2, v[102:103]
	v_lshl_add_u64 v[106:107], s[14:15], 0, v[104:105]
	v_lshl_add_u64 v[102:103], v[102:103], 1, s[20:21]
	v_lshl_add_u64 v[104:105], s[24:25], 0, v[104:105]
	s_waitcnt vmcnt(33)
	v_mov_b32_e32 v98, v206
	v_mov_b32_e32 v99, v207
	v_mov_b32_e32 v100, v208
	v_mov_b32_e32 v101, v209
	v_add_u32_e32 v173, 0xa0200, v172
	global_load_dwordx4 v[206:209], v173, s[14:15]
	v_pk_add_f32 v[94:95], v[94:95], v[100:101]
	v_pk_add_f32 v[92:93], v[92:93], v[98:99]
	global_store_dwordx4 v[104:105], v[92:95], off
	v_cvt_pk_bf16_f32 v98, v92, v93
	v_cvt_pk_bf16_f32 v99, v94, v95
	global_store_dwordx2 v[102:103], v[98:99], off
	v_mul_f32_e32 v93, v93, v93
	v_mul_f32_e32 v95, v95, v95
	v_fmac_f32_e32 v93, v92, v92
	v_fmac_f32_e32 v95, v94, v94
	v_add_f32_e32 v92, v93, v95
	s_waitcnt vmcnt(35)
	v_mov_b32_e32 v98, v210
	v_mov_b32_e32 v99, v211
	v_mov_b32_e32 v100, v212
	v_mov_b32_e32 v101, v213
	v_add_u32_e32 v173, 0xa0240, v172
	global_load_dwordx4 v[210:213], v173, s[14:15]
	v_pk_add_f32 v[90:91], v[90:91], v[100:101]
	v_pk_add_f32 v[88:89], v[88:89], v[98:99]
	global_store_dwordx4 v[104:105], v[88:91], off offset:64
	v_cvt_pk_bf16_f32 v98, v88, v89
	v_cvt_pk_bf16_f32 v99, v90, v91
	global_store_dwordx2 v[102:103], v[98:99], off offset:32
	v_mul_f32_e32 v89, v89, v89
	v_mul_f32_e32 v91, v91, v91
	v_fmac_f32_e32 v89, v88, v88
	v_fmac_f32_e32 v91, v90, v90
	v_add_f32_e32 v88, v89, v91
	v_add_f32_e32 v88, v92, v88
	s_waitcnt vmcnt(37)
	v_mov_b32_e32 v98, v214
	v_mov_b32_e32 v99, v215
	v_mov_b32_e32 v100, v216
	v_mov_b32_e32 v101, v217
	v_add_u32_e32 v173, 0xb0000, v172
	global_load_dwordx4 v[214:217], v173, s[14:15]
	v_pk_add_f32 v[86:87], v[86:87], v[100:101]
	v_pk_add_f32 v[84:85], v[84:85], v[98:99]
	global_store_dwordx4 v[104:105], v[84:87], off offset:512
	v_cvt_pk_bf16_f32 v98, v84, v85
	v_cvt_pk_bf16_f32 v99, v86, v87
	global_store_dwordx2 v[102:103], v[98:99], off offset:256
	v_mul_f32_e32 v85, v85, v85
	v_mul_f32_e32 v87, v87, v87
	v_fmac_f32_e32 v85, v84, v84
	v_fmac_f32_e32 v87, v86, v86
	v_add_f32_e32 v84, v85, v87
	v_add_f32_e32 v86, v88, v84
	s_waitcnt vmcnt(39)
	v_mov_b32_e32 v98, v218
	v_mov_b32_e32 v99, v219
	v_mov_b32_e32 v100, v220
	v_mov_b32_e32 v101, v221
	v_add_u32_e32 v173, 0xb0040, v172
	global_load_dwordx4 v[218:221], v173, s[14:15]
	v_pk_add_f32 v[84:85], v[82:83], v[100:101]
	v_pk_add_f32 v[82:83], v[80:81], v[98:99]
	v_mul_f32_e32 v81, v85, v85
	v_mul_f32_e32 v80, v83, v83
	v_fmac_f32_e32 v80, v82, v82
	v_fmac_f32_e32 v81, v84, v84
	v_add_f32_e32 v80, v80, v81
	v_add_f32_e32 v80, v86, v80
	ds_bpermute_b32 v81, v116, v80
	global_store_dwordx4 v[104:105], v[82:85], off offset:576
	s_waitcnt lgkmcnt(0)
	v_add_f32_e32 v80, v80, v81
	ds_bpermute_b32 v81, v114, v80
	v_cvt_pk_bf16_f32 v82, v82, v83
	v_cvt_pk_bf16_f32 v83, v84, v85
	global_store_dwordx2 v[102:103], v[82:83], off offset:288
	s_and_saveexec_b64 s[42:43], s[10:11]
	s_cbranch_execz .LBB0_1928
	s_waitcnt lgkmcnt(0)
	v_add_f32_e32 v82, v80, v81
	v_lshlrev_b64 v[80:81], 6, v[96:97]
	v_lshl_add_u64 v[80:81], s[22:23], 0, v[80:81]
	v_lshl_add_u64 v[80:81], s[40:41], 2, v[80:81]
	s_lshl_b32 s30, s67, 2
	v_lshl_add_u64 v[80:81], v[80:81], 0, s[30:31]
	global_store_dword v[80:81], v82, off
; __device__ __forceinline__ unsigned pk2(float lo, float hi) { unsigned r; asm volatile("v_cvt_pk_bf16_f32 %0, %1, %2" : "=v"(r) : "v"(lo), "v"(hi)); return r; }
;     __device__ __forceinline__ void operator()(const f32x4 (&acc)[2][2][4][2], const Unit& u, int wr, int wc, int fr, int fq) const {
;     ...
;             for (int m = 0; m < 4; ++m) {
;                 const int row = row0 + ai * 128 + m * 16; const size_t ro = (size_t)row * DM + col0;
;                 float s = 0.f;
; #pragma unroll
;                 for (int bj = 0; bj < 2; ++bj)
; #pragma unroll
;                     for (int n = 0; n < 2; ++n) {
;                         const size_t o = ro + bj * 128 + n * 16;
;                         const f32x4 xn = *(const f32x4*)(xo + o) + acc[ai][bj][m][n];
;                         *(f32x4*)(xf + o) = xn;
;                         u32x2 w; w.x = pk2(xn[0], xn[1]); w.y = pk2(xn[2], xn[3]); *(u32x2*)(xb + o) = w;
;                         s += (xn[0] * xn[0] + xn[1] * xn[1]) + (xn[2] * xn[2] + xn[3] * xn[3]);
;                     }
;                 s += __shfl_xor(s, 16); s += __shfl_xor(s, 32);
;                 if (fq == 0) ssq[(size_t)row * 16 + u.pn * 4 + wc] = s;
.LBB0_1928:
	s_or_b64 exec, exec, s[42:43]
	v_or_b32_e32 v80, 48, v146
	s_waitcnt lgkmcnt(0)
	v_ashrrev_i32_e32 v81, 31, v80
	v_lshlrev_b64 v[82:83], 10, v[80:81]
	v_lshl_add_u64 v[86:87], v[82:83], 0, v[142:143]
	v_lshlrev_b64 v[88:89], 2, v[86:87]
	v_lshl_add_u64 v[90:91], s[14:15], 0, v[88:89]
	v_lshl_add_u64 v[86:87], v[86:87], 1, s[20:21]
	v_lshl_add_u64 v[88:89], s[24:25], 0, v[88:89]
	s_waitcnt vmcnt(41)
	v_mov_b32_e32 v82, v232
	v_mov_b32_e32 v83, v233
	v_mov_b32_e32 v84, v234
	v_mov_b32_e32 v85, v235
	v_add_u32_e32 v173, 0xb0200, v172
	global_load_dwordx4 v[232:235], v173, s[14:15]
	v_pk_add_f32 v[78:79], v[78:79], v[84:85]
	v_pk_add_f32 v[76:77], v[76:77], v[82:83]
	global_store_dwordx4 v[88:89], v[76:79], off
	v_cvt_pk_bf16_f32 v82, v76, v77
	v_cvt_pk_bf16_f32 v83, v78, v79
	global_store_dwordx2 v[86:87], v[82:83], off
	v_mul_f32_e32 v77, v77, v77
	v_mul_f32_e32 v79, v79, v79
	v_fmac_f32_e32 v77, v76, v76
	v_fmac_f32_e32 v79, v78, v78
	v_add_f32_e32 v76, v77, v79
	s_waitcnt vmcnt(43)
	v_mov_b32_e32 v82, v236
	v_mov_b32_e32 v83, v237
	v_mov_b32_e32 v84, v238
	v_mov_b32_e32 v85, v239
	v_add_u32_e32 v173, 0xb0240, v172
	global_load_dwordx4 v[236:239], v173, s[14:15]
	v_pk_add_f32 v[74:75], v[74:75], v[84:85]
	v_pk_add_f32 v[72:73], v[72:73], v[82:83]
	global_store_dwordx4 v[88:89], v[72:75], off offset:64
	v_cvt_pk_bf16_f32 v82, v72, v73
	v_cvt_pk_bf16_f32 v83, v74, v75
	global_store_dwordx2 v[86:87], v[82:83], off offset:32
	v_mul_f32_e32 v73, v73, v73
	v_mul_f32_e32 v75, v75, v75
	v_fmac_f32_e32 v73, v72, v72
	v_fmac_f32_e32 v75, v74, v74
	v_add_f32_e32 v72, v73, v75
	v_add_f32_e32 v72, v76, v72
	s_waitcnt vmcnt(45)
	v_mov_b32_e32 v82, v240
	v_mov_b32_e32 v83, v241
	v_mov_b32_e32 v84, v242
	v_mov_b32_e32 v85, v243
	v_pk_add_f32 v[70:71], v[70:71], v[84:85]
	v_pk_add_f32 v[68:69], v[68:69], v[82:83]
	global_store_dwordx4 v[88:89], v[68:71], off offset:512
	v_cvt_pk_bf16_f32 v82, v68, v69
	v_cvt_pk_bf16_f32 v83, v70, v71
	global_store_dwordx2 v[86:87], v[82:83], off offset:256
	v_mul_f32_e32 v69, v69, v69
	v_mul_f32_e32 v71, v71, v71
	v_fmac_f32_e32 v69, v68, v68
	v_fmac_f32_e32 v71, v70, v70
	v_add_f32_e32 v68, v69, v71
	v_add_f32_e32 v70, v72, v68
	s_waitcnt vmcnt(46)
	v_mov_b32_e32 v82, v244
	v_mov_b32_e32 v83, v245
	v_mov_b32_e32 v84, v246
	v_mov_b32_e32 v85, v247
	v_pk_add_f32 v[68:69], v[66:67], v[84:85]
	v_pk_add_f32 v[66:67], v[64:65], v[82:83]
	v_mul_f32_e32 v65, v69, v69
	v_mul_f32_e32 v64, v67, v67
	v_fmac_f32_e32 v64, v66, v66
	v_fmac_f32_e32 v65, v68, v68
	v_add_f32_e32 v64, v64, v65
	v_add_f32_e32 v64, v70, v64
	ds_bpermute_b32 v65, v116, v64
	global_store_dwordx4 v[88:89], v[66:69], off offset:576
	s_waitcnt lgkmcnt(0)
	v_add_f32_e32 v64, v64, v65
	ds_bpermute_b32 v65, v114, v64
	v_cvt_pk_bf16_f32 v66, v66, v67
	v_cvt_pk_bf16_f32 v67, v68, v69
	global_store_dwordx2 v[86:87], v[66:67], off offset:288
	s_and_saveexec_b64 s[42:43], s[10:11]
	s_cbranch_execz .LBB0_1930
	s_waitcnt lgkmcnt(0)
	v_add_f32_e32 v66, v64, v65
	v_lshlrev_b64 v[64:65], 6, v[80:81]
	v_lshl_add_u64 v[64:65], s[22:23], 0, v[64:65]
	v_lshl_add_u64 v[64:65], s[40:41], 2, v[64:65]
	s_lshl_b32 s30, s67, 2
	v_lshl_add_u64 v[64:65], v[64:65], 0, s[30:31]
	global_store_dword v[64:65], v66, off
.LBB0_1930:
	s_or_b64 exec, exec, s[42:43]
	v_add_u32_e32 v64, 0x80, v146
	s_waitcnt lgkmcnt(0)
	v_ashrrev_i32_e32 v65, 31, v64
	v_lshlrev_b64 v[66:67], 10, v[64:65]
	v_lshl_add_u64 v[70:71], v[66:67], 0, v[142:143]
	v_lshlrev_b64 v[72:73], 2, v[70:71]
	v_lshl_add_u64 v[74:75], s[14:15], 0, v[72:73]
	v_lshl_add_u64 v[70:71], v[70:71], 1, s[20:21]
	v_lshl_add_u64 v[72:73], s[24:25], 0, v[72:73]
	s_waitcnt vmcnt(47)
	v_mov_b32_e32 v66, v248
	v_mov_b32_e32 v67, v249
	v_mov_b32_e32 v68, v250
	v_mov_b32_e32 v69, v251
	v_pk_add_f32 v[62:63], v[62:63], v[68:69]
	v_pk_add_f32 v[60:61], v[60:61], v[66:67]
	global_store_dwordx4 v[72:73], v[60:63], off
	v_cvt_pk_bf16_f32 v66, v60, v61
	v_cvt_pk_bf16_f32 v67, v62, v63
	global_store_dwordx2 v[70:71], v[66:67], off
	v_mul_f32_e32 v61, v61, v61
	v_mul_f32_e32 v63, v63, v63
	v_fmac_f32_e32 v61, v60, v60
	v_fmac_f32_e32 v63, v62, v62
	v_add_f32_e32 v60, v61, v63
	s_waitcnt vmcnt(48)
	v_mov_b32_e32 v66, v252
	v_mov_b32_e32 v67, v253
	v_mov_b32_e32 v68, v254
	v_mov_b32_e32 v69, v255
	v_pk_add_f32 v[58:59], v[58:59], v[68:69]
	v_pk_add_f32 v[56:57], v[56:57], v[66:67]
	global_store_dwordx4 v[72:73], v[56:59], off offset:64
	v_cvt_pk_bf16_f32 v66, v56, v57
	v_cvt_pk_bf16_f32 v67, v58, v59
	global_store_dwordx2 v[70:71], v[66:67], off offset:32
	v_mul_f32_e32 v57, v57, v57
	v_mul_f32_e32 v59, v59, v59
	v_fmac_f32_e32 v57, v56, v56
	v_fmac_f32_e32 v59, v58, v58
	v_add_f32_e32 v56, v57, v59
	v_add_f32_e32 v56, v60, v56
	s_waitcnt vmcnt(49)
	v_mov_b32_e32 v66, v174
	v_mov_b32_e32 v67, v175
	v_mov_b32_e32 v68, v176
	v_mov_b32_e32 v69, v177
	v_pk_add_f32 v[54:55], v[54:55], v[68:69]
	v_pk_add_f32 v[52:53], v[52:53], v[66:67]
	global_store_dwordx4 v[72:73], v[52:55], off offset:512
	v_cvt_pk_bf16_f32 v66, v52, v53
	v_cvt_pk_bf16_f32 v67, v54, v55
	global_store_dwordx2 v[70:71], v[66:67], off offset:256
	v_mul_f32_e32 v53, v53, v53
	v_mul_f32_e32 v55, v55, v55
	v_fmac_f32_e32 v53, v52, v52
	v_fmac_f32_e32 v55, v54, v54
	v_add_f32_e32 v52, v53, v55
	v_add_f32_e32 v54, v56, v52
	s_waitcnt vmcnt(48)
	v_mov_b32_e32 v66, v178
	v_mov_b32_e32 v67, v179
	v_mov_b32_e32 v68, v180
	v_mov_b32_e32 v69, v181
	v_pk_add_f32 v[52:53], v[50:51], v[68:69]
	v_pk_add_f32 v[50:51], v[48:49], v[66:67]
	v_mul_f32_e32 v49, v53, v53
	v_mul_f32_e32 v48, v51, v51
	v_fmac_f32_e32 v48, v50, v50
	v_fmac_f32_e32 v49, v52, v52
	v_add_f32_e32 v48, v48, v49
	v_add_f32_e32 v48, v54, v48
	ds_bpermute_b32 v49, v116, v48
	global_store_dwordx4 v[72:73], v[50:53], off offset:576
	s_waitcnt lgkmcnt(0)
	v_add_f32_e32 v48, v48, v49
	ds_bpermute_b32 v49, v114, v48
	v_cvt_pk_bf16_f32 v50, v50, v51
	v_cvt_pk_bf16_f32 v51, v52, v53
	global_store_dwordx2 v[70:71], v[50:51], off offset:288
	s_and_saveexec_b64 s[42:43], s[10:11]
	s_cbranch_execz .LBB0_1932
	s_waitcnt lgkmcnt(0)
	v_add_f32_e32 v50, v48, v49
	v_lshlrev_b64 v[48:49], 6, v[64:65]
	v_lshl_add_u64 v[48:49], s[22:23], 0, v[48:49]
	v_lshl_add_u64 v[48:49], s[40:41], 2, v[48:49]
	s_lshl_b32 s30, s67, 2
	v_lshl_add_u64 v[48:49], v[48:49], 0, s[30:31]
	global_store_dword v[48:49], v50, off
; __device__ __forceinline__ unsigned pk2(float lo, float hi) { unsigned r; asm volatile("v_cvt_pk_bf16_f32 %0, %1, %2" : "=v"(r) : "v"(lo), "v"(hi)); return r; }
;     __device__ __forceinline__ void operator()(const f32x4 (&acc)[2][2][4][2], const Unit& u, int wr, int wc, int fr, int fq) const {
;     ...
;             for (int m = 0; m < 4; ++m) {
;                 const int row = row0 + ai * 128 + m * 16; const size_t ro = (size_t)row * DM + col0;
;                 float s = 0.f;
; #pragma unroll
;                 for (int bj = 0; bj < 2; ++bj)
; #pragma unroll
;                     for (int n = 0; n < 2; ++n) {
;                         const size_t o = ro + bj * 128 + n * 16;
;                         const f32x4 xn = *(const f32x4*)(xo + o) + acc[ai][bj][m][n];
;                         *(f32x4*)(xf + o) = xn;
;                         u32x2 w; w.x = pk2(xn[0], xn[1]); w.y = pk2(xn[2], xn[3]); *(u32x2*)(xb + o) = w;
;                         s += (xn[0] * xn[0] + xn[1] * xn[1]) + (xn[2] * xn[2] + xn[3] * xn[3]);
;                     }
;                 s += __shfl_xor(s, 16); s += __shfl_xor(s, 32);
;                 if (fq == 0) ssq[(size_t)row * 16 + u.pn * 4 + wc] = s;
.LBB0_1932:
	s_or_b64 exec, exec, s[42:43]
	v_add_u32_e32 v48, 0x90, v146
	s_waitcnt lgkmcnt(0)
	v_ashrrev_i32_e32 v49, 31, v48
	v_lshlrev_b64 v[50:51], 10, v[48:49]
	v_lshl_add_u64 v[54:55], v[50:51], 0, v[142:143]
	v_lshlrev_b64 v[56:57], 2, v[54:55]
	v_lshl_add_u64 v[58:59], s[14:15], 0, v[56:57]
	v_lshl_add_u64 v[54:55], v[54:55], 1, s[20:21]
	v_lshl_add_u64 v[56:57], s[24:25], 0, v[56:57]
	s_waitcnt vmcnt(47)
	v_mov_b32_e32 v50, v182
	v_mov_b32_e32 v51, v183
	v_mov_b32_e32 v52, v184
	v_mov_b32_e32 v53, v185
	v_pk_add_f32 v[46:47], v[46:47], v[52:53]
	v_pk_add_f32 v[44:45], v[44:45], v[50:51]
	global_store_dwordx4 v[56:57], v[44:47], off
	v_cvt_pk_bf16_f32 v50, v44, v45
	v_cvt_pk_bf16_f32 v51, v46, v47
	global_store_dwordx2 v[54:55], v[50:51], off
	v_mul_f32_e32 v45, v45, v45
	v_mul_f32_e32 v47, v47, v47
	v_fmac_f32_e32 v45, v44, v44
	v_fmac_f32_e32 v47, v46, v46
	v_add_f32_e32 v44, v45, v47
	s_waitcnt vmcnt(46)
	v_mov_b32_e32 v50, v186
	v_mov_b32_e32 v51, v187
	v_mov_b32_e32 v52, v188
	v_mov_b32_e32 v53, v189
	v_pk_add_f32 v[42:43], v[42:43], v[52:53]
	v_pk_add_f32 v[40:41], v[40:41], v[50:51]
	global_store_dwordx4 v[56:57], v[40:43], off offset:64
	v_cvt_pk_bf16_f32 v50, v40, v41
	v_cvt_pk_bf16_f32 v51, v42, v43
	global_store_dwordx2 v[54:55], v[50:51], off offset:32
	v_mul_f32_e32 v41, v41, v41
	v_mul_f32_e32 v43, v43, v43
	v_fmac_f32_e32 v41, v40, v40
	v_fmac_f32_e32 v43, v42, v42
	v_add_f32_e32 v40, v41, v43
	v_add_f32_e32 v40, v44, v40
	s_waitcnt vmcnt(45)
	v_mov_b32_e32 v50, v190
	v_mov_b32_e32 v51, v191
	v_mov_b32_e32 v52, v192
	v_mov_b32_e32 v53, v193
	v_pk_add_f32 v[38:39], v[38:39], v[52:53]
	v_pk_add_f32 v[36:37], v[36:37], v[50:51]
	global_store_dwordx4 v[56:57], v[36:39], off offset:512
	v_cvt_pk_bf16_f32 v50, v36, v37
	v_cvt_pk_bf16_f32 v51, v38, v39
	global_store_dwordx2 v[54:55], v[50:51], off offset:256
	v_mul_f32_e32 v37, v37, v37
	v_mul_f32_e32 v39, v39, v39
	v_fmac_f32_e32 v37, v36, v36
	v_fmac_f32_e32 v39, v38, v38
	v_add_f32_e32 v36, v37, v39
	v_add_f32_e32 v38, v40, v36
	s_waitcnt vmcnt(44)
	v_mov_b32_e32 v50, v194
	v_mov_b32_e32 v51, v195
	v_mov_b32_e32 v52, v196
	v_mov_b32_e32 v53, v197
	v_pk_add_f32 v[36:37], v[34:35], v[52:53]
	v_pk_add_f32 v[34:35], v[32:33], v[50:51]
	v_mul_f32_e32 v33, v37, v37
	v_mul_f32_e32 v32, v35, v35
	v_fmac_f32_e32 v32, v34, v34
	v_fmac_f32_e32 v33, v36, v36
	v_add_f32_e32 v32, v32, v33
	v_add_f32_e32 v32, v38, v32
	ds_bpermute_b32 v33, v116, v32
	global_store_dwordx4 v[56:57], v[34:37], off offset:576
	s_waitcnt lgkmcnt(0)
	v_add_f32_e32 v32, v32, v33
	ds_bpermute_b32 v33, v114, v32
	v_cvt_pk_bf16_f32 v34, v34, v35
	v_cvt_pk_bf16_f32 v35, v36, v37
	global_store_dwordx2 v[54:55], v[34:35], off offset:288
	s_and_saveexec_b64 s[42:43], s[10:11]
	s_cbranch_execz .LBB0_1934
	s_waitcnt lgkmcnt(0)
	v_add_f32_e32 v34, v32, v33
	v_lshlrev_b64 v[32:33], 6, v[48:49]
	v_lshl_add_u64 v[32:33], s[22:23], 0, v[32:33]
	v_lshl_add_u64 v[32:33], s[40:41], 2, v[32:33]
	s_lshl_b32 s30, s67, 2
	v_lshl_add_u64 v[32:33], v[32:33], 0, s[30:31]
	global_store_dword v[32:33], v34, off
; __device__ __forceinline__ unsigned pk2(float lo, float hi) { unsigned r; asm volatile("v_cvt_pk_bf16_f32 %0, %1, %2" : "=v"(r) : "v"(lo), "v"(hi)); return r; }
;     __device__ __forceinline__ void operator()(const f32x4 (&acc)[2][2][4][2], const Unit& u, int wr, int wc, int fr, int fq) const {
;     ...
;             for (int m = 0; m < 4; ++m) {
;                 const int row = row0 + ai * 128 + m * 16; const size_t ro = (size_t)row * DM + col0;
;                 float s = 0.f;
; #pragma unroll
;                 for (int bj = 0; bj < 2; ++bj)
; #pragma unroll
;                     for (int n = 0; n < 2; ++n) {
;                         const size_t o = ro + bj * 128 + n * 16;
;                         const f32x4 xn = *(const f32x4*)(xo + o) + acc[ai][bj][m][n];
;                         *(f32x4*)(xf + o) = xn;
;                         u32x2 w; w.x = pk2(xn[0], xn[1]); w.y = pk2(xn[2], xn[3]); *(u32x2*)(xb + o) = w;
;                         s += (xn[0] * xn[0] + xn[1] * xn[1]) + (xn[2] * xn[2] + xn[3] * xn[3]);
;                     }
;                 s += __shfl_xor(s, 16); s += __shfl_xor(s, 32);
;                 if (fq == 0) ssq[(size_t)row * 16 + u.pn * 4 + wc] = s;
.LBB0_1934:
	s_or_b64 exec, exec, s[42:43]
	v_add_u32_e32 v32, 0xa0, v146
	s_waitcnt lgkmcnt(0)
	v_ashrrev_i32_e32 v33, 31, v32
	v_lshlrev_b64 v[34:35], 10, v[32:33]
	v_lshl_add_u64 v[38:39], v[34:35], 0, v[142:143]
	v_lshlrev_b64 v[40:41], 2, v[38:39]
	v_lshl_add_u64 v[42:43], s[14:15], 0, v[40:41]
	v_lshl_add_u64 v[38:39], v[38:39], 1, s[20:21]
	v_lshl_add_u64 v[40:41], s[24:25], 0, v[40:41]
	s_waitcnt vmcnt(43)
	v_mov_b32_e32 v34, v198
	v_mov_b32_e32 v35, v199
	v_mov_b32_e32 v36, v200
	v_mov_b32_e32 v37, v201
	v_pk_add_f32 v[30:31], v[30:31], v[36:37]
	v_pk_add_f32 v[28:29], v[28:29], v[34:35]
	global_store_dwordx4 v[40:41], v[28:31], off
	v_cvt_pk_bf16_f32 v34, v28, v29
	v_cvt_pk_bf16_f32 v35, v30, v31
	global_store_dwordx2 v[38:39], v[34:35], off
	v_mul_f32_e32 v29, v29, v29
	v_mul_f32_e32 v31, v31, v31
	v_fmac_f32_e32 v29, v28, v28
	v_fmac_f32_e32 v31, v30, v30
	v_add_f32_e32 v28, v29, v31
	s_waitcnt vmcnt(42)
	v_mov_b32_e32 v34, v202
	v_mov_b32_e32 v35, v203
	v_mov_b32_e32 v36, v204
	v_mov_b32_e32 v37, v205
	v_pk_add_f32 v[26:27], v[26:27], v[36:37]
	v_pk_add_f32 v[24:25], v[24:25], v[34:35]
	global_store_dwordx4 v[40:41], v[24:27], off offset:64
	v_cvt_pk_bf16_f32 v34, v24, v25
	v_cvt_pk_bf16_f32 v35, v26, v27
	global_store_dwordx2 v[38:39], v[34:35], off offset:32
	v_mul_f32_e32 v25, v25, v25
	v_mul_f32_e32 v27, v27, v27
	v_fmac_f32_e32 v25, v24, v24
	v_fmac_f32_e32 v27, v26, v26
	v_add_f32_e32 v24, v25, v27
	v_add_f32_e32 v24, v28, v24
	s_waitcnt vmcnt(41)
	v_mov_b32_e32 v34, v206
	v_mov_b32_e32 v35, v207
	v_mov_b32_e32 v36, v208
	v_mov_b32_e32 v37, v209
	v_pk_add_f32 v[22:23], v[22:23], v[36:37]
	v_pk_add_f32 v[20:21], v[20:21], v[34:35]
	global_store_dwordx4 v[40:41], v[20:23], off offset:512
	v_cvt_pk_bf16_f32 v34, v20, v21
	v_cvt_pk_bf16_f32 v35, v22, v23
	global_store_dwordx2 v[38:39], v[34:35], off offset:256
	v_mul_f32_e32 v21, v21, v21
	v_mul_f32_e32 v23, v23, v23
	v_fmac_f32_e32 v21, v20, v20
	v_fmac_f32_e32 v23, v22, v22
	v_add_f32_e32 v20, v21, v23
	v_add_f32_e32 v22, v24, v20
	s_waitcnt vmcnt(40)
	v_mov_b32_e32 v34, v210
	v_mov_b32_e32 v35, v211
	v_mov_b32_e32 v36, v212
	v_mov_b32_e32 v37, v213
	v_pk_add_f32 v[20:21], v[18:19], v[36:37]
	v_pk_add_f32 v[18:19], v[16:17], v[34:35]
	v_mul_f32_e32 v17, v21, v21
	v_mul_f32_e32 v16, v19, v19
	v_fmac_f32_e32 v16, v18, v18
	v_fmac_f32_e32 v17, v20, v20
	v_add_f32_e32 v16, v16, v17
	v_add_f32_e32 v16, v22, v16
	ds_bpermute_b32 v17, v116, v16
	global_store_dwordx4 v[40:41], v[18:21], off offset:576
	s_waitcnt lgkmcnt(0)
	v_add_f32_e32 v16, v16, v17
	ds_bpermute_b32 v17, v114, v16
	v_cvt_pk_bf16_f32 v18, v18, v19
	v_cvt_pk_bf16_f32 v19, v20, v21
	global_store_dwordx2 v[38:39], v[18:19], off offset:288
	s_and_saveexec_b64 s[42:43], s[10:11]
	s_cbranch_execz .LBB0_1936
	s_waitcnt lgkmcnt(0)
	v_add_f32_e32 v18, v16, v17
	v_lshlrev_b64 v[16:17], 6, v[32:33]
	v_lshl_add_u64 v[16:17], s[22:23], 0, v[16:17]
	v_lshl_add_u64 v[16:17], s[40:41], 2, v[16:17]
	s_lshl_b32 s30, s67, 2
	v_lshl_add_u64 v[16:17], v[16:17], 0, s[30:31]
	global_store_dword v[16:17], v18, off
.LBB0_1936:
	s_or_b64 exec, exec, s[42:43]
	v_add_u32_e32 v16, 0xb0, v146
	s_waitcnt lgkmcnt(0)
	v_ashrrev_i32_e32 v17, 31, v16
	v_lshlrev_b64 v[18:19], 10, v[16:17]
	v_lshl_add_u64 v[22:23], v[18:19], 0, v[142:143]
	v_lshlrev_b64 v[24:25], 2, v[22:23]
	v_lshl_add_u64 v[26:27], s[14:15], 0, v[24:25]
	v_lshl_add_u64 v[22:23], v[22:23], 1, s[20:21]
	v_lshl_add_u64 v[24:25], s[24:25], 0, v[24:25]
	s_waitcnt vmcnt(39)
	v_mov_b32_e32 v18, v214
	v_mov_b32_e32 v19, v215
	v_mov_b32_e32 v20, v216
	v_mov_b32_e32 v21, v217
	v_pk_add_f32 v[14:15], v[14:15], v[20:21]
	v_pk_add_f32 v[12:13], v[12:13], v[18:19]
	global_store_dwordx4 v[24:25], v[12:15], off
	v_cvt_pk_bf16_f32 v18, v12, v13
	v_cvt_pk_bf16_f32 v19, v14, v15
	global_store_dwordx2 v[22:23], v[18:19], off
	v_mul_f32_e32 v13, v13, v13
	v_mul_f32_e32 v15, v15, v15
	v_fmac_f32_e32 v13, v12, v12
	v_fmac_f32_e32 v15, v14, v14
	v_add_f32_e32 v12, v13, v15
	s_waitcnt vmcnt(38)
	v_mov_b32_e32 v18, v218
	v_mov_b32_e32 v19, v219
	v_mov_b32_e32 v20, v220
	v_mov_b32_e32 v21, v221
	v_pk_add_f32 v[10:11], v[10:11], v[20:21]
	v_pk_add_f32 v[8:9], v[8:9], v[18:19]
	global_store_dwordx4 v[24:25], v[8:11], off offset:64
	v_cvt_pk_bf16_f32 v18, v8, v9
	v_cvt_pk_bf16_f32 v19, v10, v11
	global_store_dwordx2 v[22:23], v[18:19], off offset:32
	v_mul_f32_e32 v9, v9, v9
	v_mul_f32_e32 v11, v11, v11
	v_fmac_f32_e32 v9, v8, v8
	v_fmac_f32_e32 v11, v10, v10
	v_add_f32_e32 v8, v9, v11
	v_add_f32_e32 v8, v12, v8
	s_waitcnt vmcnt(37)
	v_mov_b32_e32 v18, v232
	v_mov_b32_e32 v19, v233
	v_mov_b32_e32 v20, v234
	v_mov_b32_e32 v21, v235
	v_pk_add_f32 v[6:7], v[6:7], v[20:21]
	v_pk_add_f32 v[4:5], v[4:5], v[18:19]
	global_store_dwordx4 v[24:25], v[4:7], off offset:512
	v_cvt_pk_bf16_f32 v18, v4, v5
	v_cvt_pk_bf16_f32 v19, v6, v7
	global_store_dwordx2 v[22:23], v[18:19], off offset:256
	v_mul_f32_e32 v5, v5, v5
	v_mul_f32_e32 v7, v7, v7
	v_fmac_f32_e32 v5, v4, v4
	v_fmac_f32_e32 v7, v6, v6
	v_add_f32_e32 v4, v5, v7
	v_add_f32_e32 v6, v8, v4
	s_waitcnt vmcnt(36)
	v_mov_b32_e32 v18, v236
	v_mov_b32_e32 v19, v237
	v_mov_b32_e32 v20, v238
	v_mov_b32_e32 v21, v239
	v_pk_add_f32 v[4:5], v[2:3], v[20:21]
	v_pk_add_f32 v[2:3], v[0:1], v[18:19]
	v_mul_f32_e32 v1, v5, v5
	v_mul_f32_e32 v0, v3, v3
	v_fmac_f32_e32 v0, v2, v2
	v_fmac_f32_e32 v1, v4, v4
	v_add_f32_e32 v0, v0, v1
	v_add_f32_e32 v0, v6, v0
	ds_bpermute_b32 v1, v116, v0
	global_store_dwordx4 v[24:25], v[2:5], off offset:576
	s_waitcnt lgkmcnt(0)
	v_add_f32_e32 v0, v0, v1
	ds_bpermute_b32 v1, v114, v0
	v_cvt_pk_bf16_f32 v2, v2, v3
	v_cvt_pk_bf16_f32 v3, v4, v5
	global_store_dwordx2 v[22:23], v[2:3], off offset:288
	s_and_saveexec_b64 s[14:15], s[10:11]
	s_cbranch_execz .LBB0_1895
	s_waitcnt lgkmcnt(0)
	v_add_f32_e32 v2, v0, v1
	v_lshlrev_b64 v[0:1], 6, v[16:17]
	v_lshl_add_u64 v[0:1], s[22:23], 0, v[0:1]
	v_lshl_add_u64 v[0:1], s[40:41], 2, v[0:1]
	s_lshl_b32 s30, s67, 2
	v_lshl_add_u64 v[0:1], v[0:1], 0, s[30:31]
	global_store_dword v[0:1], v2, off
	s_branch .LBB0_1895

; __device__ __forceinline__ unsigned pk2(float lo, float hi) { unsigned r; asm volatile("v_cvt_pk_bf16_f32 %0, %1, %2" : "=v"(r) : "v"(lo), "v"(hi)); return r; }
;     __device__ __forceinline__ void operator()(const f32x4 (&acc)[2][2][4][2], const Unit& u, int wr, int wc, int fr, int fq) const {
;         const int row0 = u.pm * 256 + wr * 64 + fr, col0 = u.pn * 256 + wc * 32 + 4 * fq;
;         const float* xo = (u.pm < 64) ? xoldA : (xoldB - (size_t)T_P * DM);
; #pragma unroll
;         for (int ai = 0; ai < 2; ++ai)
; #pragma unroll
;             for (int m = 0; m < 4; ++m) {
;                 const int row = row0 + ai * 128 + m * 16; const size_t ro = (size_t)row * DM + col0;
;                 float s = 0.f;
; #pragma unroll
;                 for (int bj = 0; bj < 2; ++bj)
; #pragma unroll
;                     for (int n = 0; n < 2; ++n) {
;                         const size_t o = ro + bj * 128 + n * 16;
;                         const f32x4 xn = *(const f32x4*)(xo + o) + acc[ai][bj][m][n];
;                         *(f32x4*)(xf + o) = xn;
;                         u32x2 w; w.x = pk2(xn[0], xn[1]); w.y = pk2(xn[2], xn[3]); *(u32x2*)(xb + o) = w;
;                         s += (xn[0] * xn[0] + xn[1] * xn[1]) + (xn[2] * xn[2] + xn[3] * xn[3]);
;                     }
;                 s += __shfl_xor(s, 16); s += __shfl_xor(s, 32);
;                 if (fq == 0) ssq[(size_t)row * 16 + u.pn * 4 + wc] = s;
.LBB0_2178:
	v_lshl_add_u32 v138, s42, 8, v140
	v_lshl_or_b32 v136, s40, 8, v142
	v_ashrrev_i32_e32 v139, 31, v138
	v_ashrrev_i32_e32 v137, 31, v136
	v_lshlrev_b64 v[148:149], 10, v[138:139]
	s_cmp_lt_i32 s42, 64
	v_lshl_add_u64 v[152:153], v[148:149], 0, v[136:137]
	s_cselect_b32 s13, s17, -1
	s_cselect_b32 s12, s16, 0xfc000000
	v_lshlrev_b64 v[154:155], 2, v[152:153]
	v_lshl_add_u64 v[156:157], s[12:13], 0, v[154:155]
	v_subrev_u32_e32 v162, s12, v156
	v_add_u32_e32 v163, 0x0, v162
	global_load_dwordx4 v[170:173], v163, s[12:13]
	v_add_u32_e32 v163, 0x40, v162
	global_load_dwordx4 v[174:177], v163, s[12:13]
	v_add_u32_e32 v163, 0x200, v162
	global_load_dwordx4 v[178:181], v163, s[12:13]
	v_add_u32_e32 v163, 0x240, v162
	global_load_dwordx4 v[182:185], v163, s[12:13]
	v_add_u32_e32 v163, 0x10000, v162
	global_load_dwordx4 v[186:189], v163, s[12:13]
	v_add_u32_e32 v163, 0x10040, v162
	global_load_dwordx4 v[190:193], v163, s[12:13]
	v_add_u32_e32 v163, 0x10200, v162
	global_load_dwordx4 v[194:197], v163, s[12:13]
	v_add_u32_e32 v163, 0x10240, v162
	global_load_dwordx4 v[198:201], v163, s[12:13]
	v_add_u32_e32 v163, 0x20000, v162
	global_load_dwordx4 v[202:205], v163, s[12:13]
	v_add_u32_e32 v163, 0x20040, v162
	global_load_dwordx4 v[206:209], v163, s[12:13]
	v_add_u32_e32 v163, 0x20200, v162
	global_load_dwordx4 v[210:213], v163, s[12:13]
	v_add_u32_e32 v163, 0x20240, v162
	global_load_dwordx4 v[232:235], v163, s[12:13]
	v_add_u32_e32 v163, 0x30000, v162
	global_load_dwordx4 v[236:239], v163, s[12:13]
	v_add_u32_e32 v163, 0x30040, v162
	global_load_dwordx4 v[240:243], v163, s[12:13]
	v_add_u32_e32 v163, 0x30200, v162
	global_load_dwordx4 v[244:247], v163, s[12:13]
	v_add_u32_e32 v163, 0x30240, v162
	global_load_dwordx4 v[248:251], v163, s[12:13]
	v_add_u32_e32 v163, 0x80000, v162
	global_load_dwordx4 v[252:255], v163, s[12:13]
	v_lshl_add_u64 v[158:159], v[152:153], 1, s[22:23]
	v_lshl_add_u64 v[160:161], s[16:17], 0, v[154:155]
	v_xor_b32_e32 v147, 32, v146
	s_lshl_b32 s40, s40, 2
	s_ashr_i32 s41, s40, 31
	s_waitcnt vmcnt(16)
	v_mov_b32_e32 v148, v170
	v_mov_b32_e32 v149, v171
	v_mov_b32_e32 v150, v172
	v_mov_b32_e32 v151, v173
	v_add_u32_e32 v163, 0x80040, v162
	global_load_dwordx4 v[170:173], v163, s[12:13]
	v_pk_add_f32 v[126:127], v[126:127], v[150:151]
	v_pk_add_f32 v[124:125], v[124:125], v[148:149]
	global_store_dwordx4 v[160:161], v[124:127], off
	v_cvt_pk_bf16_f32 v148, v124, v125
	v_cvt_pk_bf16_f32 v149, v126, v127
	global_store_dwordx2 v[158:159], v[148:149], off
	s_waitcnt vmcnt(18)
	v_mov_b32_e32 v148, v174
	v_mov_b32_e32 v149, v175
	v_mov_b32_e32 v150, v176
	v_mov_b32_e32 v151, v177
	v_add_u32_e32 v163, 0x80200, v162
	global_load_dwordx4 v[174:177], v163, s[12:13]
	v_pk_add_f32 v[122:123], v[122:123], v[150:151]
	v_pk_add_f32 v[120:121], v[120:121], v[148:149]
	global_store_dwordx4 v[160:161], v[120:123], off offset:64
	v_cvt_pk_bf16_f32 v148, v120, v121
	v_cvt_pk_bf16_f32 v149, v122, v123
	global_store_dwordx2 v[158:159], v[148:149], off offset:32
	s_waitcnt vmcnt(20)
	v_mov_b32_e32 v148, v178
	v_mov_b32_e32 v149, v179
	v_mov_b32_e32 v150, v180
	v_mov_b32_e32 v151, v181
	v_add_u32_e32 v163, 0x80240, v162
	global_load_dwordx4 v[178:181], v163, s[12:13]
	v_pk_add_f32 v[150:151], v[118:119], v[150:151]
	v_pk_add_f32 v[148:149], v[116:117], v[148:149]
	global_store_dwordx4 v[160:161], v[148:151], off offset:512
	v_cvt_pk_bf16_f32 v116, v148, v149
	v_cvt_pk_bf16_f32 v117, v150, v151
	global_store_dwordx2 v[158:159], v[116:117], off offset:256
	v_mul_f32_e32 v118, v125, v125
	v_mul_f32_e32 v119, v127, v127
	v_fmac_f32_e32 v118, v124, v124
	v_fmac_f32_e32 v119, v126, v126
	v_add_f32_e32 v118, v118, v119
	v_mul_f32_e32 v119, v121, v121
	v_mul_f32_e32 v121, v123, v123
	v_fmac_f32_e32 v119, v120, v120
	v_fmac_f32_e32 v121, v122, v122
	v_add_f32_e32 v119, v119, v121
	v_add_f32_e32 v118, v118, v119
	v_mul_f32_e32 v119, v149, v149
	v_mul_f32_e32 v120, v151, v151
	v_fmac_f32_e32 v119, v148, v148
	v_fmac_f32_e32 v120, v150, v150
	v_add_f32_e32 v119, v119, v120
	v_and_b32_e32 v117, 64, v146
	v_add_f32_e32 v122, v118, v119
	v_xor_b32_e32 v116, 16, v146
	v_add_u32_e32 v117, 64, v117
	v_cmp_lt_i32_e32 vcc, v116, v117
	s_waitcnt vmcnt(22)
	v_mov_b32_e32 v152, v182
	v_mov_b32_e32 v153, v183
	v_mov_b32_e32 v154, v184
	v_mov_b32_e32 v155, v185
	v_add_u32_e32 v163, 0x90000, v162
	global_load_dwordx4 v[182:185], v163, s[12:13]
	v_pk_add_f32 v[120:121], v[114:115], v[154:155]
	v_pk_add_f32 v[118:119], v[112:113], v[152:153]
	v_mul_f32_e32 v113, v121, v121
	v_mul_f32_e32 v112, v119, v119
	v_fmac_f32_e32 v112, v118, v118
	v_fmac_f32_e32 v113, v120, v120
	v_cndmask_b32_e32 v116, v146, v116, vcc
	v_add_f32_e32 v112, v112, v113
	v_lshlrev_b32_e32 v116, 2, v116
	v_add_f32_e32 v112, v122, v112
	ds_bpermute_b32 v113, v116, v112
	v_cmp_lt_i32_e32 vcc, v147, v117
	global_store_dwordx4 v[160:161], v[118:121], off offset:576
	s_waitcnt lgkmcnt(0)
	v_add_f32_e32 v112, v112, v113
	v_cndmask_b32_e32 v114, v146, v147, vcc
	v_lshlrev_b32_e32 v114, 2, v114
	ds_bpermute_b32 v113, v114, v112
	v_cvt_pk_bf16_f32 v118, v118, v119
	v_cvt_pk_bf16_f32 v119, v120, v121
	global_store_dwordx2 v[158:159], v[118:119], off offset:288
	s_and_saveexec_b64 s[42:43], s[8:9]
	s_cbranch_execz .LBB0_2180
	s_waitcnt lgkmcnt(0)
	v_add_f32_e32 v115, v112, v113
	v_lshlrev_b64 v[112:113], 6, v[138:139]
	v_lshl_add_u64 v[112:113], s[24:25], 0, v[112:113]
	v_lshl_add_u64 v[112:113], s[40:41], 2, v[112:113]
	s_lshl_b32 s26, s74, 2
	v_lshl_add_u64 v[112:113], v[112:113], 0, s[26:27]
	global_store_dword v[112:113], v115, off
; __device__ __forceinline__ unsigned pk2(float lo, float hi) { unsigned r; asm volatile("v_cvt_pk_bf16_f32 %0, %1, %2" : "=v"(r) : "v"(lo), "v"(hi)); return r; }
;     __device__ __forceinline__ void operator()(const f32x4 (&acc)[2][2][4][2], const Unit& u, int wr, int wc, int fr, int fq) const {
;     ...
;             for (int m = 0; m < 4; ++m) {
;                 const int row = row0 + ai * 128 + m * 16; const size_t ro = (size_t)row * DM + col0;
;                 float s = 0.f;
; #pragma unroll
;                 for (int bj = 0; bj < 2; ++bj)
; #pragma unroll
;                     for (int n = 0; n < 2; ++n) {
;                         const size_t o = ro + bj * 128 + n * 16;
;                         const f32x4 xn = *(const f32x4*)(xo + o) + acc[ai][bj][m][n];
;                         *(f32x4*)(xf + o) = xn;
;                         u32x2 w; w.x = pk2(xn[0], xn[1]); w.y = pk2(xn[2], xn[3]); *(u32x2*)(xb + o) = w;
;                         s += (xn[0] * xn[0] + xn[1] * xn[1]) + (xn[2] * xn[2] + xn[3] * xn[3]);
;                     }
;                 s += __shfl_xor(s, 16); s += __shfl_xor(s, 32);
;                 if (fq == 0) ssq[(size_t)row * 16 + u.pn * 4 + wc] = s;
.LBB0_2180:
	s_or_b64 exec, exec, s[42:43]
	v_or_b32_e32 v112, 16, v138
	s_waitcnt lgkmcnt(0)
	v_ashrrev_i32_e32 v113, 31, v112
	v_lshlrev_b64 v[118:119], 10, v[112:113]
	v_lshl_add_u64 v[122:123], v[118:119], 0, v[136:137]
	v_lshlrev_b64 v[124:125], 2, v[122:123]
	v_lshl_add_u64 v[126:127], s[12:13], 0, v[124:125]
	v_lshl_add_u64 v[122:123], v[122:123], 1, s[22:23]
	v_lshl_add_u64 v[124:125], s[16:17], 0, v[124:125]
	s_waitcnt vmcnt(24)
	v_mov_b32_e32 v118, v186
	v_mov_b32_e32 v119, v187
	v_mov_b32_e32 v120, v188
	v_mov_b32_e32 v121, v189
	v_add_u32_e32 v163, 0x90040, v162
	global_load_dwordx4 v[186:189], v163, s[12:13]
	v_pk_add_f32 v[110:111], v[110:111], v[120:121]
	v_pk_add_f32 v[108:109], v[108:109], v[118:119]
	global_store_dwordx4 v[124:125], v[108:111], off
	v_cvt_pk_bf16_f32 v118, v108, v109
	v_cvt_pk_bf16_f32 v119, v110, v111
	global_store_dwordx2 v[122:123], v[118:119], off
	v_mul_f32_e32 v109, v109, v109
	v_mul_f32_e32 v111, v111, v111
	v_fmac_f32_e32 v109, v108, v108
	v_fmac_f32_e32 v111, v110, v110
	v_add_f32_e32 v108, v109, v111
	s_waitcnt vmcnt(26)
	v_mov_b32_e32 v118, v190
	v_mov_b32_e32 v119, v191
	v_mov_b32_e32 v120, v192
	v_mov_b32_e32 v121, v193
	v_add_u32_e32 v163, 0x90200, v162
	global_load_dwordx4 v[190:193], v163, s[12:13]
	v_pk_add_f32 v[106:107], v[106:107], v[120:121]
	v_pk_add_f32 v[104:105], v[104:105], v[118:119]
	global_store_dwordx4 v[124:125], v[104:107], off offset:64
	v_cvt_pk_bf16_f32 v118, v104, v105
	v_cvt_pk_bf16_f32 v119, v106, v107
	global_store_dwordx2 v[122:123], v[118:119], off offset:32
	v_mul_f32_e32 v105, v105, v105
	v_mul_f32_e32 v107, v107, v107
	v_fmac_f32_e32 v105, v104, v104
	v_fmac_f32_e32 v107, v106, v106
	v_add_f32_e32 v104, v105, v107
	v_add_f32_e32 v104, v108, v104
	s_waitcnt vmcnt(28)
	v_mov_b32_e32 v118, v194
	v_mov_b32_e32 v119, v195
	v_mov_b32_e32 v120, v196
	v_mov_b32_e32 v121, v197
	v_add_u32_e32 v163, 0x90240, v162
	global_load_dwordx4 v[194:197], v163, s[12:13]
	v_pk_add_f32 v[102:103], v[102:103], v[120:121]
	v_pk_add_f32 v[100:101], v[100:101], v[118:119]
	global_store_dwordx4 v[124:125], v[100:103], off offset:512
	v_cvt_pk_bf16_f32 v118, v100, v101
	v_cvt_pk_bf16_f32 v119, v102, v103
	global_store_dwordx2 v[122:123], v[118:119], off offset:256
	v_mul_f32_e32 v101, v101, v101
	v_mul_f32_e32 v103, v103, v103
	v_fmac_f32_e32 v101, v100, v100
	v_fmac_f32_e32 v103, v102, v102
	v_add_f32_e32 v100, v101, v103
	v_add_f32_e32 v102, v104, v100
	s_waitcnt vmcnt(30)
	v_mov_b32_e32 v118, v198
	v_mov_b32_e32 v119, v199
	v_mov_b32_e32 v120, v200
	v_mov_b32_e32 v121, v201
	v_add_u32_e32 v163, 0xa0000, v162
	global_load_dwordx4 v[198:201], v163, s[12:13]
	v_pk_add_f32 v[100:101], v[98:99], v[120:121]
	v_pk_add_f32 v[98:99], v[96:97], v[118:119]
	v_mul_f32_e32 v97, v101, v101
	v_mul_f32_e32 v96, v99, v99
	v_fmac_f32_e32 v96, v98, v98
	v_fmac_f32_e32 v97, v100, v100
	v_add_f32_e32 v96, v96, v97
	v_add_f32_e32 v96, v102, v96
	ds_bpermute_b32 v97, v116, v96
	global_store_dwordx4 v[124:125], v[98:101], off offset:576
	s_waitcnt lgkmcnt(0)
	v_add_f32_e32 v96, v96, v97
	ds_bpermute_b32 v97, v114, v96
	v_cvt_pk_bf16_f32 v98, v98, v99
	v_cvt_pk_bf16_f32 v99, v100, v101
	global_store_dwordx2 v[122:123], v[98:99], off offset:288
	s_and_saveexec_b64 s[42:43], s[8:9]
	s_cbranch_execz .LBB0_2182
	s_waitcnt lgkmcnt(0)
	v_add_f32_e32 v98, v96, v97
	v_lshlrev_b64 v[96:97], 6, v[112:113]
	v_lshl_add_u64 v[96:97], s[24:25], 0, v[96:97]
	v_lshl_add_u64 v[96:97], s[40:41], 2, v[96:97]
	s_lshl_b32 s26, s74, 2
	v_lshl_add_u64 v[96:97], v[96:97], 0, s[26:27]
	global_store_dword v[96:97], v98, off
.LBB0_2182:
	s_or_b64 exec, exec, s[42:43]
	v_or_b32_e32 v96, 32, v138
	s_waitcnt lgkmcnt(0)
	v_ashrrev_i32_e32 v97, 31, v96
	v_lshlrev_b64 v[98:99], 10, v[96:97]
	v_lshl_add_u64 v[102:103], v[98:99], 0, v[136:137]
	v_lshlrev_b64 v[104:105], 2, v[102:103]
	v_lshl_add_u64 v[106:107], s[12:13], 0, v[104:105]
	v_lshl_add_u64 v[102:103], v[102:103], 1, s[22:23]
	v_lshl_add_u64 v[104:105], s[16:17], 0, v[104:105]
	s_waitcnt vmcnt(32)
	v_mov_b32_e32 v98, v202
	v_mov_b32_e32 v99, v203
	v_mov_b32_e32 v100, v204
	v_mov_b32_e32 v101, v205
	v_add_u32_e32 v163, 0xa0040, v162
	global_load_dwordx4 v[202:205], v163, s[12:13]
	v_pk_add_f32 v[94:95], v[94:95], v[100:101]
	v_pk_add_f32 v[92:93], v[92:93], v[98:99]
	global_store_dwordx4 v[104:105], v[92:95], off
	v_cvt_pk_bf16_f32 v98, v92, v93
	v_cvt_pk_bf16_f32 v99, v94, v95
	global_store_dwordx2 v[102:103], v[98:99], off
	v_mul_f32_e32 v93, v93, v93
	v_mul_f32_e32 v95, v95, v95
	v_fmac_f32_e32 v93, v92, v92
	v_fmac_f32_e32 v95, v94, v94
	v_add_f32_e32 v92, v93, v95
	s_waitcnt vmcnt(34)
	v_mov_b32_e32 v98, v206
	v_mov_b32_e32 v99, v207
	v_mov_b32_e32 v100, v208
	v_mov_b32_e32 v101, v209
	v_add_u32_e32 v163, 0xa0200, v162
	global_load_dwordx4 v[206:209], v163, s[12:13]
	v_pk_add_f32 v[90:91], v[90:91], v[100:101]
	v_pk_add_f32 v[88:89], v[88:89], v[98:99]
	global_store_dwordx4 v[104:105], v[88:91], off offset:64
	v_cvt_pk_bf16_f32 v98, v88, v89
	v_cvt_pk_bf16_f32 v99, v90, v91
	global_store_dwordx2 v[102:103], v[98:99], off offset:32
	v_mul_f32_e32 v89, v89, v89
	v_mul_f32_e32 v91, v91, v91
	v_fmac_f32_e32 v89, v88, v88
	v_fmac_f32_e32 v91, v90, v90
	v_add_f32_e32 v88, v89, v91
	v_add_f32_e32 v88, v92, v88
	s_waitcnt vmcnt(36)
	v_mov_b32_e32 v98, v210
	v_mov_b32_e32 v99, v211
	v_mov_b32_e32 v100, v212
	v_mov_b32_e32 v101, v213
	v_add_u32_e32 v163, 0xa0240, v162
	global_load_dwordx4 v[210:213], v163, s[12:13]
	v_pk_add_f32 v[86:87], v[86:87], v[100:101]
	v_pk_add_f32 v[84:85], v[84:85], v[98:99]
	global_store_dwordx4 v[104:105], v[84:87], off offset:512
	v_cvt_pk_bf16_f32 v98, v84, v85
	v_cvt_pk_bf16_f32 v99, v86, v87
	global_store_dwordx2 v[102:103], v[98:99], off offset:256
	v_mul_f32_e32 v85, v85, v85
	v_mul_f32_e32 v87, v87, v87
	v_fmac_f32_e32 v85, v84, v84
	v_fmac_f32_e32 v87, v86, v86
	v_add_f32_e32 v84, v85, v87
	v_add_f32_e32 v86, v88, v84
	s_waitcnt vmcnt(38)
	v_mov_b32_e32 v98, v232
	v_mov_b32_e32 v99, v233
	v_mov_b32_e32 v100, v234
	v_mov_b32_e32 v101, v235
	v_add_u32_e32 v163, 0xb0000, v162
	global_load_dwordx4 v[232:235], v163, s[12:13]
	v_pk_add_f32 v[84:85], v[82:83], v[100:101]
	v_pk_add_f32 v[82:83], v[80:81], v[98:99]
	v_mul_f32_e32 v81, v85, v85
	v_mul_f32_e32 v80, v83, v83
	v_fmac_f32_e32 v80, v82, v82
	v_fmac_f32_e32 v81, v84, v84
	v_add_f32_e32 v80, v80, v81
	v_add_f32_e32 v80, v86, v80
	ds_bpermute_b32 v81, v116, v80
	global_store_dwordx4 v[104:105], v[82:85], off offset:576
	s_waitcnt lgkmcnt(0)
	v_add_f32_e32 v80, v80, v81
	ds_bpermute_b32 v81, v114, v80
	v_cvt_pk_bf16_f32 v82, v82, v83
	v_cvt_pk_bf16_f32 v83, v84, v85
	global_store_dwordx2 v[102:103], v[82:83], off offset:288
	s_and_saveexec_b64 s[42:43], s[8:9]
	s_cbranch_execz .LBB0_2184
	s_waitcnt lgkmcnt(0)
	v_add_f32_e32 v82, v80, v81
	v_lshlrev_b64 v[80:81], 6, v[96:97]
	v_lshl_add_u64 v[80:81], s[24:25], 0, v[80:81]
	v_lshl_add_u64 v[80:81], s[40:41], 2, v[80:81]
	s_lshl_b32 s26, s74, 2
	v_lshl_add_u64 v[80:81], v[80:81], 0, s[26:27]
	global_store_dword v[80:81], v82, off
; __device__ __forceinline__ unsigned pk2(float lo, float hi) { unsigned r; asm volatile("v_cvt_pk_bf16_f32 %0, %1, %2" : "=v"(r) : "v"(lo), "v"(hi)); return r; }
;     __device__ __forceinline__ void operator()(const f32x4 (&acc)[2][2][4][2], const Unit& u, int wr, int wc, int fr, int fq) const {
;     ...
;             for (int m = 0; m < 4; ++m) {
;                 const int row = row0 + ai * 128 + m * 16; const size_t ro = (size_t)row * DM + col0;
;                 float s = 0.f;
; #pragma unroll
;                 for (int bj = 0; bj < 2; ++bj)
; #pragma unroll
;                     for (int n = 0; n < 2; ++n) {
;                         const size_t o = ro + bj * 128 + n * 16;
;                         const f32x4 xn = *(const f32x4*)(xo + o) + acc[ai][bj][m][n];
;                         *(f32x4*)(xf + o) = xn;
;                         u32x2 w; w.x = pk2(xn[0], xn[1]); w.y = pk2(xn[2], xn[3]); *(u32x2*)(xb + o) = w;
;                         s += (xn[0] * xn[0] + xn[1] * xn[1]) + (xn[2] * xn[2] + xn[3] * xn[3]);
;                     }
;                 s += __shfl_xor(s, 16); s += __shfl_xor(s, 32);
;                 if (fq == 0) ssq[(size_t)row * 16 + u.pn * 4 + wc] = s;
;             }
.LBB0_2184:
	s_or_b64 exec, exec, s[42:43]
	v_or_b32_e32 v80, 48, v138
	s_waitcnt lgkmcnt(0)
	v_ashrrev_i32_e32 v81, 31, v80
	v_lshlrev_b64 v[82:83], 10, v[80:81]
	v_lshl_add_u64 v[86:87], v[82:83], 0, v[136:137]
	v_lshlrev_b64 v[88:89], 2, v[86:87]
	v_lshl_add_u64 v[90:91], s[12:13], 0, v[88:89]
	v_lshl_add_u64 v[86:87], v[86:87], 1, s[22:23]
	v_lshl_add_u64 v[88:89], s[16:17], 0, v[88:89]
	s_waitcnt vmcnt(40)
	v_mov_b32_e32 v82, v236
	v_mov_b32_e32 v83, v237
	v_mov_b32_e32 v84, v238
	v_mov_b32_e32 v85, v239
	v_add_u32_e32 v163, 0xb0040, v162
	global_load_dwordx4 v[236:239], v163, s[12:13]
	v_pk_add_f32 v[78:79], v[78:79], v[84:85]
	v_pk_add_f32 v[76:77], v[76:77], v[82:83]
	global_store_dwordx4 v[88:89], v[76:79], off
	v_cvt_pk_bf16_f32 v82, v76, v77
	v_cvt_pk_bf16_f32 v83, v78, v79
	global_store_dwordx2 v[86:87], v[82:83], off
	v_mul_f32_e32 v77, v77, v77
	v_mul_f32_e32 v79, v79, v79
	v_fmac_f32_e32 v77, v76, v76
	v_fmac_f32_e32 v79, v78, v78
	v_add_f32_e32 v76, v77, v79
	s_waitcnt vmcnt(42)
	v_mov_b32_e32 v82, v240
	v_mov_b32_e32 v83, v241
	v_mov_b32_e32 v84, v242
	v_mov_b32_e32 v85, v243
	v_add_u32_e32 v163, 0xb0200, v162
	global_load_dwordx4 v[240:243], v163, s[12:13]
	v_pk_add_f32 v[74:75], v[74:75], v[84:85]
	v_pk_add_f32 v[72:73], v[72:73], v[82:83]
	global_store_dwordx4 v[88:89], v[72:75], off offset:64
	v_cvt_pk_bf16_f32 v82, v72, v73
	v_cvt_pk_bf16_f32 v83, v74, v75
	global_store_dwordx2 v[86:87], v[82:83], off offset:32
	v_mul_f32_e32 v73, v73, v73
	v_mul_f32_e32 v75, v75, v75
	v_fmac_f32_e32 v73, v72, v72
	v_fmac_f32_e32 v75, v74, v74
	v_add_f32_e32 v72, v73, v75
	v_add_f32_e32 v72, v76, v72
	s_waitcnt vmcnt(44)
	v_mov_b32_e32 v82, v244
	v_mov_b32_e32 v83, v245
	v_mov_b32_e32 v84, v246
	v_mov_b32_e32 v85, v247
	v_add_u32_e32 v163, 0xb0240, v162
	global_load_dwordx4 v[244:247], v163, s[12:13]
	v_pk_add_f32 v[70:71], v[70:71], v[84:85]
	v_pk_add_f32 v[68:69], v[68:69], v[82:83]
	global_store_dwordx4 v[88:89], v[68:71], off offset:512
	v_cvt_pk_bf16_f32 v82, v68, v69
	v_cvt_pk_bf16_f32 v83, v70, v71
	global_store_dwordx2 v[86:87], v[82:83], off offset:256
	v_mul_f32_e32 v69, v69, v69
	v_mul_f32_e32 v71, v71, v71
	v_fmac_f32_e32 v69, v68, v68
	v_fmac_f32_e32 v71, v70, v70
	v_add_f32_e32 v68, v69, v71
	v_add_f32_e32 v70, v72, v68
	s_waitcnt vmcnt(46)
	v_mov_b32_e32 v82, v248
	v_mov_b32_e32 v83, v249
	v_mov_b32_e32 v84, v250
	v_mov_b32_e32 v85, v251
	v_pk_add_f32 v[68:69], v[66:67], v[84:85]
	v_pk_add_f32 v[66:67], v[64:65], v[82:83]
	v_mul_f32_e32 v65, v69, v69
	v_mul_f32_e32 v64, v67, v67
	v_fmac_f32_e32 v64, v66, v66
	v_fmac_f32_e32 v65, v68, v68
	v_add_f32_e32 v64, v64, v65
	v_add_f32_e32 v64, v70, v64
	ds_bpermute_b32 v65, v116, v64
	global_store_dwordx4 v[88:89], v[66:69], off offset:576
	s_waitcnt lgkmcnt(0)
	v_add_f32_e32 v64, v64, v65
	ds_bpermute_b32 v65, v114, v64
	v_cvt_pk_bf16_f32 v66, v66, v67
	v_cvt_pk_bf16_f32 v67, v68, v69
	global_store_dwordx2 v[86:87], v[66:67], off offset:288
	s_and_saveexec_b64 s[42:43], s[8:9]
	s_cbranch_execz .LBB0_2186
	s_waitcnt lgkmcnt(0)
	v_add_f32_e32 v66, v64, v65
	v_lshlrev_b64 v[64:65], 6, v[80:81]
	v_lshl_add_u64 v[64:65], s[24:25], 0, v[64:65]
	v_lshl_add_u64 v[64:65], s[40:41], 2, v[64:65]
	s_lshl_b32 s26, s74, 2
	v_lshl_add_u64 v[64:65], v[64:65], 0, s[26:27]
	global_store_dword v[64:65], v66, off
.LBB0_2186:
	s_or_b64 exec, exec, s[42:43]
	v_add_u32_e32 v64, 0x80, v138
	s_waitcnt lgkmcnt(0)
	v_ashrrev_i32_e32 v65, 31, v64
	v_lshlrev_b64 v[66:67], 10, v[64:65]
	v_lshl_add_u64 v[70:71], v[66:67], 0, v[136:137]
	v_lshlrev_b64 v[72:73], 2, v[70:71]
	v_lshl_add_u64 v[74:75], s[12:13], 0, v[72:73]
	v_lshl_add_u64 v[70:71], v[70:71], 1, s[22:23]
	v_lshl_add_u64 v[72:73], s[16:17], 0, v[72:73]
	s_waitcnt vmcnt(47)
	v_mov_b32_e32 v66, v252
	v_mov_b32_e32 v67, v253
	v_mov_b32_e32 v68, v254
	v_mov_b32_e32 v69, v255
	v_pk_add_f32 v[62:63], v[62:63], v[68:69]
	v_pk_add_f32 v[60:61], v[60:61], v[66:67]
	global_store_dwordx4 v[72:73], v[60:63], off
	v_cvt_pk_bf16_f32 v66, v60, v61
	v_cvt_pk_bf16_f32 v67, v62, v63
	global_store_dwordx2 v[70:71], v[66:67], off
	v_mul_f32_e32 v61, v61, v61
	v_mul_f32_e32 v63, v63, v63
	v_fmac_f32_e32 v61, v60, v60
	v_fmac_f32_e32 v63, v62, v62
	v_add_f32_e32 v60, v61, v63
	s_waitcnt vmcnt(48)
	v_mov_b32_e32 v66, v170
	v_mov_b32_e32 v67, v171
	v_mov_b32_e32 v68, v172
	v_mov_b32_e32 v69, v173
	v_pk_add_f32 v[58:59], v[58:59], v[68:69]
	v_pk_add_f32 v[56:57], v[56:57], v[66:67]
	global_store_dwordx4 v[72:73], v[56:59], off offset:64
	v_cvt_pk_bf16_f32 v66, v56, v57
	v_cvt_pk_bf16_f32 v67, v58, v59
	global_store_dwordx2 v[70:71], v[66:67], off offset:32
	v_mul_f32_e32 v57, v57, v57
	v_mul_f32_e32 v59, v59, v59
	v_fmac_f32_e32 v57, v56, v56
	v_fmac_f32_e32 v59, v58, v58
	v_add_f32_e32 v56, v57, v59
	v_add_f32_e32 v56, v60, v56
	s_waitcnt vmcnt(47)
	v_mov_b32_e32 v66, v174
	v_mov_b32_e32 v67, v175
	v_mov_b32_e32 v68, v176
	v_mov_b32_e32 v69, v177
	v_pk_add_f32 v[54:55], v[54:55], v[68:69]
	v_pk_add_f32 v[52:53], v[52:53], v[66:67]
	global_store_dwordx4 v[72:73], v[52:55], off offset:512
	v_cvt_pk_bf16_f32 v66, v52, v53
	v_cvt_pk_bf16_f32 v67, v54, v55
	global_store_dwordx2 v[70:71], v[66:67], off offset:256
	v_mul_f32_e32 v53, v53, v53
	v_mul_f32_e32 v55, v55, v55
	v_fmac_f32_e32 v53, v52, v52
	v_fmac_f32_e32 v55, v54, v54
	v_add_f32_e32 v52, v53, v55
	v_add_f32_e32 v54, v56, v52
	s_waitcnt vmcnt(46)
	v_mov_b32_e32 v66, v178
	v_mov_b32_e32 v67, v179
	v_mov_b32_e32 v68, v180
	v_mov_b32_e32 v69, v181
	v_pk_add_f32 v[52:53], v[50:51], v[68:69]
	v_pk_add_f32 v[50:51], v[48:49], v[66:67]
	v_mul_f32_e32 v49, v53, v53
	v_mul_f32_e32 v48, v51, v51
	v_fmac_f32_e32 v48, v50, v50
	v_fmac_f32_e32 v49, v52, v52
	v_add_f32_e32 v48, v48, v49
	v_add_f32_e32 v48, v54, v48
	ds_bpermute_b32 v49, v116, v48
	global_store_dwordx4 v[72:73], v[50:53], off offset:576
	s_waitcnt lgkmcnt(0)
	v_add_f32_e32 v48, v48, v49
	ds_bpermute_b32 v49, v114, v48
	v_cvt_pk_bf16_f32 v50, v50, v51
	v_cvt_pk_bf16_f32 v51, v52, v53
	global_store_dwordx2 v[70:71], v[50:51], off offset:288
	s_and_saveexec_b64 s[42:43], s[8:9]
	s_cbranch_execz .LBB0_2188
	s_waitcnt lgkmcnt(0)
	v_add_f32_e32 v50, v48, v49
	v_lshlrev_b64 v[48:49], 6, v[64:65]
	v_lshl_add_u64 v[48:49], s[24:25], 0, v[48:49]
	v_lshl_add_u64 v[48:49], s[40:41], 2, v[48:49]
	s_lshl_b32 s26, s74, 2
	v_lshl_add_u64 v[48:49], v[48:49], 0, s[26:27]
	global_store_dword v[48:49], v50, off
; __device__ __forceinline__ unsigned pk2(float lo, float hi) { unsigned r; asm volatile("v_cvt_pk_bf16_f32 %0, %1, %2" : "=v"(r) : "v"(lo), "v"(hi)); return r; }
;     __device__ __forceinline__ void operator()(const f32x4 (&acc)[2][2][4][2], const Unit& u, int wr, int wc, int fr, int fq) const {
;     ...
;             for (int m = 0; m < 4; ++m) {
;                 const int row = row0 + ai * 128 + m * 16; const size_t ro = (size_t)row * DM + col0;
;                 float s = 0.f;
; #pragma unroll
;                 for (int bj = 0; bj < 2; ++bj)
; #pragma unroll
;                     for (int n = 0; n < 2; ++n) {
;                         const size_t o = ro + bj * 128 + n * 16;
;                         const f32x4 xn = *(const f32x4*)(xo + o) + acc[ai][bj][m][n];
;                         *(f32x4*)(xf + o) = xn;
;                         u32x2 w; w.x = pk2(xn[0], xn[1]); w.y = pk2(xn[2], xn[3]); *(u32x2*)(xb + o) = w;
;                         s += (xn[0] * xn[0] + xn[1] * xn[1]) + (xn[2] * xn[2] + xn[3] * xn[3]);
;                     }
;                 s += __shfl_xor(s, 16); s += __shfl_xor(s, 32);
;                 if (fq == 0) ssq[(size_t)row * 16 + u.pn * 4 + wc] = s;
;             }
.LBB0_2188:
	s_or_b64 exec, exec, s[42:43]
	v_add_u32_e32 v48, 0x90, v138
	s_waitcnt lgkmcnt(0)
	v_ashrrev_i32_e32 v49, 31, v48
	v_lshlrev_b64 v[50:51], 10, v[48:49]
	v_lshl_add_u64 v[54:55], v[50:51], 0, v[136:137]
	v_lshlrev_b64 v[56:57], 2, v[54:55]
	v_lshl_add_u64 v[58:59], s[12:13], 0, v[56:57]
	v_lshl_add_u64 v[54:55], v[54:55], 1, s[22:23]
	v_lshl_add_u64 v[56:57], s[16:17], 0, v[56:57]
	s_waitcnt vmcnt(45)
	v_mov_b32_e32 v50, v182
	v_mov_b32_e32 v51, v183
	v_mov_b32_e32 v52, v184
	v_mov_b32_e32 v53, v185
	v_pk_add_f32 v[46:47], v[46:47], v[52:53]
	v_pk_add_f32 v[44:45], v[44:45], v[50:51]
	global_store_dwordx4 v[56:57], v[44:47], off
	v_cvt_pk_bf16_f32 v50, v44, v45
	v_cvt_pk_bf16_f32 v51, v46, v47
	global_store_dwordx2 v[54:55], v[50:51], off
	v_mul_f32_e32 v45, v45, v45
	v_mul_f32_e32 v47, v47, v47
	v_fmac_f32_e32 v45, v44, v44
	v_fmac_f32_e32 v47, v46, v46
	v_add_f32_e32 v44, v45, v47
	s_waitcnt vmcnt(44)
	v_mov_b32_e32 v50, v186
	v_mov_b32_e32 v51, v187
	v_mov_b32_e32 v52, v188
	v_mov_b32_e32 v53, v189
	v_pk_add_f32 v[42:43], v[42:43], v[52:53]
	v_pk_add_f32 v[40:41], v[40:41], v[50:51]
	global_store_dwordx4 v[56:57], v[40:43], off offset:64
	v_cvt_pk_bf16_f32 v50, v40, v41
	v_cvt_pk_bf16_f32 v51, v42, v43
	global_store_dwordx2 v[54:55], v[50:51], off offset:32
	v_mul_f32_e32 v41, v41, v41
	v_mul_f32_e32 v43, v43, v43
	v_fmac_f32_e32 v41, v40, v40
	v_fmac_f32_e32 v43, v42, v42
	v_add_f32_e32 v40, v41, v43
	v_add_f32_e32 v40, v44, v40
	s_waitcnt vmcnt(43)
	v_mov_b32_e32 v50, v190
	v_mov_b32_e32 v51, v191
	v_mov_b32_e32 v52, v192
	v_mov_b32_e32 v53, v193
	v_pk_add_f32 v[38:39], v[38:39], v[52:53]
	v_pk_add_f32 v[36:37], v[36:37], v[50:51]
	global_store_dwordx4 v[56:57], v[36:39], off offset:512
	v_cvt_pk_bf16_f32 v50, v36, v37
	v_cvt_pk_bf16_f32 v51, v38, v39
	global_store_dwordx2 v[54:55], v[50:51], off offset:256
	v_mul_f32_e32 v37, v37, v37
	v_mul_f32_e32 v39, v39, v39
	v_fmac_f32_e32 v37, v36, v36
	v_fmac_f32_e32 v39, v38, v38
	v_add_f32_e32 v36, v37, v39
	v_add_f32_e32 v38, v40, v36
	s_waitcnt vmcnt(42)
	v_mov_b32_e32 v50, v194
	v_mov_b32_e32 v51, v195
	v_mov_b32_e32 v52, v196
	v_mov_b32_e32 v53, v197
	v_pk_add_f32 v[36:37], v[34:35], v[52:53]
	v_pk_add_f32 v[34:35], v[32:33], v[50:51]
	v_mul_f32_e32 v33, v37, v37
	v_mul_f32_e32 v32, v35, v35
	v_fmac_f32_e32 v32, v34, v34
	v_fmac_f32_e32 v33, v36, v36
	v_add_f32_e32 v32, v32, v33
	v_add_f32_e32 v32, v38, v32
	ds_bpermute_b32 v33, v116, v32
	global_store_dwordx4 v[56:57], v[34:37], off offset:576
	s_waitcnt lgkmcnt(0)
	v_add_f32_e32 v32, v32, v33
	ds_bpermute_b32 v33, v114, v32
	v_cvt_pk_bf16_f32 v34, v34, v35
	v_cvt_pk_bf16_f32 v35, v36, v37
	global_store_dwordx2 v[54:55], v[34:35], off offset:288
	s_and_saveexec_b64 s[42:43], s[8:9]
	s_cbranch_execz .LBB0_2190
	s_waitcnt lgkmcnt(0)
	v_add_f32_e32 v34, v32, v33
	v_lshlrev_b64 v[32:33], 6, v[48:49]
	v_lshl_add_u64 v[32:33], s[24:25], 0, v[32:33]
	v_lshl_add_u64 v[32:33], s[40:41], 2, v[32:33]
	s_lshl_b32 s26, s74, 2
	v_lshl_add_u64 v[32:33], v[32:33], 0, s[26:27]
	global_store_dword v[32:33], v34, off
; __device__ __forceinline__ unsigned pk2(float lo, float hi) { unsigned r; asm volatile("v_cvt_pk_bf16_f32 %0, %1, %2" : "=v"(r) : "v"(lo), "v"(hi)); return r; }
;     __device__ __forceinline__ void operator()(const f32x4 (&acc)[2][2][4][2], const Unit& u, int wr, int wc, int fr, int fq) const {
;     ...
;             for (int m = 0; m < 4; ++m) {
;                 const int row = row0 + ai * 128 + m * 16; const size_t ro = (size_t)row * DM + col0;
;                 float s = 0.f;
; #pragma unroll
;                 for (int bj = 0; bj < 2; ++bj)
; #pragma unroll
;                     for (int n = 0; n < 2; ++n) {
;                         const size_t o = ro + bj * 128 + n * 16;
;                         const f32x4 xn = *(const f32x4*)(xo + o) + acc[ai][bj][m][n];
;                         *(f32x4*)(xf + o) = xn;
;                         u32x2 w; w.x = pk2(xn[0], xn[1]); w.y = pk2(xn[2], xn[3]); *(u32x2*)(xb + o) = w;
;                         s += (xn[0] * xn[0] + xn[1] * xn[1]) + (xn[2] * xn[2] + xn[3] * xn[3]);
;                     }
;                 s += __shfl_xor(s, 16); s += __shfl_xor(s, 32);
;                 if (fq == 0) ssq[(size_t)row * 16 + u.pn * 4 + wc] = s;
;             }
.LBB0_2190:
	s_or_b64 exec, exec, s[42:43]
	v_add_u32_e32 v32, 0xa0, v138
	s_waitcnt lgkmcnt(0)
	v_ashrrev_i32_e32 v33, 31, v32
	v_lshlrev_b64 v[34:35], 10, v[32:33]
	v_lshl_add_u64 v[38:39], v[34:35], 0, v[136:137]
	v_lshlrev_b64 v[40:41], 2, v[38:39]
	v_lshl_add_u64 v[42:43], s[12:13], 0, v[40:41]
	v_lshl_add_u64 v[38:39], v[38:39], 1, s[22:23]
	v_lshl_add_u64 v[40:41], s[16:17], 0, v[40:41]
	s_waitcnt vmcnt(41)
	v_mov_b32_e32 v34, v198
	v_mov_b32_e32 v35, v199
	v_mov_b32_e32 v36, v200
	v_mov_b32_e32 v37, v201
	v_pk_add_f32 v[30:31], v[30:31], v[36:37]
	v_pk_add_f32 v[28:29], v[28:29], v[34:35]
	global_store_dwordx4 v[40:41], v[28:31], off
	v_cvt_pk_bf16_f32 v34, v28, v29
	v_cvt_pk_bf16_f32 v35, v30, v31
	global_store_dwordx2 v[38:39], v[34:35], off
	v_mul_f32_e32 v29, v29, v29
	v_mul_f32_e32 v31, v31, v31
	v_fmac_f32_e32 v29, v28, v28
	v_fmac_f32_e32 v31, v30, v30
	v_add_f32_e32 v28, v29, v31
	s_waitcnt vmcnt(40)
	v_mov_b32_e32 v34, v202
	v_mov_b32_e32 v35, v203
	v_mov_b32_e32 v36, v204
	v_mov_b32_e32 v37, v205
	v_pk_add_f32 v[26:27], v[26:27], v[36:37]
	v_pk_add_f32 v[24:25], v[24:25], v[34:35]
	global_store_dwordx4 v[40:41], v[24:27], off offset:64
	v_cvt_pk_bf16_f32 v34, v24, v25
	v_cvt_pk_bf16_f32 v35, v26, v27
	global_store_dwordx2 v[38:39], v[34:35], off offset:32
	v_mul_f32_e32 v25, v25, v25
	v_mul_f32_e32 v27, v27, v27
	v_fmac_f32_e32 v25, v24, v24
	v_fmac_f32_e32 v27, v26, v26
	v_add_f32_e32 v24, v25, v27
	v_add_f32_e32 v24, v28, v24
	s_waitcnt vmcnt(39)
	v_mov_b32_e32 v34, v206
	v_mov_b32_e32 v35, v207
	v_mov_b32_e32 v36, v208
	v_mov_b32_e32 v37, v209
	v_pk_add_f32 v[22:23], v[22:23], v[36:37]
	v_pk_add_f32 v[20:21], v[20:21], v[34:35]
	global_store_dwordx4 v[40:41], v[20:23], off offset:512
	v_cvt_pk_bf16_f32 v34, v20, v21
	v_cvt_pk_bf16_f32 v35, v22, v23
	global_store_dwordx2 v[38:39], v[34:35], off offset:256
	v_mul_f32_e32 v21, v21, v21
	v_mul_f32_e32 v23, v23, v23
	v_fmac_f32_e32 v21, v20, v20
	v_fmac_f32_e32 v23, v22, v22
	v_add_f32_e32 v20, v21, v23
	v_add_f32_e32 v22, v24, v20
	s_waitcnt vmcnt(38)
	v_mov_b32_e32 v34, v210
	v_mov_b32_e32 v35, v211
	v_mov_b32_e32 v36, v212
	v_mov_b32_e32 v37, v213
	v_pk_add_f32 v[20:21], v[18:19], v[36:37]
	v_pk_add_f32 v[18:19], v[16:17], v[34:35]
	v_mul_f32_e32 v17, v21, v21
	v_mul_f32_e32 v16, v19, v19
	v_fmac_f32_e32 v16, v18, v18
	v_fmac_f32_e32 v17, v20, v20
	v_add_f32_e32 v16, v16, v17
	v_add_f32_e32 v16, v22, v16
	ds_bpermute_b32 v17, v116, v16
	global_store_dwordx4 v[40:41], v[18:21], off offset:576
	s_waitcnt lgkmcnt(0)
	v_add_f32_e32 v16, v16, v17
	ds_bpermute_b32 v17, v114, v16
	v_cvt_pk_bf16_f32 v18, v18, v19
	v_cvt_pk_bf16_f32 v19, v20, v21
	global_store_dwordx2 v[38:39], v[18:19], off offset:288
	s_and_saveexec_b64 s[42:43], s[8:9]
	s_cbranch_execz .LBB0_2192
	s_waitcnt lgkmcnt(0)
	v_add_f32_e32 v18, v16, v17
	v_lshlrev_b64 v[16:17], 6, v[32:33]
	v_lshl_add_u64 v[16:17], s[24:25], 0, v[16:17]
	v_lshl_add_u64 v[16:17], s[40:41], 2, v[16:17]
	s_lshl_b32 s26, s74, 2
	v_lshl_add_u64 v[16:17], v[16:17], 0, s[26:27]
	global_store_dword v[16:17], v18, off
.LBB0_2192:
	s_or_b64 exec, exec, s[42:43]
	v_add_u32_e32 v16, 0xb0, v138
	s_waitcnt lgkmcnt(0)
	v_ashrrev_i32_e32 v17, 31, v16
	v_lshlrev_b64 v[18:19], 10, v[16:17]
	v_lshl_add_u64 v[22:23], v[18:19], 0, v[136:137]
	v_lshlrev_b64 v[24:25], 2, v[22:23]
	v_lshl_add_u64 v[26:27], s[12:13], 0, v[24:25]
	v_lshl_add_u64 v[22:23], v[22:23], 1, s[22:23]
	v_lshl_add_u64 v[24:25], s[16:17], 0, v[24:25]
	s_waitcnt vmcnt(37)
	v_mov_b32_e32 v18, v232
	v_mov_b32_e32 v19, v233
	v_mov_b32_e32 v20, v234
	v_mov_b32_e32 v21, v235
	v_pk_add_f32 v[14:15], v[14:15], v[20:21]
	v_pk_add_f32 v[12:13], v[12:13], v[18:19]
	global_store_dwordx4 v[24:25], v[12:15], off
	v_cvt_pk_bf16_f32 v18, v12, v13
	v_cvt_pk_bf16_f32 v19, v14, v15
	global_store_dwordx2 v[22:23], v[18:19], off
	v_mul_f32_e32 v13, v13, v13
	v_mul_f32_e32 v15, v15, v15
	v_fmac_f32_e32 v13, v12, v12
	v_fmac_f32_e32 v15, v14, v14
	v_add_f32_e32 v12, v13, v15
	s_waitcnt vmcnt(36)
	v_mov_b32_e32 v18, v236
	v_mov_b32_e32 v19, v237
	v_mov_b32_e32 v20, v238
	v_mov_b32_e32 v21, v239
	v_pk_add_f32 v[10:11], v[10:11], v[20:21]
	v_pk_add_f32 v[8:9], v[8:9], v[18:19]
	global_store_dwordx4 v[24:25], v[8:11], off offset:64
	v_cvt_pk_bf16_f32 v18, v8, v9
	v_cvt_pk_bf16_f32 v19, v10, v11
	global_store_dwordx2 v[22:23], v[18:19], off offset:32
	v_mul_f32_e32 v9, v9, v9
	v_mul_f32_e32 v11, v11, v11
	v_fmac_f32_e32 v9, v8, v8
	v_fmac_f32_e32 v11, v10, v10
	v_add_f32_e32 v8, v9, v11
	v_add_f32_e32 v8, v12, v8
	s_waitcnt vmcnt(35)
	v_mov_b32_e32 v18, v240
	v_mov_b32_e32 v19, v241
	v_mov_b32_e32 v20, v242
	v_mov_b32_e32 v21, v243
	v_pk_add_f32 v[6:7], v[6:7], v[20:21]
	v_pk_add_f32 v[4:5], v[4:5], v[18:19]
	global_store_dwordx4 v[24:25], v[4:7], off offset:512
	v_cvt_pk_bf16_f32 v18, v4, v5
	v_cvt_pk_bf16_f32 v19, v6, v7
	global_store_dwordx2 v[22:23], v[18:19], off offset:256
	v_mul_f32_e32 v5, v5, v5
	v_mul_f32_e32 v7, v7, v7
	v_fmac_f32_e32 v5, v4, v4
	v_fmac_f32_e32 v7, v6, v6
	v_add_f32_e32 v4, v5, v7
	v_add_f32_e32 v6, v8, v4
	s_waitcnt vmcnt(34)
	v_mov_b32_e32 v18, v244
	v_mov_b32_e32 v19, v245
	v_mov_b32_e32 v20, v246
	v_mov_b32_e32 v21, v247
	v_pk_add_f32 v[4:5], v[2:3], v[20:21]
	v_pk_add_f32 v[2:3], v[0:1], v[18:19]
	v_mul_f32_e32 v1, v5, v5
	v_mul_f32_e32 v0, v3, v3
	v_fmac_f32_e32 v0, v2, v2
	v_fmac_f32_e32 v1, v4, v4
	v_add_f32_e32 v0, v0, v1
	v_add_f32_e32 v0, v6, v0
	ds_bpermute_b32 v1, v116, v0
	global_store_dwordx4 v[24:25], v[2:5], off offset:576
	s_waitcnt lgkmcnt(0)
	v_add_f32_e32 v0, v0, v1
	ds_bpermute_b32 v1, v114, v0
	v_cvt_pk_bf16_f32 v2, v2, v3
	v_cvt_pk_bf16_f32 v3, v4, v5
	global_store_dwordx2 v[22:23], v[2:3], off offset:288
	s_and_saveexec_b64 s[12:13], s[8:9]
	s_cbranch_execz .LBB0_2153
	s_waitcnt lgkmcnt(0)
	v_add_f32_e32 v2, v0, v1
	v_lshlrev_b64 v[0:1], 6, v[16:17]
	v_lshl_add_u64 v[0:1], s[24:25], 0, v[0:1]
	v_lshl_add_u64 v[0:1], s[40:41], 2, v[0:1]
	s_lshl_b32 s26, s74, 2
	v_lshl_add_u64 v[0:1], v[0:1], 0, s[26:27]
	global_store_dword v[0:1], v2, off
	s_branch .LBB0_2153
